# nt (streaming) cache hint on the 104 once-read dwordx4 global loads of the mixer phases P2-P4
# speedup vs baseline: 1.0172x; 1.0168x over previous
.LBB0_271:
	s_cmpk_gt_i32 s8, 0x7ff
	s_cbranch_scc1 .LBB0_290
	s_lshl_b32 s9, s8, 23
	s_and_b32 s9, s9, 0x1800000
	s_add_u32 s9, s86, s9
	s_addc_u32 s14, s87, 0
	s_add_u32 s10, s9, 0xa000000
	v_add_u32_e32 v64, 0x200, v62
	s_addc_u32 s11, s14, 0
	s_ashr_i32 s12, s8, 2
	v_ashrrev_i32_e32 v63, 31, v62
	v_ashrrev_i32_e32 v65, 31, v64
	s_ashr_i32 s13, s12, 31
	v_lshlrev_b64 v[58:59], 3, v[62:63]
	v_lshlrev_b64 v[60:61], 3, v[64:65]
	s_lshl_b64 s[12:13], s[12:13], 13
	s_waitcnt vmcnt(0)
	v_lshl_add_u64 v[2:3], s[12:13], 0, v[58:59]
	v_lshl_add_u64 v[4:5], s[12:13], 0, v[60:61]
	v_lshlrev_b64 v[18:19], 1, v[2:3]
	v_lshlrev_b64 v[20:21], 1, v[4:5]
	v_lshl_add_u64 v[2:3], s[10:11], 0, v[18:19]
	v_lshl_add_u64 v[6:7], s[10:11], 0, v[20:21]
	s_add_u32 s10, s9, 0xc000000
	s_addc_u32 s11, s14, 0
	v_lshl_add_u64 v[10:11], s[10:11], 0, v[18:19]
	v_lshl_add_u64 v[14:15], s[10:11], 0, v[20:21]
	s_add_u32 s10, s9, 0xe000000
	s_addc_u32 s11, s14, 0
	v_lshl_add_u64 v[18:19], s[10:11], 0, v[18:19]
	v_lshl_add_u64 v[22:23], s[10:11], 0, v[20:21]
	global_load_dwordx4 v[2:5], v[2:3], off nt
	s_nop 0
	global_load_dwordx4 v[6:9], v[6:7], off nt
	s_nop 0
	global_load_dwordx4 v[10:13], v[10:11], off nt
	s_nop 0
	global_load_dwordx4 v[14:17], v[14:15], off nt
	s_nop 0
	global_load_dwordx4 v[18:21], v[18:19], off nt
	s_nop 0
	global_load_dwordx4 v[22:25], v[22:23], off nt
	v_lshlrev_b32_e32 v63, 3, v62
	v_and_b32_e32 v0, 0x78, v63
	v_ashrrev_i32_e32 v26, 4, v62
	s_movk_i32 s9, 0x88
	v_mad_u64_u32 v[28:29], s[10:11], v26, s9, v[0:1]
	v_lshl_add_u32 v90, v28, 1, 0
	v_ashrrev_i32_e32 v28, 4, v64
	v_mad_u64_u32 v[30:31], s[10:11], v28, s9, v[0:1]
	s_add_i32 s9, 0, 0x4400
	s_movk_i32 s10, 0x100
	v_and_b32_e32 v27, 63, v62
	v_mov_b32_e32 v29, s9
	v_cmp_gt_u32_e32 vcc, s10, v62
	v_lshlrev_b32_e32 v32, 2, v27
	v_lshl_add_u32 v92, v30, 1, 0
	v_cndmask_b32_e64 v29, v29, 0, vcc
	v_add_u32_e32 v93, v29, v32
	v_ashrrev_i32_e32 v29, 6, v62
	v_and_b32_e32 v108, -4, v29
	v_lshl_or_b32 v34, v29, 9, v180
	v_ashrrev_i32_e32 v30, 7, v62
	v_lshlrev_b32_e32 v29, 2, v62
	v_lshl_add_u32 v109, v27, 3, 0
	v_lshlrev_b32_e32 v27, 11, v30
	v_and_b32_e32 v35, 0x1fc, v29
	v_add3_u32 v110, 0, v27, v35
	s_ashr_i32 s24, s3, 8
	s_bfe_u32 s3, s3, 0x20006
	v_bfe_u32 v27, v62, 4, 2
	s_cmp_lt_u32 s17, 4
	v_bfe_u32 v29, v62, 2, 2
	v_lshlrev_b32_e32 v91, 2, v27
	v_cmp_gt_i32_e64 s[40:41], s10, v62
	s_cselect_b32 s9, 0, s9
	v_lshl_or_b32 v88, v27, 3, v29
	s_lshl_b32 s10, s3, 6
	v_lshl_or_b32 v27, s3, 5, v91
	s_lshl_b32 s3, s24, 11
	s_add_i32 s3, s3, 0
	v_lshlrev_b32_e32 v0, 1, v0
	v_and_b32_e32 v65, 15, v62
	v_and_b32_e32 v29, 12, v32
	v_lshl_add_u32 v111, v27, 2, s3
	v_lshl_add_u32 v112, v27, 1, 0
	v_add_u32_e32 v44, 0, v0
	v_lshl_add_u64 v[66:67], s[46:47], 0, v[0:1]
	v_ashrrev_i32_e32 v27, 31, v26
	v_add_u32_e32 v0, 0x400, v62
	v_lshlrev_b32_e32 v89, 1, v29
	v_lshl_or_b32 v29, s24, 7, v65
	v_mul_lo_u32 v45, v26, s18
	v_lshlrev_b64 v[68:69], 8, v[26:27]
	v_ashrrev_i32_e32 v26, 4, v0
	v_mul_lo_u32 v113, v29, s18
	v_ashrrev_i32_e32 v29, 31, v28
	v_ashrrev_i32_e32 v27, 31, v26
	v_add_u32_e32 v0, 0x600, v62
	v_mul_lo_u32 v46, v28, s18
	v_lshlrev_b64 v[70:71], 8, v[28:29]
	v_mul_lo_u32 v28, v26, s18
	v_lshlrev_b64 v[72:73], 8, v[26:27]
	v_ashrrev_i32_e32 v26, 4, v0
	v_ashrrev_i32_e32 v27, 31, v26
	v_add_u32_e32 v0, 0x800, v62
	v_mul_lo_u32 v29, v26, s18
	v_lshlrev_b64 v[74:75], 8, v[26:27]
	v_ashrrev_i32_e32 v26, 4, v0
	v_ashrrev_i32_e32 v27, 31, v26
	v_add_u32_e32 v0, 0xa00, v62
	v_mul_lo_u32 v47, v26, s18
	v_lshlrev_b64 v[76:77], 8, v[26:27]
	v_ashrrev_i32_e32 v26, 4, v0
	v_ashrrev_i32_e32 v27, 31, v26
	v_add_u32_e32 v0, 0xc00, v62
	v_mul_lo_u32 v48, v26, s18
	v_lshlrev_b64 v[78:79], 8, v[26:27]
	v_ashrrev_i32_e32 v26, 4, v0
	s_add_i32 s9, s9, s10
	v_ashrrev_i32_e32 v27, 31, v26
	v_add_u32_e32 v0, 0xe00, v62
	v_ashrrev_i32_e32 v31, 31, v30
	v_add_u32_e32 v32, s9, v89
	v_mul_lo_u32 v49, v26, s18
	v_lshlrev_b64 v[80:81], 8, v[26:27]
	v_ashrrev_i32_e32 v26, 4, v0
	s_ashr_i32 s9, s8, 31
	v_lshlrev_b64 v[30:31], 9, v[30:31]
	v_ashrrev_i32_e32 v27, 31, v26
	s_lshl_b64 s[10:11], s[8:9], 10
	v_mul_lo_u32 v50, v26, s18
	v_lshlrev_b64 v[82:83], 8, v[26:27]
	v_lshl_add_u64 v[26:27], s[10:11], 0, v[30:31]
	v_lshlrev_b32_e32 v33, 9, v108
	v_add_u32_e32 v36, 0, v89
	v_mul_u32_u24_e32 v37, 0x110, v88
	v_add_u32_e32 v38, 0x2200, v113
	v_add_u32_e32 v39, 0x3300, v113
	v_add_u32_e32 v40, 0x4400, v113
	v_add_u32_e32 v41, 0x5500, v113
	v_add_u32_e32 v42, 0x6600, v113
	v_add_u32_e32 v43, 0x7700, v113
	s_ashr_i32 s3, s2, 31
	v_or_b32_e32 v26, v26, v35
	v_cndmask_b32_e64 v94, 14, 1, vcc
	v_cndmask_b32_e64 v95, 13, 2, vcc
	v_cndmask_b32_e64 v96, 12, 3, vcc
	v_cndmask_b32_e64 v97, 11, 4, vcc
	v_cndmask_b32_e64 v98, 10, 5, vcc
	v_cndmask_b32_e64 v99, 9, 6, vcc
	v_cndmask_b32_e64 v100, 8, 7, vcc
	v_cndmask_b32_e64 v101, 7, 8, vcc
	v_cndmask_b32_e64 v102, 6, 9, vcc
	v_cndmask_b32_e64 v103, 5, 10, vcc
	v_cndmask_b32_e64 v104, 4, 11, vcc
	v_cndmask_b32_e64 v105, 3, 12, vcc
	v_cndmask_b32_e64 v106, 2, 13, vcc
	v_cndmask_b32_e64 v107, 1, 14, vcc
	v_lshl_add_u64 v[84:85], s[94:95], 0, v[26:27]
	s_lshl_b64 s[10:11], s[2:3], 10
	v_add_u32_e32 v0, v109, v34
	v_add_u32_e32 v114, v32, v37
	v_add_u32_e32 v115, v36, v37
	v_add_u32_e32 v116, v112, v38
	v_add_u32_e32 v117, v112, v39
	v_add_u32_e32 v118, v112, v40
	v_add_u32_e32 v119, v112, v41
	v_add_u32_e32 v120, v112, v42
	v_add_u32_e32 v121, v112, v43
	v_add_u32_e32 v122, v44, v45
	v_add_u32_e32 v123, v44, v46
	v_add_u32_e32 v124, v44, v28
	v_add_u32_e32 v125, v44, v29
	v_add_u32_e32 v126, v44, v47
	v_add_u32_e32 v127, v44, v48
	v_add_u32_e32 v128, v44, v49
	v_add_u32_e32 v129, v44, v50
	v_add_u32_e32 v130, v109, v33
	s_mov_b64 s[12:13], s[8:9]
	s_waitcnt vmcnt(0)
	v_lshlrev_b32_e32 v236, 4, v214
	v_add_u32_e32 v237, 0x2000000, v236
	v_add_u32_e32 v238, 0x4000000, v236
	v_add_u32_e32 v239, 0x2000, v236
	v_add_u32_e32 v240, 0x2002000, v236
	v_add_u32_e32 v241, 0x4002000, v236
	s_branch .LBB0_274

.LBB0_276:
	v_readfirstlane_b32 s14, v62
	s_bfe_u32 s25, s14, 0x20006
	s_lshl_b32 s14, s25, 4
	s_or_b32 s15, s14, 15
	v_mov_b32_e32 v50, s15
	v_mov_b32_e32 v51, s14
	v_cndmask_b32_e32 v43, v50, v51, vcc
	v_or_b32_e32 v42, s14, v94
	v_or_b32_e32 v41, s14, v95
	v_or_b32_e32 v40, s14, v96
	v_mad_u32_u24 v26, v43, s18, v93
	v_mad_u32_u24 v27, v42, s18, v93
	v_mad_u32_u24 v28, v41, s18, v93
	v_mad_u32_u24 v29, v40, s18, v93
	v_or_b32_e32 v38, s14, v97
	v_or_b32_e32 v39, s14, v98
	v_or_b32_e32 v37, s14, v99
	v_or_b32_e32 v35, s14, v100
	v_mad_u32_u24 v30, v38, s18, v93
	v_mad_u32_u24 v31, v39, s18, v93
	v_mad_u32_u24 v32, v37, s18, v93
	v_mad_u32_u24 v33, v35, s18, v93
	ds_read_b32 v34, v26
	ds_read_b32 v36, v27
	ds_read_b32 v44, v28
	ds_read_b32 v45, v29
	ds_read_b32 v46, v30
	ds_read_b32 v47, v31
	ds_read_b32 v48, v32
	ds_read_b32 v49, v33
	global_load_dwordx4 v[2:5], v236, s[100:101] nt
	s_waitcnt lgkmcnt(7)
	v_lshlrev_b32_e32 v26, 16, v34
	v_and_b32_e32 v27, 0xffff0000, v34
	s_waitcnt lgkmcnt(6)
	v_lshlrev_b32_e32 v28, 16, v36
	v_and_b32_e32 v29, 0xffff0000, v36
	s_waitcnt lgkmcnt(5)
	v_lshlrev_b32_e32 v30, 16, v44
	v_and_b32_e32 v31, 0xffff0000, v44
	v_pk_add_f32 v[26:27], v[26:27], 1.0 op_sel_hi:[1,0] neg_lo:[1,0] neg_hi:[1,0]
	v_pk_add_f32 v[28:29], v[28:29], 1.0 op_sel_hi:[1,0] neg_lo:[1,0] neg_hi:[1,0]
	s_waitcnt lgkmcnt(4)
	v_lshlrev_b32_e32 v32, 16, v45
	v_and_b32_e32 v33, 0xffff0000, v45
	v_pk_mul_f32 v[26:27], v[26:27], v[28:29]
	v_pk_add_f32 v[28:29], v[30:31], 1.0 op_sel_hi:[1,0] neg_lo:[1,0] neg_hi:[1,0]
	s_waitcnt lgkmcnt(3)
	v_lshlrev_b32_e32 v44, 16, v46
	v_and_b32_e32 v45, 0xffff0000, v46
	v_pk_mul_f32 v[26:27], v[26:27], v[28:29]
	v_pk_add_f32 v[28:29], v[32:33], 1.0 op_sel_hi:[1,0] neg_lo:[1,0] neg_hi:[1,0]
	v_or_b32_e32 v36, s14, v101
	v_pk_mul_f32 v[26:27], v[26:27], v[28:29]
	v_pk_add_f32 v[28:29], v[44:45], 1.0 op_sel_hi:[1,0] neg_lo:[1,0] neg_hi:[1,0]
	v_or_b32_e32 v34, s14, v102
	v_pk_mul_f32 v[26:27], v[26:27], v[28:29]
	s_waitcnt lgkmcnt(2)
	v_lshlrev_b32_e32 v28, 16, v47
	v_and_b32_e32 v29, 0xffff0000, v47
	v_pk_add_f32 v[44:45], v[28:29], 1.0 op_sel_hi:[1,0] neg_lo:[1,0] neg_hi:[1,0]
	s_waitcnt lgkmcnt(1)
	v_lshlrev_b32_e32 v46, 16, v48
	v_and_b32_e32 v47, 0xffff0000, v48
	v_mad_u32_u24 v52, v36, s18, v93
	v_mad_u32_u24 v53, v34, s18, v93
	v_or_b32_e32 v33, s14, v103
	v_or_b32_e32 v32, s14, v104
	v_or_b32_e32 v31, s14, v105
	v_or_b32_e32 v30, s14, v106
	v_or_b32_e32 v29, s14, v107
	v_cndmask_b32_e32 v28, v51, v50, vcc
	s_waitcnt lgkmcnt(0)
	v_lshlrev_b32_e32 v48, 16, v49
	v_and_b32_e32 v49, 0xffff0000, v49
	v_mad_u32_u24 v54, v33, s18, v93
	v_mad_u32_u24 v55, v32, s18, v93
	v_mad_u32_u24 v56, v31, s18, v93
	v_mad_u32_u24 v57, v30, s18, v93
	v_mad_u32_u24 v86, v29, s18, v93
	v_mad_u32_u24 v50, v28, s18, v93
	ds_read_b32 v51, v52
	ds_read_b32 v53, v53
	ds_read_b32 v87, v54
	ds_read_b32 v131, v55
	ds_read_b32 v132, v56
	ds_read_b32 v133, v57
	ds_read_b32 v135, v86
	ds_read_b32 v137, v50
	global_load_dwordx4 v[10:13], v237, s[100:101] nt
	v_pk_mul_f32 v[26:27], v[26:27], v[44:45]
	v_pk_add_f32 v[44:45], v[46:47], 1.0 op_sel_hi:[1,0] neg_lo:[1,0] neg_hi:[1,0]
	s_waitcnt lgkmcnt(7)
	v_lshlrev_b32_e32 v50, 16, v51
	v_and_b32_e32 v51, 0xffff0000, v51
	v_pk_mul_f32 v[26:27], v[26:27], v[44:45]
	v_pk_add_f32 v[44:45], v[48:49], 1.0 op_sel_hi:[1,0] neg_lo:[1,0] neg_hi:[1,0]
	s_waitcnt lgkmcnt(6)
	v_lshlrev_b32_e32 v52, 16, v53
	v_and_b32_e32 v53, 0xffff0000, v53
	v_pk_mul_f32 v[26:27], v[26:27], v[44:45]
	v_pk_add_f32 v[44:45], v[50:51], 1.0 op_sel_hi:[1,0] neg_lo:[1,0] neg_hi:[1,0]
	s_waitcnt lgkmcnt(5)
	v_lshlrev_b32_e32 v54, 16, v87
	v_and_b32_e32 v55, 0xffff0000, v87
	v_pk_mul_f32 v[26:27], v[26:27], v[44:45]
	v_pk_add_f32 v[44:45], v[52:53], 1.0 op_sel_hi:[1,0] neg_lo:[1,0] neg_hi:[1,0]
	s_waitcnt lgkmcnt(4)
	v_lshlrev_b32_e32 v56, 16, v131
	v_and_b32_e32 v57, 0xffff0000, v131
	v_pk_mul_f32 v[26:27], v[26:27], v[44:45]
	v_pk_add_f32 v[44:45], v[54:55], 1.0 op_sel_hi:[1,0] neg_lo:[1,0] neg_hi:[1,0]
	s_waitcnt lgkmcnt(3)
	v_lshlrev_b32_e32 v86, 16, v132
	v_and_b32_e32 v87, 0xffff0000, v132
	v_pk_mul_f32 v[26:27], v[26:27], v[44:45]
	v_pk_add_f32 v[44:45], v[56:57], 1.0 op_sel_hi:[1,0] neg_lo:[1,0] neg_hi:[1,0]
	s_waitcnt lgkmcnt(2)
	v_lshlrev_b32_e32 v132, 16, v133
	v_and_b32_e32 v133, 0xffff0000, v133
	v_pk_mul_f32 v[26:27], v[26:27], v[44:45]
	v_pk_add_f32 v[44:45], v[86:87], 1.0 op_sel_hi:[1,0] neg_lo:[1,0] neg_hi:[1,0]
	s_waitcnt lgkmcnt(1)
	v_lshlrev_b32_e32 v134, 16, v135
	v_and_b32_e32 v135, 0xffff0000, v135
	v_pk_mul_f32 v[26:27], v[26:27], v[44:45]
	v_pk_add_f32 v[44:45], v[132:133], 1.0 op_sel_hi:[1,0] neg_lo:[1,0] neg_hi:[1,0]
	s_waitcnt lgkmcnt(0)
	v_lshlrev_b32_e32 v136, 16, v137
	v_and_b32_e32 v137, 0xffff0000, v137
	v_pk_mul_f32 v[26:27], v[26:27], v[44:45]
	v_pk_add_f32 v[44:45], v[134:135], 1.0 op_sel_hi:[1,0] neg_lo:[1,0] neg_hi:[1,0]
	v_or_b32_e32 v131, s25, v108
	v_pk_mul_f32 v[26:27], v[26:27], v[44:45]
	v_pk_add_f32 v[44:45], v[136:137], 1.0 op_sel_hi:[1,0] neg_lo:[1,0] neg_hi:[1,0]
	s_cmp_lg_u32 s25, 0
	v_mov_b32_e32 v147, v146
	v_lshl_add_u32 v131, v131, 9, v109
	v_pk_mul_f32 v[26:27], v[26:27], v[44:45]
	s_cselect_b64 s[14:15], -1, 0
	ds_write_b64 v131, v[26:27] offset:52224
	s_and_b64 s[26:27], vcc, s[14:15]
	v_mov_b64_e32 v[26:27], v[146:147]
	s_waitcnt lgkmcnt(0)
	s_barrier
	s_and_saveexec_b64 s[14:15], s[26:27]
	ds_read_b64 v[26:27], v109 offset:52224
	s_or_b64 exec, exec, s[14:15]
	s_cmp_eq_u32 s25, 0
	s_cselect_b64 s[14:15], -1, 0
	s_cmp_gt_u32 s25, 1
	v_cndmask_b32_e64 v44, 0, 1, s[14:15]
	s_cselect_b64 s[14:15], -1, 0
	v_cndmask_b32_e64 v45, 0, 1, s[14:15]
	v_cndmask_b32_e32 v44, v44, v45, vcc
	v_and_b32_e32 v44, 1, v44
	v_cmp_eq_u32_e64 s[42:43], 1, v44
	s_and_saveexec_b64 s[14:15], s[42:43]
	s_cbranch_execz .LBB0_280
	ds_read_b64 v[44:45], v130 offset:52736
	s_waitcnt lgkmcnt(0)
	v_pk_mul_f32 v[26:27], v[26:27], v[44:45]

.LBB0_284:
	s_or_b64 exec, exec, s[14:15]
	v_mul_u32_u24_e32 v43, 0x110, v43
	v_add_u32_e32 v43, v93, v43
	ds_read_b32 v220, v43
	v_mul_u32_u24_e32 v42, 0x110, v42
	v_add_u32_e32 v42, v93, v42
	ds_read_b32 v221, v42
	v_mul_u32_u24_e32 v41, 0x110, v41
	v_add_u32_e32 v41, v93, v41
	ds_read_b32 v222, v41
	v_mul_u32_u24_e32 v40, 0x110, v40
	v_add_u32_e32 v40, v93, v40
	ds_read_b32 v223, v40
	v_mul_u32_u24_e32 v38, 0x110, v38
	v_add_u32_e32 v38, v93, v38
	ds_read_b32 v224, v38
	v_mul_u32_u24_e32 v39, 0x110, v39
	v_add_u32_e32 v39, v93, v39
	ds_read_b32 v225, v39
	v_mul_u32_u24_e32 v37, 0x110, v37
	v_add_u32_e32 v37, v93, v37
	ds_read_b32 v226, v37
	v_mul_u32_u24_e32 v35, 0x110, v35
	v_add_u32_e32 v35, v93, v35
	ds_read_b32 v227, v35
	v_mul_u32_u24_e32 v36, 0x110, v36
	v_add_u32_e32 v36, v93, v36
	ds_read_b32 v228, v36
	v_mul_u32_u24_e32 v34, 0x110, v34
	v_add_u32_e32 v34, v93, v34
	ds_read_b32 v229, v34
	v_mul_u32_u24_e32 v33, 0x110, v33
	v_add_u32_e32 v33, v93, v33
	ds_read_b32 v230, v33
	v_mul_u32_u24_e32 v32, 0x110, v32
	v_add_u32_e32 v32, v93, v32
	ds_read_b32 v231, v32
	v_mul_u32_u24_e32 v31, 0x110, v31
	v_add_u32_e32 v31, v93, v31
	ds_read_b32 v232, v31
	v_mul_u32_u24_e32 v30, 0x110, v30
	v_add_u32_e32 v30, v93, v30
	ds_read_b32 v233, v30
	v_mul_u32_u24_e32 v29, 0x110, v29
	v_add_u32_e32 v29, v93, v29
	ds_read_b32 v234, v29
	v_mul_u32_u24_e32 v28, 0x110, v28
	v_add_u32_e32 v28, v93, v28
	ds_read_b32 v235, v28
	s_waitcnt lgkmcnt(15)
	v_lshlrev_b32_e32 v44, 16, v220
	v_and_b32_e32 v45, 0xffff0000, v220
	v_sub_f32_e32 v46, 1.0, v44
	v_sub_f32_e32 v47, 1.0, v45
	v_mul_f32_e32 v26, v26, v46
	v_mul_f32_e32 v27, v27, v47
	v_max_f32_e32 v46, 0xda24260, v26
	v_max_f32_e32 v47, 0xda24260, v27
	v_rcp_f32_e32 v46, v46
	v_rcp_f32_e32 v47, v47
	v_mov_b64_e32 v[86:87], s[12:13]
	s_waitcnt lgkmcnt(14)
	v_lshlrev_b32_e32 v244, 16, v221
	v_and_b32_e32 v245, 0xffff0000, v221
	v_sub_f32_e32 v242, 1.0, v244
	v_sub_f32_e32 v243, 1.0, v245
	v_pk_mul_f32 v[44:45], v[46:47], v[44:45]
	v_mul_f32_e32 v26, v26, v242
	v_mul_f32_e32 v27, v27, v243
	v_max_f32_e32 v242, 0xda24260, v26
	v_max_f32_e32 v243, 0xda24260, v27
	v_rcp_f32_e32 v242, v242
	v_rcp_f32_e32 v243, v243
	v_cvt_pk_bf16_f32 v44, v44, v45
	ds_write_b32 v43, v44
	s_waitcnt lgkmcnt(14)
	v_lshlrev_b32_e32 v44, 16, v222
	v_and_b32_e32 v45, 0xffff0000, v222
	v_sub_f32_e32 v46, 1.0, v44
	v_sub_f32_e32 v47, 1.0, v45
	v_pk_mul_f32 v[244:245], v[242:243], v[244:245]
	v_mul_f32_e32 v26, v26, v46
	v_mul_f32_e32 v27, v27, v47
	v_max_f32_e32 v46, 0xda24260, v26
	v_max_f32_e32 v47, 0xda24260, v27
	v_rcp_f32_e32 v46, v46
	v_rcp_f32_e32 v47, v47
	v_cvt_pk_bf16_f32 v244, v244, v245
	ds_write_b32 v42, v244
	s_waitcnt lgkmcnt(14)
	v_lshlrev_b32_e32 v244, 16, v223
	v_and_b32_e32 v245, 0xffff0000, v223
	v_sub_f32_e32 v242, 1.0, v244
	v_sub_f32_e32 v243, 1.0, v245
	v_pk_mul_f32 v[44:45], v[46:47], v[44:45]
	v_mul_f32_e32 v26, v26, v242
	v_mul_f32_e32 v27, v27, v243
	v_max_f32_e32 v242, 0xda24260, v26
	v_max_f32_e32 v243, 0xda24260, v27
	v_rcp_f32_e32 v242, v242
	v_rcp_f32_e32 v243, v243
	v_cvt_pk_bf16_f32 v44, v44, v45
	ds_write_b32 v41, v44
	global_load_dwordx4 v[18:21], v238, s[100:101] nt
	s_waitcnt lgkmcnt(14)
	v_lshlrev_b32_e32 v44, 16, v224
	v_and_b32_e32 v45, 0xffff0000, v224
	v_sub_f32_e32 v46, 1.0, v44
	v_sub_f32_e32 v47, 1.0, v45
	v_pk_mul_f32 v[244:245], v[242:243], v[244:245]
	v_mul_f32_e32 v26, v26, v46
	v_mul_f32_e32 v27, v27, v47
	v_max_f32_e32 v46, 0xda24260, v26
	v_max_f32_e32 v47, 0xda24260, v27
	v_rcp_f32_e32 v46, v46
	v_rcp_f32_e32 v47, v47
	v_cvt_pk_bf16_f32 v244, v244, v245
	ds_write_b32 v40, v244
	s_waitcnt lgkmcnt(14)
	v_lshlrev_b32_e32 v244, 16, v225
	v_and_b32_e32 v245, 0xffff0000, v225
	v_sub_f32_e32 v242, 1.0, v244
	v_sub_f32_e32 v243, 1.0, v245
	v_pk_mul_f32 v[44:45], v[46:47], v[44:45]
	v_mul_f32_e32 v26, v26, v242
	v_mul_f32_e32 v27, v27, v243
	v_max_f32_e32 v242, 0xda24260, v26
	v_max_f32_e32 v243, 0xda24260, v27
	v_rcp_f32_e32 v242, v242
	v_rcp_f32_e32 v243, v243
	v_cvt_pk_bf16_f32 v44, v44, v45
	ds_write_b32 v38, v44
	s_waitcnt lgkmcnt(14)
	v_lshlrev_b32_e32 v44, 16, v226
	v_and_b32_e32 v45, 0xffff0000, v226
	v_sub_f32_e32 v46, 1.0, v44
	v_sub_f32_e32 v47, 1.0, v45
	v_pk_mul_f32 v[244:245], v[242:243], v[244:245]
	v_mul_f32_e32 v26, v26, v46
	v_mul_f32_e32 v27, v27, v47
	v_max_f32_e32 v46, 0xda24260, v26
	v_max_f32_e32 v47, 0xda24260, v27
	v_rcp_f32_e32 v46, v46
	v_rcp_f32_e32 v47, v47
	v_cvt_pk_bf16_f32 v244, v244, v245
	ds_write_b32 v39, v244
	global_load_dwordx4 v[6:9], v239, s[100:101] nt
	s_waitcnt lgkmcnt(14)
	v_lshlrev_b32_e32 v244, 16, v227
	v_and_b32_e32 v245, 0xffff0000, v227
	v_sub_f32_e32 v242, 1.0, v244
	v_sub_f32_e32 v243, 1.0, v245
	v_pk_mul_f32 v[44:45], v[46:47], v[44:45]
	v_mul_f32_e32 v26, v26, v242
	v_mul_f32_e32 v27, v27, v243
	v_max_f32_e32 v242, 0xda24260, v26
	v_max_f32_e32 v243, 0xda24260, v27
	v_rcp_f32_e32 v242, v242
	v_rcp_f32_e32 v243, v243
	v_cvt_pk_bf16_f32 v44, v44, v45
	ds_write_b32 v37, v44
	s_waitcnt lgkmcnt(14)
	v_lshlrev_b32_e32 v44, 16, v228
	v_and_b32_e32 v45, 0xffff0000, v228
	v_sub_f32_e32 v46, 1.0, v44
	v_sub_f32_e32 v47, 1.0, v45
	v_pk_mul_f32 v[244:245], v[242:243], v[244:245]
	v_mul_f32_e32 v26, v26, v46
	v_mul_f32_e32 v27, v27, v47
	v_max_f32_e32 v46, 0xda24260, v26
	v_max_f32_e32 v47, 0xda24260, v27
	v_rcp_f32_e32 v46, v46
	v_rcp_f32_e32 v47, v47
	v_cvt_pk_bf16_f32 v244, v244, v245
	ds_write_b32 v35, v244
	s_waitcnt lgkmcnt(14)
	v_lshlrev_b32_e32 v244, 16, v229
	v_and_b32_e32 v245, 0xffff0000, v229
	v_sub_f32_e32 v242, 1.0, v244
	v_sub_f32_e32 v243, 1.0, v245
	v_pk_mul_f32 v[44:45], v[46:47], v[44:45]
	v_mul_f32_e32 v26, v26, v242
	v_mul_f32_e32 v27, v27, v243
	v_max_f32_e32 v242, 0xda24260, v26
	v_max_f32_e32 v243, 0xda24260, v27
	v_rcp_f32_e32 v242, v242
	v_rcp_f32_e32 v243, v243
	v_cvt_pk_bf16_f32 v44, v44, v45
	ds_write_b32 v36, v44
	global_load_dwordx4 v[14:17], v240, s[100:101] nt
	s_waitcnt lgkmcnt(14)
	v_lshlrev_b32_e32 v44, 16, v230
	v_and_b32_e32 v45, 0xffff0000, v230
	v_sub_f32_e32 v46, 1.0, v44
	v_sub_f32_e32 v47, 1.0, v45
	v_pk_mul_f32 v[244:245], v[242:243], v[244:245]
	v_mul_f32_e32 v26, v26, v46
	v_mul_f32_e32 v27, v27, v47
	v_max_f32_e32 v46, 0xda24260, v26
	v_max_f32_e32 v47, 0xda24260, v27
	v_rcp_f32_e32 v46, v46
	v_rcp_f32_e32 v47, v47
	v_cvt_pk_bf16_f32 v244, v244, v245
	ds_write_b32 v34, v244
	s_waitcnt lgkmcnt(14)
	v_lshlrev_b32_e32 v244, 16, v231
	v_and_b32_e32 v245, 0xffff0000, v231
	v_sub_f32_e32 v242, 1.0, v244
	v_sub_f32_e32 v243, 1.0, v245
	v_pk_mul_f32 v[44:45], v[46:47], v[44:45]
	v_mul_f32_e32 v26, v26, v242
	v_mul_f32_e32 v27, v27, v243
	v_max_f32_e32 v242, 0xda24260, v26
	v_max_f32_e32 v243, 0xda24260, v27
	v_rcp_f32_e32 v242, v242
	v_rcp_f32_e32 v243, v243
	v_cvt_pk_bf16_f32 v44, v44, v45
	ds_write_b32 v33, v44
	s_waitcnt lgkmcnt(14)
	v_lshlrev_b32_e32 v44, 16, v232
	v_and_b32_e32 v45, 0xffff0000, v232
	v_sub_f32_e32 v46, 1.0, v44
	v_sub_f32_e32 v47, 1.0, v45
	v_pk_mul_f32 v[244:245], v[242:243], v[244:245]
	v_mul_f32_e32 v26, v26, v46
	v_mul_f32_e32 v27, v27, v47
	v_max_f32_e32 v46, 0xda24260, v26
	v_max_f32_e32 v47, 0xda24260, v27
	v_rcp_f32_e32 v46, v46
	v_rcp_f32_e32 v47, v47
	v_cvt_pk_bf16_f32 v244, v244, v245
	ds_write_b32 v32, v244
	global_load_dwordx4 v[22:25], v241, s[100:101] nt
	s_waitcnt lgkmcnt(14)
	v_lshlrev_b32_e32 v244, 16, v233
	v_and_b32_e32 v245, 0xffff0000, v233
	v_sub_f32_e32 v242, 1.0, v244
	v_sub_f32_e32 v243, 1.0, v245
	v_pk_mul_f32 v[44:45], v[46:47], v[44:45]
	v_mul_f32_e32 v26, v26, v242
	v_mul_f32_e32 v27, v27, v243
	v_max_f32_e32 v242, 0xda24260, v26
	v_max_f32_e32 v243, 0xda24260, v27
	v_rcp_f32_e32 v242, v242
	v_rcp_f32_e32 v243, v243
	v_cvt_pk_bf16_f32 v44, v44, v45
	ds_write_b32 v31, v44
	s_waitcnt lgkmcnt(14)
	v_lshlrev_b32_e32 v44, 16, v234
	v_and_b32_e32 v45, 0xffff0000, v234
	v_sub_f32_e32 v46, 1.0, v44
	v_sub_f32_e32 v47, 1.0, v45
	v_pk_mul_f32 v[244:245], v[242:243], v[244:245]
	v_mul_f32_e32 v26, v26, v46
	v_mul_f32_e32 v27, v27, v47
	v_max_f32_e32 v46, 0xda24260, v26
	v_max_f32_e32 v47, 0xda24260, v27
	v_rcp_f32_e32 v46, v46
	v_rcp_f32_e32 v47, v47
	v_cvt_pk_bf16_f32 v244, v244, v245
	ds_write_b32 v30, v244
	s_waitcnt lgkmcnt(14)
	v_lshlrev_b32_e32 v244, 16, v235
	v_and_b32_e32 v245, 0xffff0000, v235
	v_sub_f32_e32 v242, 1.0, v244
	v_sub_f32_e32 v243, 1.0, v245
	v_pk_mul_f32 v[44:45], v[46:47], v[44:45]
	v_mul_f32_e32 v26, v26, v242
	v_mul_f32_e32 v27, v27, v243
	v_max_f32_e32 v242, 0xda24260, v26
	v_max_f32_e32 v243, 0xda24260, v27
	v_rcp_f32_e32 v242, v242
	v_rcp_f32_e32 v243, v243
	v_cvt_pk_bf16_f32 v44, v44, v45
	ds_write_b32 v29, v44
	s_nop 0
	v_pk_mul_f32 v[244:245], v[242:243], v[244:245]
	s_nop 0
	v_cvt_pk_bf16_f32 v244, v244, v245
	ds_write_b32 v28, v244
	s_waitcnt lgkmcnt(0)
	s_barrier
	s_and_saveexec_b64 s[42:43], s[40:41]
	s_cbranch_execz .LBB0_273
	ds_read2st64_b32 v[26:27], v110 offset0:204 offset1:206
	ds_read2st64_b32 v[28:29], v110 offset0:208 offset1:210
	s_bfe_i64 s[14:15], s[12:13], 0x200000
	v_mov_b64_e32 v[86:87], s[14:15]
	s_waitcnt lgkmcnt(1)
	v_mov_b32_e32 v30, v26
	s_waitcnt lgkmcnt(0)
	v_mov_b32_e32 v31, v28
	v_mov_b32_e32 v28, v27
	v_pk_mul_f32 v[26:27], v[30:31], v[28:29]
	s_nop 0
	v_mul_f32_e32 v26, v26, v27
	global_store_dword v[84:85], v26, off
	s_branch .LBB0_273
.LBB0_286:
	s_lshl_b32 s10, s8, 22
	s_and_b32 s10, s10, 0x1c00000
	s_add_u32 s14, s86, s10
	s_addc_u32 s15, s87, 0
	s_add_u32 s10, s14, 0x4000000
	s_addc_u32 s11, s15, 0
	s_ashr_i32 s12, s8, 3
	s_ashr_i32 s13, s12, 31
	s_lshl_b64 s[12:13], s[12:13], 13
	s_waitcnt vmcnt(13)
	v_lshl_add_u64 v[2:3], s[12:13], 0, v[60:61]
	s_add_u32 s14, s14, 0x2000000
	v_lshlrev_b64 v[2:3], 1, v[2:3]
	s_addc_u32 s15, s15, 0
	v_lshl_add_u64 v[4:5], s[10:11], 0, v[2:3]
	v_lshl_add_u64 v[2:3], s[14:15], 0, v[2:3]
	global_load_dwordx4 v[14:17], v[4:5], off nt
	global_load_dwordx4 v[6:9], v[2:3], off nt
	v_lshl_add_u64 v[2:3], s[12:13], 0, v[58:59]
	v_lshlrev_b64 v[2:3], 1, v[2:3]
	v_lshl_add_u64 v[4:5], s[10:11], 0, v[2:3]
	v_lshl_add_u64 v[2:3], s[14:15], 0, v[2:3]
	global_load_dwordx4 v[10:13], v[4:5], off nt
	s_nop 0
	global_load_dwordx4 v[2:5], v[2:3], off nt
	v_and_b32_e32 v0, 56, v63
	v_lshl_add_u32 v0, v0, 1, 0
	s_waitcnt vmcnt(15)
	v_ashrrev_i32_e32 v18, 3, v62
	s_movk_i32 s12, 0x90
	v_sub_u32_e32 v19, 0x7f, v18
	v_cvt_f32_i32_e32 v43, v18
	v_mad_u64_u32 v[34:35], s[10:11], v18, s12, v[0:1]
	v_ashrrev_i32_e32 v18, 3, v64
	v_mad_u64_u32 v[36:37], s[10:11], v18, s12, v[0:1]
	s_lshl_b32 s10, s17, 4
	s_and_b32 s10, s10, 48
	s_lshl_b32 s11, s10, 1
	s_lshl_b32 s12, s24, 6
	v_mul_u32_u24_e32 v0, 0x48, v88
	v_cvt_f32_i32_e32 v42, v19
	v_sub_u32_e32 v19, 0x7f, v18
	v_cvt_f32_i32_e32 v44, v18
	s_add_i32 s11, s11, 0
	s_add_i32 s12, s12, 0
	v_lshlrev_b32_e32 v0, 1, v0
	v_lshl_or_b32 v18, s24, 5, v65
	v_cvt_f32_i32_e32 v35, v19
	v_add3_u32 v37, s11, v89, v0
	v_add3_u32 v45, s12, v89, v0
	v_or_b32_e32 v0, s10, v91
	s_lshl_b64 s[10:11], s[8:9], 14
	v_or_b32_e32 v20, 16, v18
	v_ashrrev_i32_e32 v21, 31, v20
	s_add_u32 s12, s76, s10
	v_ashrrev_i32_e32 v19, 31, v18
	v_lshlrev_b64 v[20:21], 7, v[20:21]
	s_addc_u32 s13, s77, s11
	v_lshlrev_b64 v[18:19], 7, v[18:19]
	v_lshlrev_b32_e32 v0, 1, v0
	v_lshl_add_u64 v[38:39], s[12:13], 0, v[20:21]
	s_lshl_b64 s[10:11], s[2:3], 14
	v_lshl_add_u64 v[40:41], s[12:13], 0, v[18:19]
	s_waitcnt vmcnt(0)
	s_branch .LBB0_288

.LBB0_288:
	s_mov_b32 s9, s8
	s_add_i32 s8, s8, s2
	s_cmpk_gt_i32 s8, 0x7ff
	s_cselect_b64 s[12:13], -1, 0
	s_cmpk_lt_i32 s8, 0x800
	s_cselect_b32 s3, s8, -1
	s_and_b32 s9, s9, 7
	s_cmp_eq_u32 s9, 1
	s_cselect_b64 vcc, -1, 0
	s_cmp_lg_u32 s9, 2
	v_cndmask_b32_e32 v18, v181, v182, vcc
	s_cselect_b64 vcc, -1, 0
	s_cmp_lg_u32 s9, 3
	v_cndmask_b32_e32 v18, v183, v18, vcc
	s_cselect_b64 vcc, -1, 0
	s_cmp_lg_u32 s9, 4
	v_cndmask_b32_e32 v18, v184, v18, vcc
	s_cselect_b64 vcc, -1, 0
	s_cmp_lg_u32 s9, 5
	v_cndmask_b32_e32 v18, v185, v18, vcc
	s_cselect_b64 vcc, -1, 0
	s_cmp_lg_u32 s9, 6
	v_cndmask_b32_e32 v18, v186, v18, vcc
	s_cselect_b64 vcc, -1, 0
	s_cmp_lg_u32 s9, 7
	v_cndmask_b32_e32 v18, v187, v18, vcc
	s_cselect_b64 vcc, -1, 0
	v_cndmask_b32_e32 v31, v188, v18, vcc
	v_mul_f32_e32 v18, v31, v42
	v_exp_f32_e32 v18, v18
	v_mul_f32_e32 v19, v31, v43
	v_exp_f32_e32 v30, v19
	s_waitcnt vmcnt(4)
	v_lshlrev_b32_e32 v22, 16, v2
	v_and_b32_e32 v23, 0xffff0000, v2
	v_lshlrev_b32_e32 v24, 16, v3
	v_and_b32_e32 v25, 0xffff0000, v3
	v_lshlrev_b32_e32 v26, 16, v4
	v_and_b32_e32 v27, 0xffff0000, v4
	v_lshlrev_b32_e32 v28, 16, v5
	v_and_b32_e32 v29, 0xffff0000, v5
	v_pk_mul_f32 v[20:21], v[18:19], v[24:25] op_sel_hi:[0,1]
	v_pk_mul_f32 v[32:33], v[18:19], v[22:23] op_sel_hi:[0,1]
	v_pk_mul_f32 v[46:47], v[18:19], v[28:29] op_sel_hi:[0,1]
	v_pk_mul_f32 v[48:49], v[18:19], v[26:27] op_sel_hi:[0,1]
	v_cvt_pk_bf16_f32 v18, v32, v33
	v_cvt_pk_bf16_f32 v19, v20, v21
	v_cvt_pk_bf16_f32 v20, v48, v49
	v_cvt_pk_bf16_f32 v21, v46, v47
	ds_write_b128 v34, v[18:21]
	v_pk_mul_f32 v[20:21], v[30:31], v[24:25] op_sel_hi:[0,1]
	v_pk_mul_f32 v[18:19], v[30:31], v[22:23] op_sel_hi:[0,1]
	v_pk_mul_f32 v[22:23], v[30:31], v[28:29] op_sel_hi:[0,1]
	v_pk_mul_f32 v[24:25], v[30:31], v[26:27] op_sel_hi:[0,1]
	v_cvt_pk_bf16_f32 v18, v18, v19
	v_cvt_pk_bf16_f32 v19, v20, v21
	v_cvt_pk_bf16_f32 v20, v24, v25
	v_cvt_pk_bf16_f32 v21, v22, v23
	ds_write_b128 v34, v[18:21] offset:18432
	ds_write_b128 v34, v[10:13] offset:36864
	v_mul_f32_e32 v18, v31, v35
	v_exp_f32_e32 v18, v18
	v_mul_f32_e32 v19, v31, v44
	v_exp_f32_e32 v30, v19
	v_lshlrev_b32_e32 v22, 16, v6
	v_and_b32_e32 v23, 0xffff0000, v6
	v_lshlrev_b32_e32 v24, 16, v7
	v_and_b32_e32 v25, 0xffff0000, v7
	v_lshlrev_b32_e32 v26, 16, v8
	v_and_b32_e32 v27, 0xffff0000, v8
	v_lshlrev_b32_e32 v28, 16, v9
	v_and_b32_e32 v29, 0xffff0000, v9
	v_pk_mul_f32 v[20:21], v[18:19], v[24:25] op_sel_hi:[0,1]
	v_pk_mul_f32 v[32:33], v[18:19], v[22:23] op_sel_hi:[0,1]
	v_pk_mul_f32 v[46:47], v[18:19], v[28:29] op_sel_hi:[0,1]
	v_pk_mul_f32 v[48:49], v[18:19], v[26:27] op_sel_hi:[0,1]
	v_cvt_pk_bf16_f32 v18, v32, v33
	v_cvt_pk_bf16_f32 v19, v20, v21
	v_cvt_pk_bf16_f32 v20, v48, v49
	v_cvt_pk_bf16_f32 v21, v46, v47
	ds_write_b128 v36, v[18:21]
	v_pk_mul_f32 v[20:21], v[30:31], v[24:25] op_sel_hi:[0,1]
	v_pk_mul_f32 v[18:19], v[30:31], v[22:23] op_sel_hi:[0,1]
	v_pk_mul_f32 v[22:23], v[30:31], v[28:29] op_sel_hi:[0,1]
	v_pk_mul_f32 v[24:25], v[30:31], v[26:27] op_sel_hi:[0,1]
	v_cvt_pk_bf16_f32 v18, v18, v19
	v_cvt_pk_bf16_f32 v19, v20, v21
	v_cvt_pk_bf16_f32 v20, v24, v25
	v_cvt_pk_bf16_f32 v21, v22, v23
	s_cmp_lt_i32 s3, 0
	ds_write_b128 v36, v[18:21] offset:18432
	ds_write_b128 v36, v[14:17] offset:36864
	s_waitcnt lgkmcnt(0)
	s_barrier
	s_cbranch_scc1 .LBB0_287
	s_lshr_b32 s80, s3, 3
	s_lshl_b32 s3, s3, 22
	s_lshl_b64 s[14:15], s[80:81], 13
	s_and_b32 s3, s3, 0x1c00000
	s_add_u32 s3, s86, s3
	s_addc_u32 s9, s87, 0
	s_add_u32 s24, s3, 0x2000000
	s_addc_u32 s25, s9, 0
	s_add_u32 s26, s3, 0x4000000
	v_lshl_add_u64 v[2:3], s[14:15], 0, v[58:59]
	s_addc_u32 s27, s9, 0
	v_lshlrev_b64 v[2:3], 1, v[2:3]
	v_lshl_add_u64 v[4:5], s[24:25], 0, v[2:3]
	v_lshl_add_u64 v[6:7], s[26:27], 0, v[2:3]
	global_load_dwordx4 v[2:5], v[4:5], off nt
	s_nop 0
	global_load_dwordx4 v[10:13], v[6:7], off nt
	v_lshl_add_u64 v[6:7], s[14:15], 0, v[60:61]
	v_lshlrev_b64 v[6:7], 1, v[6:7]
	v_lshl_add_u64 v[8:9], s[24:25], 0, v[6:7]
	v_lshl_add_u64 v[14:15], s[26:27], 0, v[6:7]
	global_load_dwordx4 v[6:9], v[8:9], off nt
	s_nop 0
	global_load_dwordx4 v[14:17], v[14:15], off nt
	s_branch .LBB0_287

.LBB0_363:
	v_mov_b32_e32 v0, s24
	v_mov_b32_e32 v2, s17
	s_xor_b32 s25, s17, -2
	v_cndmask_b32_e32 v0, v0, v2, vcc
	s_add_i32 s25, s25, s13
	s_add_i32 s26, s17, 1
	v_add_u32_e32 v108, v0, v124
	v_mov_b32_e32 v0, s25
	v_mov_b32_e32 v10, s26
	s_xor_b32 s25, s17, -3
	v_cndmask_b32_e32 v0, v0, v10, vcc
	s_add_i32 s25, s25, s13
	s_add_i32 s26, s17, 2
	v_add_u32_e32 v110, v0, v124
	v_mov_b32_e32 v0, s25
	v_mov_b32_e32 v26, s26
	s_xor_b32 s25, s17, -4
	v_ashrrev_i32_e32 v109, 31, v108
	v_cndmask_b32_e32 v0, v0, v26, vcc
	s_add_i32 s25, s25, s13
	s_add_i32 s26, s17, 3
	v_lshlrev_b64 v[2:3], 10, v[108:109]
	v_ashrrev_i32_e32 v111, 31, v110
	v_add_u32_e32 v112, v0, v124
	v_mov_b32_e32 v0, s25
	v_mov_b32_e32 v38, s26
	s_xor_b32 s25, s17, -5
	v_or_b32_e32 v2, v2, v96
	v_lshlrev_b64 v[10:11], 10, v[110:111]
	v_cndmask_b32_e32 v0, v0, v38, vcc
	s_add_i32 s25, s25, s13
	s_add_i32 s26, s17, 4
	v_or_b32_e32 v4, v2, v90
	v_mov_b32_e32 v5, v3
	v_or_b32_e32 v10, v10, v96
	v_ashrrev_i32_e32 v113, 31, v112
	v_add_u32_e32 v114, v0, v124
	v_mov_b32_e32 v0, s25
	v_mov_b32_e32 v50, s26
	s_xor_b32 s25, s17, -6
	v_lshlrev_b64 v[4:5], 8, v[4:5]
	v_or_b32_e32 v12, v10, v90
	v_mov_b32_e32 v13, v11
	v_lshlrev_b64 v[26:27], 10, v[112:113]
	v_cndmask_b32_e32 v0, v0, v50, vcc
	s_add_i32 s25, s25, s13
	s_add_i32 s26, s17, 5
	v_lshl_add_u64 v[4:5], v[92:93], 0, v[4:5]
	v_lshlrev_b64 v[12:13], 8, v[12:13]
	v_or_b32_e32 v26, v26, v96
	v_ashrrev_i32_e32 v115, 31, v114
	v_add_u32_e32 v116, v0, v124
	v_mov_b32_e32 v0, s25
	v_mov_b32_e32 v62, s26
	s_xor_b32 s25, s17, -7
	global_load_dwordx4 v[22:25], v[4:5], off nt
	v_lshl_add_u64 v[6:7], v[2:3], 2, v[94:95]
	v_lshl_add_u64 v[12:13], v[92:93], 0, v[12:13]
	v_or_b32_e32 v28, v26, v90
	v_mov_b32_e32 v29, v27
	v_lshlrev_b64 v[38:39], 10, v[114:115]
	v_cndmask_b32_e32 v0, v0, v62, vcc
	s_add_i32 s25, s25, s13
	s_add_i32 s26, s17, 6
	global_load_dwordx4 v[2:5], v[6:7], off offset:16 nt
	s_nop 0
	global_load_dwordx4 v[6:9], v[6:7], off nt
	v_lshl_add_u64 v[14:15], v[10:11], 2, v[94:95]
	global_load_dwordx4 v[18:21], v[12:13], off nt
	v_lshlrev_b64 v[28:29], 8, v[28:29]
	v_or_b32_e32 v38, v38, v96
	v_ashrrev_i32_e32 v117, 31, v116
	v_add_u32_e32 v118, v0, v124
	v_mov_b32_e32 v0, s25
	v_mov_b32_e32 v74, s26
	s_xor_b32 s25, s17, -8
	global_load_dwordx4 v[10:13], v[14:15], off offset:16 nt
	s_nop 0
	global_load_dwordx4 v[14:17], v[14:15], off nt
	v_lshl_add_u64 v[28:29], v[92:93], 0, v[28:29]
	v_or_b32_e32 v40, v38, v90
	v_mov_b32_e32 v41, v39
	v_lshlrev_b64 v[50:51], 10, v[116:117]
	v_cndmask_b32_e32 v0, v0, v74, vcc
	s_add_i32 s25, s25, s13
	s_add_i32 s26, s17, 7
	global_load_dwordx4 v[34:37], v[28:29], off nt
	v_lshl_add_u64 v[30:31], v[26:27], 2, v[94:95]
	v_lshlrev_b64 v[40:41], 8, v[40:41]
	v_or_b32_e32 v50, v50, v96
	v_ashrrev_i32_e32 v119, 31, v118
	v_add_u32_e32 v120, v0, v124
	v_mov_b32_e32 v0, s25
	v_mov_b32_e32 v86, s26
	global_load_dwordx4 v[26:29], v[30:31], off offset:16 nt
	s_nop 0
	global_load_dwordx4 v[30:33], v[30:31], off nt
	v_lshl_add_u64 v[40:41], v[92:93], 0, v[40:41]
	v_or_b32_e32 v52, v50, v90
	v_mov_b32_e32 v53, v51
	v_lshlrev_b64 v[62:63], 10, v[118:119]
	v_cndmask_b32_e32 v0, v0, v86, vcc
	global_load_dwordx4 v[46:49], v[40:41], off nt
	v_lshl_add_u64 v[42:43], v[38:39], 2, v[94:95]
	v_lshlrev_b64 v[52:53], 8, v[52:53]
	v_or_b32_e32 v62, v62, v96
	v_ashrrev_i32_e32 v121, 31, v120
	v_add_u32_e32 v122, v0, v124
	global_load_dwordx4 v[38:41], v[42:43], off offset:16 nt
	s_nop 0
	global_load_dwordx4 v[42:45], v[42:43], off nt
	v_lshl_add_u64 v[52:53], v[92:93], 0, v[52:53]
	v_or_b32_e32 v64, v62, v90
	v_mov_b32_e32 v65, v63
	v_lshlrev_b64 v[74:75], 10, v[120:121]
	v_ashrrev_i32_e32 v123, 31, v122
	global_load_dwordx4 v[58:61], v[52:53], off nt
	v_lshl_add_u64 v[54:55], v[50:51], 2, v[94:95]
	v_lshlrev_b64 v[64:65], 8, v[64:65]
	v_or_b32_e32 v74, v74, v96
	v_lshlrev_b64 v[86:87], 10, v[122:123]
	global_load_dwordx4 v[50:53], v[54:55], off offset:16 nt
	s_nop 0
	global_load_dwordx4 v[54:57], v[54:55], off nt
	v_lshl_add_u64 v[64:65], v[92:93], 0, v[64:65]
	v_or_b32_e32 v76, v74, v90
	v_mov_b32_e32 v77, v75
	v_or_b32_e32 v86, v86, v96
	global_load_dwordx4 v[70:73], v[64:65], off nt
	v_lshl_add_u64 v[66:67], v[62:63], 2, v[94:95]
	v_lshlrev_b64 v[76:77], 8, v[76:77]
	v_or_b32_e32 v88, v86, v90
	v_mov_b32_e32 v89, v87
	global_load_dwordx4 v[62:65], v[66:67], off offset:16 nt
	s_nop 0
	global_load_dwordx4 v[66:69], v[66:67], off nt
	v_lshl_add_u64 v[76:77], v[92:93], 0, v[76:77]
	v_lshlrev_b64 v[88:89], 8, v[88:89]
	global_load_dwordx4 v[82:85], v[76:77], off nt
	v_lshl_add_u64 v[78:79], v[74:75], 2, v[94:95]
	v_lshl_add_u64 v[88:89], v[92:93], 0, v[88:89]
	global_load_dwordx4 v[74:77], v[78:79], off offset:16 nt
	s_nop 0
	global_load_dwordx4 v[78:81], v[78:79], off nt
	v_lshl_add_u64 v[130:131], v[86:87], 2, v[94:95]
	global_load_dwordx4 v[126:129], v[88:89], off nt
	s_nop 0
	global_load_dwordx4 v[86:89], v[130:131], off offset:16 nt
	s_nop 0
	global_load_dwordx4 v[130:133], v[130:131], off nt
	v_lshlrev_b64 v[108:109], 18, v[108:109]
	v_lshl_add_u64 v[108:109], v[98:99], 0, v[108:109]
	s_waitcnt vmcnt(23)
	v_lshlrev_b32_e32 v134, 16, v22
	v_and_b32_e32 v135, 0xffff0000, v22
	v_lshlrev_b32_e32 v136, 16, v23
	v_and_b32_e32 v137, 0xffff0000, v23
	v_lshlrev_b32_e32 v138, 16, v24
	v_and_b32_e32 v139, 0xffff0000, v24
	v_lshlrev_b32_e32 v140, 16, v25
	v_and_b32_e32 v141, 0xffff0000, v25
	v_cvt_pk_bf16_f32 v22, v100, v101
	v_cvt_pk_bf16_f32 v23, v102, v103
	v_cvt_pk_bf16_f32 v24, v104, v105
	v_cvt_pk_bf16_f32 v25, v106, v107
	global_store_dwordx4 v[108:109], v[22:25], off
	s_waitcnt vmcnt(22)
	v_pk_fma_f32 v[8:9], v[102:103], v[8:9], v[136:137]
	v_pk_fma_f32 v[6:7], v[100:101], v[6:7], v[134:135]
	v_pk_fma_f32 v[22:23], v[106:107], v[4:5], v[140:141]
	v_pk_fma_f32 v[24:25], v[104:105], v[2:3], v[138:139]
	s_waitcnt vmcnt(21)
	v_lshlrev_b32_e32 v100, 16, v18
	v_and_b32_e32 v101, 0xffff0000, v18
	v_lshlrev_b32_e32 v18, 16, v19
	v_and_b32_e32 v19, 0xffff0000, v19
	v_lshlrev_b32_e32 v102, 16, v20
	v_and_b32_e32 v103, 0xffff0000, v20
	v_lshlrev_b32_e32 v20, 16, v21
	v_and_b32_e32 v21, 0xffff0000, v21
	v_lshlrev_b64 v[104:105], 18, v[110:111]
	v_cvt_pk_bf16_f32 v2, v6, v7
	v_cvt_pk_bf16_f32 v3, v8, v9
	v_cvt_pk_bf16_f32 v4, v24, v25
	v_cvt_pk_bf16_f32 v5, v22, v23
	v_lshl_add_u64 v[104:105], v[98:99], 0, v[104:105]
	s_waitcnt vmcnt(19)
	v_pk_fma_f32 v[8:9], v[16:17], v[8:9], v[18:19]
	v_pk_fma_f32 v[6:7], v[14:15], v[6:7], v[100:101]
	v_pk_fma_f32 v[12:13], v[12:13], v[22:23], v[20:21]
	v_pk_fma_f32 v[10:11], v[10:11], v[24:25], v[102:103]
	v_lshlrev_b64 v[22:23], 18, v[112:113]
	global_store_dwordx4 v[104:105], v[2:5], off
	s_waitcnt vmcnt(19)
	v_lshlrev_b32_e32 v14, 16, v34
	v_and_b32_e32 v15, 0xffff0000, v34
	v_lshlrev_b32_e32 v16, 16, v35
	v_and_b32_e32 v17, 0xffff0000, v35
	v_lshlrev_b32_e32 v18, 16, v36
	v_and_b32_e32 v19, 0xffff0000, v36
	v_lshlrev_b32_e32 v20, 16, v37
	v_and_b32_e32 v21, 0xffff0000, v37
	v_cvt_pk_bf16_f32 v2, v6, v7
	v_cvt_pk_bf16_f32 v3, v8, v9
	v_cvt_pk_bf16_f32 v4, v10, v11
	v_cvt_pk_bf16_f32 v5, v12, v13
	v_lshl_add_u64 v[22:23], v[98:99], 0, v[22:23]
	global_store_dwordx4 v[22:23], v[2:5], off
	s_waitcnt vmcnt(18)
	v_pk_fma_f32 v[8:9], v[32:33], v[8:9], v[16:17]
	v_pk_fma_f32 v[6:7], v[30:31], v[6:7], v[14:15]
	v_pk_fma_f32 v[12:13], v[28:29], v[12:13], v[20:21]
	v_pk_fma_f32 v[10:11], v[26:27], v[10:11], v[18:19]
	v_lshlrev_b64 v[22:23], 18, v[114:115]
	s_waitcnt vmcnt(17)
	v_lshlrev_b32_e32 v14, 16, v46
	v_and_b32_e32 v15, 0xffff0000, v46
	v_lshlrev_b32_e32 v16, 16, v47
	v_and_b32_e32 v17, 0xffff0000, v47
	v_lshlrev_b32_e32 v18, 16, v48
	v_and_b32_e32 v19, 0xffff0000, v48
	v_lshlrev_b32_e32 v20, 16, v49
	v_and_b32_e32 v21, 0xffff0000, v49
	v_cvt_pk_bf16_f32 v2, v6, v7
	v_cvt_pk_bf16_f32 v3, v8, v9
	v_cvt_pk_bf16_f32 v4, v10, v11
	v_cvt_pk_bf16_f32 v5, v12, v13
	v_lshl_add_u64 v[22:23], v[98:99], 0, v[22:23]
	global_store_dwordx4 v[22:23], v[2:5], off
	s_waitcnt vmcnt(16)
	v_pk_fma_f32 v[8:9], v[44:45], v[8:9], v[16:17]
	v_pk_fma_f32 v[6:7], v[42:43], v[6:7], v[14:15]
	v_pk_fma_f32 v[12:13], v[40:41], v[12:13], v[20:21]
	v_pk_fma_f32 v[10:11], v[38:39], v[10:11], v[18:19]
	v_lshlrev_b64 v[22:23], 18, v[116:117]
	s_waitcnt vmcnt(15)
	v_lshlrev_b32_e32 v14, 16, v58
	v_and_b32_e32 v15, 0xffff0000, v58
	v_lshlrev_b32_e32 v16, 16, v59
	v_and_b32_e32 v17, 0xffff0000, v59
	v_lshlrev_b32_e32 v18, 16, v60
	v_and_b32_e32 v19, 0xffff0000, v60
	v_lshlrev_b32_e32 v20, 16, v61
	v_and_b32_e32 v21, 0xffff0000, v61
	v_cvt_pk_bf16_f32 v2, v6, v7
	v_cvt_pk_bf16_f32 v3, v8, v9
	v_cvt_pk_bf16_f32 v4, v10, v11
	v_cvt_pk_bf16_f32 v5, v12, v13
	v_lshl_add_u64 v[22:23], v[98:99], 0, v[22:23]
	global_store_dwordx4 v[22:23], v[2:5], off
	s_waitcnt vmcnt(14)
	v_pk_fma_f32 v[8:9], v[56:57], v[8:9], v[16:17]
	v_pk_fma_f32 v[6:7], v[54:55], v[6:7], v[14:15]
	v_pk_fma_f32 v[12:13], v[52:53], v[12:13], v[20:21]
	v_pk_fma_f32 v[10:11], v[50:51], v[10:11], v[18:19]
	v_lshlrev_b64 v[22:23], 18, v[118:119]
	s_waitcnt vmcnt(13)
	v_lshlrev_b32_e32 v14, 16, v70
	v_and_b32_e32 v15, 0xffff0000, v70
	v_lshlrev_b32_e32 v16, 16, v71
	v_and_b32_e32 v17, 0xffff0000, v71
	v_lshlrev_b32_e32 v18, 16, v72
	v_and_b32_e32 v19, 0xffff0000, v72
	v_lshlrev_b32_e32 v20, 16, v73
	v_and_b32_e32 v21, 0xffff0000, v73
	v_cvt_pk_bf16_f32 v2, v6, v7
	v_cvt_pk_bf16_f32 v3, v8, v9
	v_cvt_pk_bf16_f32 v4, v10, v11
	v_cvt_pk_bf16_f32 v5, v12, v13
	v_lshl_add_u64 v[22:23], v[98:99], 0, v[22:23]
	global_store_dwordx4 v[22:23], v[2:5], off
	s_waitcnt vmcnt(12)
	v_pk_fma_f32 v[8:9], v[68:69], v[8:9], v[16:17]
	v_pk_fma_f32 v[6:7], v[66:67], v[6:7], v[14:15]
	v_pk_fma_f32 v[12:13], v[64:65], v[12:13], v[20:21]
	v_pk_fma_f32 v[10:11], v[62:63], v[10:11], v[18:19]
	v_lshlrev_b64 v[22:23], 18, v[120:121]
	s_waitcnt vmcnt(11)
	v_lshlrev_b32_e32 v14, 16, v82
	v_and_b32_e32 v15, 0xffff0000, v82
	v_lshlrev_b32_e32 v16, 16, v83
	v_and_b32_e32 v17, 0xffff0000, v83
	v_lshlrev_b32_e32 v18, 16, v84
	v_and_b32_e32 v19, 0xffff0000, v84
	v_lshlrev_b32_e32 v20, 16, v85
	v_and_b32_e32 v21, 0xffff0000, v85
	v_cvt_pk_bf16_f32 v2, v6, v7
	v_cvt_pk_bf16_f32 v3, v8, v9
	v_cvt_pk_bf16_f32 v4, v10, v11
	v_cvt_pk_bf16_f32 v5, v12, v13
	v_lshl_add_u64 v[22:23], v[98:99], 0, v[22:23]
	global_store_dwordx4 v[22:23], v[2:5], off
	s_waitcnt vmcnt(10)
	v_pk_fma_f32 v[8:9], v[80:81], v[8:9], v[16:17]
	v_pk_fma_f32 v[6:7], v[78:79], v[6:7], v[14:15]
	v_pk_fma_f32 v[12:13], v[76:77], v[12:13], v[20:21]
	v_pk_fma_f32 v[10:11], v[74:75], v[10:11], v[18:19]
	s_waitcnt vmcnt(9)
	v_lshlrev_b32_e32 v14, 16, v126
	v_and_b32_e32 v15, 0xffff0000, v126
	v_lshlrev_b32_e32 v16, 16, v127
	v_and_b32_e32 v17, 0xffff0000, v127
	v_lshlrev_b32_e32 v18, 16, v128
	v_and_b32_e32 v19, 0xffff0000, v128
	v_lshlrev_b32_e32 v20, 16, v129
	v_and_b32_e32 v21, 0xffff0000, v129
	v_lshlrev_b64 v[22:23], 18, v[122:123]
	s_add_i32 s24, s24, -8
	s_add_i32 s17, s17, 8
	v_cvt_pk_bf16_f32 v2, v6, v7
	v_cvt_pk_bf16_f32 v3, v8, v9
	v_cvt_pk_bf16_f32 v4, v10, v11
	v_cvt_pk_bf16_f32 v5, v12, v13
	v_lshl_add_u64 v[22:23], v[98:99], 0, v[22:23]
	s_waitcnt vmcnt(7)
	v_pk_fma_f32 v[102:103], v[132:133], v[8:9], v[16:17]
	v_pk_fma_f32 v[100:101], v[130:131], v[6:7], v[14:15]
	v_pk_fma_f32 v[106:107], v[88:89], v[12:13], v[20:21]
	v_pk_fma_f32 v[104:105], v[86:87], v[10:11], v[18:19]
	s_cmp_ge_u32 s17, s13
	global_store_dwordx4 v[22:23], v[2:5], off
	s_cbranch_scc0 .LBB0_363
	v_add_u32_e32 v97, s10, v97
	v_cmp_le_i32_e32 vcc, s12, v97
	s_or_b64 s[8:9], vcc, s[8:9]
	s_andn2_b64 exec, exec, s[8:9]
	s_cbranch_execnz .LBB0_362

.LBB0_368:
	v_mov_b32_e32 v0, s16
	v_mov_b32_e32 v2, s15
	v_cndmask_b32_e32 v0, v0, v2, vcc
	v_add_u32_e32 v2, v0, v54
	v_ashrrev_i32_e32 v3, 31, v2
	v_lshlrev_b64 v[42:43], 17, v[2:3]
	s_xor_b32 s17, s15, -2
	v_lshl_add_u64 v[2:3], v[30:31], 0, v[42:43]
	s_add_i32 s17, s17, s12
	s_add_i32 s24, s15, 1
	global_load_dwordx4 v[10:13], v[2:3], off nt
	v_mov_b32_e32 v0, s17
	v_mov_b32_e32 v2, s24
	s_xor_b32 s17, s15, -3
	v_cndmask_b32_e32 v0, v0, v2, vcc
	s_add_i32 s17, s17, s12
	s_add_i32 s24, s15, 2
	v_add_u32_e32 v2, v0, v54
	v_mov_b32_e32 v0, s17
	v_mov_b32_e32 v6, s24
	s_xor_b32 s17, s15, -4
	v_cndmask_b32_e32 v0, v0, v6, vcc
	s_add_i32 s17, s17, s12
	s_add_i32 s24, s15, 3
	v_add_u32_e32 v6, v0, v54
	v_mov_b32_e32 v0, s17
	v_mov_b32_e32 v14, s24
	s_xor_b32 s17, s15, -5
	v_cndmask_b32_e32 v0, v0, v14, vcc
	s_add_i32 s17, s17, s12
	s_add_i32 s24, s15, 4
	v_add_u32_e32 v14, v0, v54
	v_mov_b32_e32 v0, s17
	v_mov_b32_e32 v18, s24
	s_xor_b32 s17, s15, -6
	v_cndmask_b32_e32 v0, v0, v18, vcc
	s_add_i32 s17, s17, s12
	s_add_i32 s24, s15, 5
	v_add_u32_e32 v18, v0, v54
	v_mov_b32_e32 v0, s17
	v_mov_b32_e32 v22, s24
	s_xor_b32 s17, s15, -7
	v_ashrrev_i32_e32 v3, 31, v2
	v_cndmask_b32_e32 v0, v0, v22, vcc
	s_add_i32 s17, s17, s12
	s_add_i32 s24, s15, 6
	v_lshlrev_b64 v[44:45], 17, v[2:3]
	v_ashrrev_i32_e32 v7, 31, v6
	v_add_u32_e32 v22, v0, v54
	v_mov_b32_e32 v0, s17
	v_mov_b32_e32 v55, s24
	s_xor_b32 s17, s15, -8
	v_lshl_add_u64 v[2:3], v[30:31], 0, v[44:45]
	v_lshlrev_b64 v[46:47], 17, v[6:7]
	v_ashrrev_i32_e32 v15, 31, v14
	v_cndmask_b32_e32 v0, v0, v55, vcc
	s_add_i32 s17, s17, s12
	s_add_i32 s24, s15, 7
	global_load_dwordx4 v[2:5], v[2:3], off nt
	v_lshl_add_u64 v[6:7], v[30:31], 0, v[46:47]
	v_lshlrev_b64 v[48:49], 17, v[14:15]
	v_ashrrev_i32_e32 v19, 31, v18
	v_add_u32_e32 v56, v0, v54
	v_mov_b32_e32 v0, s17
	v_mov_b32_e32 v55, s24
	global_load_dwordx4 v[6:9], v[6:7], off nt
	v_lshl_add_u64 v[14:15], v[30:31], 0, v[48:49]
	v_lshlrev_b64 v[50:51], 17, v[18:19]
	v_ashrrev_i32_e32 v23, 31, v22
	v_cndmask_b32_e32 v0, v0, v55, vcc
	global_load_dwordx4 v[14:17], v[14:15], off nt
	v_lshl_add_u64 v[18:19], v[30:31], 0, v[50:51]
	v_lshlrev_b64 v[52:53], 17, v[22:23]
	v_ashrrev_i32_e32 v57, 31, v56
	v_add_u32_e32 v60, v0, v54
	global_load_dwordx4 v[18:21], v[18:19], off nt
	v_lshl_add_u64 v[22:23], v[30:31], 0, v[52:53]
	v_lshlrev_b64 v[64:65], 17, v[56:57]
	v_ashrrev_i32_e32 v61, 31, v60
	global_load_dwordx4 v[22:25], v[22:23], off nt
	v_lshl_add_u64 v[56:57], v[30:31], 0, v[64:65]
	v_lshlrev_b64 v[66:67], 17, v[60:61]
	global_load_dwordx4 v[56:59], v[56:57], off nt
	v_lshl_add_u64 v[60:61], v[30:31], 0, v[66:67]
	global_load_dwordx4 v[60:63], v[60:61], off nt
	v_lshl_add_u64 v[42:43], v[32:33], 0, v[42:43]
	v_lshl_add_u64 v[44:45], v[32:33], 0, v[44:45]
	s_add_i32 s16, s16, -8
	s_add_i32 s15, s15, 8
	s_cmp_ge_u32 s15, s12
	s_waitcnt vmcnt(7)
	v_lshlrev_b32_e32 v68, 16, v10
	v_and_b32_e32 v69, 0xffff0000, v10
	v_lshlrev_b32_e32 v70, 16, v11
	v_and_b32_e32 v71, 0xffff0000, v11
	v_lshlrev_b32_e32 v72, 16, v12
	v_and_b32_e32 v73, 0xffff0000, v12
	v_lshlrev_b32_e32 v74, 16, v13
	v_and_b32_e32 v75, 0xffff0000, v13
	v_cvt_pk_bf16_f32 v10, v38, v39
	v_cvt_pk_bf16_f32 v11, v40, v41
	v_cvt_pk_bf16_f32 v12, v34, v35
	v_cvt_pk_bf16_f32 v13, v36, v37
	global_store_dwordx4 v[42:43], v[10:13], off
	v_pk_fma_f32 v[36:37], v[28:29], v[36:37], v[74:75]
	v_pk_fma_f32 v[34:35], v[26:27], v[34:35], v[72:73]
	v_pk_fma_f32 v[10:11], v[28:29], v[40:41], v[70:71]
	v_pk_fma_f32 v[12:13], v[26:27], v[38:39], v[68:69]
	s_waitcnt vmcnt(7)
	v_lshlrev_b32_e32 v38, 16, v2
	v_and_b32_e32 v39, 0xffff0000, v2
	v_lshlrev_b32_e32 v40, 16, v3
	v_and_b32_e32 v41, 0xffff0000, v3
	v_lshlrev_b32_e32 v42, 16, v4
	v_and_b32_e32 v43, 0xffff0000, v4
	v_lshlrev_b32_e32 v68, 16, v5
	v_and_b32_e32 v69, 0xffff0000, v5
	v_cvt_pk_bf16_f32 v2, v12, v13
	v_cvt_pk_bf16_f32 v3, v10, v11
	v_cvt_pk_bf16_f32 v4, v34, v35
	v_cvt_pk_bf16_f32 v5, v36, v37
	v_pk_fma_f32 v[10:11], v[28:29], v[10:11], v[40:41]
	v_pk_fma_f32 v[12:13], v[26:27], v[12:13], v[38:39]
	v_pk_fma_f32 v[36:37], v[28:29], v[36:37], v[68:69]
	v_pk_fma_f32 v[34:35], v[26:27], v[34:35], v[42:43]
	s_waitcnt vmcnt(6)
	v_lshlrev_b32_e32 v38, 16, v6
	v_and_b32_e32 v39, 0xffff0000, v6
	v_lshlrev_b32_e32 v6, 16, v7
	v_and_b32_e32 v7, 0xffff0000, v7
	v_lshlrev_b32_e32 v40, 16, v8
	v_and_b32_e32 v41, 0xffff0000, v8
	v_lshlrev_b32_e32 v8, 16, v9
	v_and_b32_e32 v9, 0xffff0000, v9
	global_store_dwordx4 v[44:45], v[2:5], off
	v_lshl_add_u64 v[42:43], v[32:33], 0, v[46:47]
	v_pk_fma_f32 v[6:7], v[28:29], v[10:11], v[6:7]
	v_cvt_pk_bf16_f32 v2, v12, v13
	v_cvt_pk_bf16_f32 v3, v10, v11
	v_cvt_pk_bf16_f32 v4, v34, v35
	v_cvt_pk_bf16_f32 v5, v36, v37
	v_pk_fma_f32 v[10:11], v[26:27], v[12:13], v[38:39]
	v_pk_fma_f32 v[8:9], v[28:29], v[36:37], v[8:9]
	v_pk_fma_f32 v[12:13], v[26:27], v[34:35], v[40:41]
	s_waitcnt vmcnt(6)
	v_lshlrev_b32_e32 v34, 16, v14
	v_and_b32_e32 v35, 0xffff0000, v14
	v_lshlrev_b32_e32 v14, 16, v15
	v_and_b32_e32 v15, 0xffff0000, v15
	v_lshlrev_b32_e32 v36, 16, v16
	v_and_b32_e32 v37, 0xffff0000, v16
	v_lshlrev_b32_e32 v16, 16, v17
	v_and_b32_e32 v17, 0xffff0000, v17
	global_store_dwordx4 v[42:43], v[2:5], off
	v_lshl_add_u64 v[38:39], v[32:33], 0, v[48:49]
	s_nop 0
	v_cvt_pk_bf16_f32 v2, v10, v11
	v_cvt_pk_bf16_f32 v3, v6, v7
	v_cvt_pk_bf16_f32 v4, v12, v13
	v_cvt_pk_bf16_f32 v5, v8, v9
	v_pk_fma_f32 v[6:7], v[28:29], v[6:7], v[14:15]
	v_pk_fma_f32 v[10:11], v[26:27], v[10:11], v[34:35]
	v_pk_fma_f32 v[8:9], v[28:29], v[8:9], v[16:17]
	v_pk_fma_f32 v[12:13], v[26:27], v[12:13], v[36:37]
	s_waitcnt vmcnt(6)
	v_lshlrev_b32_e32 v14, 16, v18
	v_and_b32_e32 v15, 0xffff0000, v18
	v_lshlrev_b32_e32 v16, 16, v19
	v_and_b32_e32 v17, 0xffff0000, v19
	v_lshlrev_b32_e32 v18, 16, v20
	v_and_b32_e32 v19, 0xffff0000, v20
	v_lshlrev_b32_e32 v20, 16, v21
	v_and_b32_e32 v21, 0xffff0000, v21
	global_store_dwordx4 v[38:39], v[2:5], off
	v_lshl_add_u64 v[34:35], v[32:33], 0, v[50:51]
	s_nop 0
	v_cvt_pk_bf16_f32 v2, v10, v11
	v_cvt_pk_bf16_f32 v3, v6, v7
	v_cvt_pk_bf16_f32 v4, v12, v13
	v_cvt_pk_bf16_f32 v5, v8, v9
	v_pk_fma_f32 v[6:7], v[28:29], v[6:7], v[16:17]
	v_pk_fma_f32 v[10:11], v[26:27], v[10:11], v[14:15]
	v_pk_fma_f32 v[8:9], v[28:29], v[8:9], v[20:21]
	v_pk_fma_f32 v[12:13], v[26:27], v[12:13], v[18:19]
	s_waitcnt vmcnt(6)
	v_lshlrev_b32_e32 v14, 16, v22
	v_and_b32_e32 v15, 0xffff0000, v22
	v_lshlrev_b32_e32 v16, 16, v23
	v_and_b32_e32 v17, 0xffff0000, v23
	v_lshlrev_b32_e32 v18, 16, v24
	v_and_b32_e32 v19, 0xffff0000, v24
	v_lshlrev_b32_e32 v20, 16, v25
	v_and_b32_e32 v21, 0xffff0000, v25
	global_store_dwordx4 v[34:35], v[2:5], off
	v_lshl_add_u64 v[22:23], v[32:33], 0, v[52:53]
	s_nop 0
	v_cvt_pk_bf16_f32 v2, v10, v11
	v_cvt_pk_bf16_f32 v3, v6, v7
	v_cvt_pk_bf16_f32 v4, v12, v13
	v_cvt_pk_bf16_f32 v5, v8, v9
	v_pk_fma_f32 v[6:7], v[28:29], v[6:7], v[16:17]
	v_pk_fma_f32 v[10:11], v[26:27], v[10:11], v[14:15]
	v_pk_fma_f32 v[8:9], v[28:29], v[8:9], v[20:21]
	v_pk_fma_f32 v[12:13], v[26:27], v[12:13], v[18:19]
	s_waitcnt vmcnt(6)
	v_lshlrev_b32_e32 v14, 16, v56
	v_and_b32_e32 v15, 0xffff0000, v56
	v_lshlrev_b32_e32 v16, 16, v57
	v_and_b32_e32 v17, 0xffff0000, v57
	v_lshlrev_b32_e32 v18, 16, v58
	v_and_b32_e32 v19, 0xffff0000, v58
	v_lshlrev_b32_e32 v20, 16, v59
	v_and_b32_e32 v21, 0xffff0000, v59
	global_store_dwordx4 v[22:23], v[2:5], off
	v_lshl_add_u64 v[22:23], v[32:33], 0, v[64:65]
	s_nop 0
	v_cvt_pk_bf16_f32 v2, v10, v11
	v_cvt_pk_bf16_f32 v3, v6, v7
	v_cvt_pk_bf16_f32 v4, v12, v13
	v_cvt_pk_bf16_f32 v5, v8, v9
	v_pk_fma_f32 v[6:7], v[28:29], v[6:7], v[16:17]
	v_pk_fma_f32 v[10:11], v[26:27], v[10:11], v[14:15]
	v_pk_fma_f32 v[8:9], v[28:29], v[8:9], v[20:21]
	v_pk_fma_f32 v[12:13], v[26:27], v[12:13], v[18:19]
	s_waitcnt vmcnt(6)
	v_lshlrev_b32_e32 v14, 16, v60
	v_and_b32_e32 v15, 0xffff0000, v60
	v_lshlrev_b32_e32 v16, 16, v61
	v_and_b32_e32 v17, 0xffff0000, v61
	v_lshlrev_b32_e32 v18, 16, v62
	v_and_b32_e32 v19, 0xffff0000, v62
	v_lshlrev_b32_e32 v20, 16, v63
	v_and_b32_e32 v21, 0xffff0000, v63
	global_store_dwordx4 v[22:23], v[2:5], off
	v_lshl_add_u64 v[22:23], v[32:33], 0, v[66:67]
	v_pk_fma_f32 v[40:41], v[28:29], v[6:7], v[16:17]
	v_cvt_pk_bf16_f32 v2, v10, v11
	v_cvt_pk_bf16_f32 v3, v6, v7
	v_cvt_pk_bf16_f32 v4, v12, v13
	v_cvt_pk_bf16_f32 v5, v8, v9
	v_pk_fma_f32 v[38:39], v[26:27], v[10:11], v[14:15]
	v_pk_fma_f32 v[36:37], v[28:29], v[8:9], v[20:21]
	v_pk_fma_f32 v[34:35], v[26:27], v[12:13], v[18:19]
	global_store_dwordx4 v[22:23], v[2:5], off
	s_cbranch_scc0 .LBB0_368
	v_add_u32_e32 v91, s10, v91
	v_cmp_le_i32_e32 vcc, s11, v91
	s_or_b64 s[8:9], vcc, s[8:9]
	s_andn2_b64 exec, exec, s[8:9]
	s_cbranch_execnz .LBB0_367

.LBB0_442:
	s_cmpk_gt_i32 s8, 0x7ff
	s_cbranch_scc1 .LBB0_459
	s_lshl_b32 s10, s8, 23
	s_and_b32 s10, s10, 0x1800000
	s_add_u32 s14, s86, s10
	s_addc_u32 s15, s87, 0
	s_add_u32 s10, s14, 0x8000000
	v_add_u32_e32 v74, 0x200, v70
	s_addc_u32 s11, s15, 0
	s_ashr_i32 s12, s8, 2
	v_ashrrev_i32_e32 v71, 31, v70
	v_ashrrev_i32_e32 v75, 31, v74
	s_ashr_i32 s13, s12, 31
	v_lshlrev_b64 v[66:67], 3, v[70:71]
	v_lshlrev_b64 v[68:69], 3, v[74:75]
	s_lshl_b64 s[12:13], s[12:13], 13
	s_waitcnt vmcnt(0)
	v_lshl_add_u64 v[2:3], s[12:13], 0, v[66:67]
	v_lshl_add_u64 v[4:5], s[12:13], 0, v[68:69]
	v_lshlrev_b64 v[22:23], 1, v[2:3]
	v_lshlrev_b64 v[24:25], 1, v[4:5]
	v_lshl_add_u64 v[2:3], s[10:11], 0, v[22:23]
	v_lshl_add_u64 v[6:7], s[10:11], 0, v[24:25]
	s_add_u32 s10, s14, 0xa000000
	s_addc_u32 s11, s15, 0
	global_load_dwordx4 v[2:5], v[2:3], off nt
	s_nop 0
	global_load_dwordx4 v[10:13], v[6:7], off nt
	v_lshl_add_u64 v[6:7], s[10:11], 0, v[22:23]
	v_lshl_add_u64 v[14:15], s[10:11], 0, v[24:25]
	s_add_u32 s10, s14, 0xc000000
	s_addc_u32 s11, s15, 0
	v_lshl_add_u64 v[18:19], s[10:11], 0, v[22:23]
	v_lshl_add_u64 v[26:27], s[10:11], 0, v[24:25]
	s_add_u32 s10, s14, 0xe000000
	s_addc_u32 s11, s15, 0
	v_lshl_add_u64 v[22:23], s[10:11], 0, v[22:23]
	v_lshl_add_u64 v[30:31], s[10:11], 0, v[24:25]
	v_lshlrev_b32_e32 v104, 3, v70
	v_ashrrev_i32_e32 v34, 4, v70
	s_movk_i32 s10, 0x88
	v_and_b32_e32 v0, 0x78, v104
	v_mul_lo_u32 v34, v34, s10
	v_add_lshl_u32 v34, v34, v0, 1
	v_readlane_b32 s14, v255, 16
	v_add_u32_e32 v109, 0, v34
	v_readlane_b32 s16, v255, 18
	v_add_u32_e32 v110, s14, v34
	v_ashrrev_i32_e32 v34, 4, v74
	v_mul_lo_u32 v34, v34, s10
	v_readlane_b32 s15, v255, 17
	s_movk_i32 s10, 0x100
	v_and_b32_e32 v102, 63, v70
	v_add_lshl_u32 v0, v34, v0, 1
	v_mov_b32_e32 v34, s16
	v_mov_b32_e32 v35, s15
	v_cmp_gt_u32_e64 s[40:41], s10, v70
	v_add_u32_e32 v111, 0, v0
	v_add_u32_e32 v112, s14, v0
	v_cndmask_b32_e64 v34, v34, v35, s[40:41]
	v_lshlrev_b32_e32 v35, 2, v102
	v_bfe_u32 v0, v70, 4, 2
	v_add_u32_e32 v113, v34, v35
	v_ashrrev_i32_e32 v34, 6, v70
	s_bfe_u32 s24, s3, 0x20006
	s_add_i32 s12, 0, 0x4400
	v_and_b32_e32 v133, -4, v34
	v_lshl_or_b32 v39, v34, 9, v180
	v_mov_b32_e32 v34, s12
	s_lshl_b32 s13, s24, 4
	v_lshlrev_b32_e32 v101, 2, v0
	v_and_b32_e32 v99, 15, v70
	v_cndmask_b32_e64 v135, v34, 0, s[40:41]
	v_or_b32_e32 v34, s13, v101
	s_lshl_b32 s25, s9, 4
	v_cmp_le_u32_e32 vcc, v34, v99
	s_cmp_lt_u32 s9, 4
	global_load_dwordx4 v[6:9], v[6:7], off nt
	s_nop 0
	global_load_dwordx4 v[14:17], v[14:15], off nt
	v_cndmask_b32_e64 v36, 0, 1, vcc
	v_cmp_ge_u32_e32 vcc, v34, v99
	global_load_dwordx4 v[18:21], v[18:19], off nt
	s_nop 0
	global_load_dwordx4 v[26:29], v[26:27], off nt
	v_cndmask_b32_e64 v37, 0, 1, vcc
	s_cselect_b64 vcc, -1, 0
	v_cndmask_b32_e32 v36, v37, v36, vcc
	global_load_dwordx4 v[22:25], v[22:23], off nt
	s_nop 0
	global_load_dwordx4 v[30:33], v[30:31], off nt
	v_and_b32_e32 v36, 1, v36
	v_cmp_eq_u32_e64 s[42:43], 1, v36
	v_or_b32_e32 v36, 1, v34
	v_cmp_lt_u32_e64 s[44:45], v34, v99
	v_or_b32_e32 v107, 16, v99
	v_cmp_le_u32_e64 s[50:51], v34, v107
	v_cndmask_b32_e64 v40, 0, 1, s[44:45]
	v_cmp_ge_u32_e64 s[44:45], v36, v99
	v_cmp_lt_u32_e64 s[52:53], v34, v107
	v_or_b32_e32 v105, 32, v99
	v_cndmask_b32_e64 v41, 0, 1, s[44:45]
	v_cndmask_b32_e32 v40, v41, v40, vcc
	v_and_b32_e32 v40, 1, v40
	v_cmp_eq_u32_e64 s[44:45], 1, v40
	v_or_b32_e32 v40, 2, v34
	v_cmp_le_u32_e64 s[46:47], v40, v99
	v_cmp_le_u32_e64 s[54:55], v40, v107
	v_cmp_le_u32_e64 s[58:59], v34, v105
	v_cndmask_b32_e64 v41, 0, 1, s[46:47]
	v_cmp_ge_u32_e64 s[46:47], v40, v99
	v_cmp_lt_u32_e64 s[60:61], v34, v105
	v_cmp_le_u32_e64 s[62:63], v40, v105
	v_cndmask_b32_e64 v42, 0, 1, s[46:47]
	v_cndmask_b32_e32 v41, v42, v41, vcc
	v_and_b32_e32 v41, 1, v41
	v_cmp_eq_u32_e64 s[46:47], 1, v41
	v_or_b32_e32 v41, 3, v34
	v_cmp_le_u32_e64 s[48:49], v41, v99
	v_cmp_le_u32_e64 s[56:57], v41, v107
	v_cmp_le_u32_e64 s[64:65], v41, v105
	v_cndmask_b32_e64 v42, 0, 1, s[48:49]
	v_cmp_ge_u32_e64 s[48:49], v41, v99
	v_or_b32_e32 v103, 48, v102
	v_cmp_le_u32_e64 s[66:67], v34, v103
	v_cndmask_b32_e64 v43, 0, 1, s[48:49]
	v_cndmask_b32_e32 v42, v43, v42, vcc
	v_and_b32_e32 v42, 1, v42
	v_cmp_eq_u32_e64 s[48:49], 1, v42
	v_cndmask_b32_e64 v42, 0, 1, s[50:51]
	v_cmp_ge_u32_e64 s[50:51], v34, v107
	v_cmp_lt_u32_e64 s[68:69], v34, v103
	v_cmp_le_u32_e64 s[70:71], v40, v103
	v_cndmask_b32_e64 v43, 0, 1, s[50:51]
	v_cndmask_b32_e32 v42, v43, v42, vcc
	v_and_b32_e32 v42, 1, v42
	v_cmp_eq_u32_e64 s[50:51], 1, v42
	v_cndmask_b32_e64 v42, 0, 1, s[52:53]
	v_cmp_ge_u32_e64 s[52:53], v36, v107
	v_cmp_le_u32_e64 s[72:73], v41, v103
	v_readlane_b32 s10, v255, 19
	v_cndmask_b32_e64 v43, 0, 1, s[52:53]
	v_cndmask_b32_e32 v42, v43, v42, vcc
	v_and_b32_e32 v42, 1, v42
	v_cmp_eq_u32_e64 s[52:53], 1, v42
	v_cndmask_b32_e64 v42, 0, 1, s[54:55]
	v_cmp_ge_u32_e64 s[54:55], v40, v107
	v_lshl_add_u32 v134, v102, 3, s10
	s_and_b64 s[10:11], vcc, exec
	v_cndmask_b32_e64 v43, 0, 1, s[54:55]
	v_cndmask_b32_e32 v42, v43, v42, vcc
	v_and_b32_e32 v42, 1, v42
	v_cmp_eq_u32_e64 s[54:55], 1, v42
	v_cndmask_b32_e64 v42, 0, 1, s[56:57]
	v_cmp_ge_u32_e64 s[56:57], v41, v107
	v_or_b32_e32 v37, s13, v99
	s_cselect_b32 s11, s15, s16
	v_cndmask_b32_e64 v43, 0, 1, s[56:57]
	v_cndmask_b32_e32 v42, v43, v42, vcc
	v_and_b32_e32 v42, 1, v42
	v_cmp_eq_u32_e64 s[56:57], 1, v42
	v_cndmask_b32_e64 v42, 0, 1, s[58:59]
	v_cmp_ge_u32_e64 s[58:59], v34, v105
	v_mul_u32_u24_e32 v37, 0x110, v37
	v_and_b32_e32 v72, 48, v70
	v_cndmask_b32_e64 v43, 0, 1, s[58:59]
	v_cndmask_b32_e32 v42, v43, v42, vcc
	v_and_b32_e32 v42, 1, v42
	v_cmp_eq_u32_e64 s[58:59], 1, v42
	v_cndmask_b32_e64 v42, 0, 1, s[60:61]
	v_cmp_ge_u32_e64 s[60:61], v36, v105
	v_lshlrev_b32_e32 v100, 3, v0
	s_cselect_b32 s10, 0, s12
	v_cndmask_b32_e64 v43, 0, 1, s[60:61]
	v_cndmask_b32_e32 v42, v43, v42, vcc
	v_and_b32_e32 v42, 1, v42
	v_cmp_eq_u32_e64 s[60:61], 1, v42
	v_cndmask_b32_e64 v42, 0, 1, s[62:63]
	v_cmp_ge_u32_e64 s[62:63], v40, v105
	v_add3_u32 v136, s11, v37, v72
	v_readlane_b32 s11, v255, 20
	v_cndmask_b32_e64 v43, 0, 1, s[62:63]
	v_cndmask_b32_e32 v42, v43, v42, vcc
	v_and_b32_e32 v42, 1, v42
	v_cmp_eq_u32_e64 s[62:63], 1, v42
	v_cndmask_b32_e64 v42, 0, 1, s[64:65]
	v_cmp_ge_u32_e64 s[64:65], v41, v105
	v_readlane_b32 s12, v255, 21
	v_add_u32_e32 v137, s10, v72
	v_cndmask_b32_e64 v43, 0, 1, s[64:65]
	v_cndmask_b32_e32 v42, v43, v42, vcc
	v_and_b32_e32 v42, 1, v42
	v_cmp_eq_u32_e64 s[64:65], 1, v42
	v_cndmask_b32_e64 v42, 0, 1, s[66:67]
	v_cmp_ge_u32_e64 s[66:67], v34, v103
	v_cndmask_b32_e64 v34, 0, 1, s[68:69]
	v_cmp_ge_u32_e64 s[68:69], v36, v103
	v_cndmask_b32_e64 v43, 0, 1, s[66:67]
	v_cndmask_b32_e32 v42, v43, v42, vcc
	v_cndmask_b32_e64 v36, 0, 1, s[68:69]
	v_cndmask_b32_e32 v34, v36, v34, vcc
	v_and_b32_e32 v34, 1, v34
	v_cmp_eq_u32_e64 s[68:69], 1, v34
	v_cndmask_b32_e64 v34, 0, 1, s[70:71]
	v_cmp_ge_u32_e64 s[70:71], v40, v103
	v_or_b32_e32 v37, 32, v100
	s_cselect_b32 s10, s11, s12
	v_cndmask_b32_e64 v36, 0, 1, s[70:71]
	v_cndmask_b32_e32 v34, v36, v34, vcc
	v_and_b32_e32 v34, 1, v34
	v_cmp_eq_u32_e64 s[70:71], 1, v34
	v_cndmask_b32_e64 v34, 0, 1, s[72:73]
	v_cmp_ge_u32_e64 s[72:73], v41, v103
	v_and_b32_e32 v42, 1, v42
	s_andn2_b32 s3, s3, 63
	v_cndmask_b32_e64 v36, 0, 1, s[72:73]
	v_cndmask_b32_e32 v34, v36, v34, vcc
	v_and_b32_e32 v34, 1, v34
	v_cmp_eq_u32_e64 s[72:73], 1, v34
	v_mul_u32_u24_e32 v34, 0x48, v99
	v_lshlrev_b32_e32 v34, 1, v34
	v_cmp_eq_u32_e64 s[66:67], 1, v42
	v_add_u32_e32 v36, s11, v72
	v_add_u32_e32 v41, s12, v72
	v_add_u32_e32 v42, 0x900, v34
	v_mul_u32_u24_e32 v44, 0x48, v103
	v_lshlrev_b32_e32 v125, 1, v37
	v_lshlrev_b32_e32 v117, 4, v70
	s_add_i32 s3, s3, 0
	v_bfe_u32 v108, v70, 2, 2
	v_add_u32_e32 v139, v36, v34
	v_add_u32_e32 v140, v41, v34
	v_add_u32_e32 v141, v36, v42
	v_add_u32_e32 v142, v41, v42
	v_add_u32_e32 v43, 0x1200, v34
	v_lshlrev_b32_e32 v44, 1, v44
	v_add3_u32 v153, s11, v34, v125
	v_add3_u32 v154, s12, v34, v125
	v_add3_u32 v155, s11, v42, v125
	v_add3_u32 v156, s12, v42, v125
	v_ashrrev_i32_e32 v76, 3, v70
	v_and_b32_e32 v34, 0x70, v117
	v_lshl_add_u32 v42, v99, 2, s3
	s_movk_i32 s3, 0x210
	v_add_u32_e32 v143, v36, v43
	v_add_u32_e32 v144, v41, v43
	v_add_u32_e32 v145, v36, v44
	v_or_b32_e32 v132, v37, v108
	v_add3_u32 v157, s11, v43, v125
	v_add3_u32 v158, s12, v43, v125
	v_mul_u32_u24_e32 v43, 0x840, v0
	v_mul_lo_u32 v36, v76, s3
	v_lshlrev_b32_e32 v0, 2, v34
	v_and_b32_e32 v37, 64, v215
	v_add3_u32 v162, 0, v36, v0
	v_xor_b32_e32 v36, 1, v215
	v_add_u32_e32 v37, 64, v37
	v_cmp_lt_i32_e32 vcc, v36, v37
	s_lshl_b32 s27, s9, 5
	s_lshl_b32 s26, s24, 5
	v_cndmask_b32_e32 v36, v215, v36, vcc
	v_lshlrev_b32_e32 v97, 2, v36
	v_xor_b32_e32 v36, 2, v215
	v_cmp_lt_i32_e32 vcc, v36, v37
	s_add_i32 s9, s14, s27
	v_and_b32_e32 v116, 12, v35
	v_cndmask_b32_e32 v36, v215, v36, vcc
	v_lshlrev_b32_e32 v98, 2, v36
	v_xor_b32_e32 v36, 4, v215
	v_cmp_lt_i32_e32 vcc, v36, v37
	v_or_b32_e32 v78, s25, v99
	s_add_i32 s10, s10, s26
	v_lshl_add_u32 v35, v116, 1, s9
	v_cndmask_b32_e32 v36, v215, v36, vcc
	s_ashr_i32 s9, s8, 31
	v_ashrrev_i32_e32 v79, 31, v78
	v_add_u32_e32 v138, s10, v100
	v_add3_u32 v159, s11, v44, v125
	v_lshlrev_b32_e32 v163, 2, v36
	s_lshl_b64 s[10:11], s[8:9], 16
	v_lshlrev_b64 v[36:37], 8, v[78:79]
	v_or_b32_e32 v114, v100, v108
	v_add3_u32 v160, s12, v44, v125
	v_readlane_b32 s12, v255, 27
	v_lshl_add_u64 v[36:37], s[10:11], 0, v[36:37]
	v_readlane_b32 s10, v255, 10
	v_lshlrev_b32_e32 v38, 9, v133
	v_mul_u32_u24_e32 v40, 0x110, v114
	v_add_u32_e32 v152, v41, v44
	v_mul_u32_u24_e32 v41, 0x110, v132
	v_readlane_b32 s14, v255, 29
	v_readlane_b32 s15, v255, 30
	v_or_b32_e32 v36, v36, v72
	v_readlane_b32 s11, v255, 11
	s_ashr_i32 s3, s2, 31
	v_cndmask_b32_e64 v115, 14, 1, s[40:41]
	v_cndmask_b32_e64 v118, 13, 2, s[40:41]
	v_cndmask_b32_e64 v119, 12, 3, s[40:41]
	v_cndmask_b32_e64 v120, 11, 4, s[40:41]
	v_cndmask_b32_e64 v121, 10, 5, s[40:41]
	v_cndmask_b32_e64 v122, 9, 6, s[40:41]
	v_cndmask_b32_e64 v123, 8, 7, s[40:41]
	v_cndmask_b32_e64 v124, 7, 8, s[40:41]
	v_cndmask_b32_e64 v126, 6, 9, s[40:41]
	v_cndmask_b32_e64 v127, 5, 10, s[40:41]
	v_cndmask_b32_e64 v128, 4, 11, s[40:41]
	v_cndmask_b32_e64 v129, 3, 12, s[40:41]
	v_cndmask_b32_e64 v130, 2, 13, s[40:41]
	v_cndmask_b32_e64 v131, 1, 14, s[40:41]
	v_mul_u32_u24_e32 v71, 0x110, v99
	v_mul_u32_u24_e32 v73, 0x110, v103
	v_mul_u32_u24_e32 v75, 0x90, v99
	v_mul_u32_u24_e32 v96, 0x90, v103
	v_add_u32_e32 v106, 0, v72
	v_ashrrev_i32_e32 v77, 31, v76
	v_lshl_add_u64 v[80:81], s[14:15], 0, v[0:1]
	v_lshl_add_u64 v[82:83], s[10:11], 0, v[36:37]
	s_lshl_b64 s[10:11], s[2:3], 16
	v_add_u32_e32 v79, v134, v39
	v_add_u32_e32 v164, v35, v40
	v_add_u32_e32 v165, v35, v41
	v_lshlrev_b32_e32 v0, 1, v34
	v_add_u32_e32 v166, v42, v43
	v_add_u32_e32 v167, v134, v38
	s_mov_b32 s29, s8
	v_readlane_b32 s13, v255, 28
	v_lshlrev_b32_e32 v236, 4, v214
	v_add_u32_e32 v237, 0x2000000, v236
	v_add_u32_e32 v238, 0x4000000, v236
	v_add_u32_e32 v239, 0x6000000, v236
	v_add_u32_e32 v240, 0x2000, v236
	v_add_u32_e32 v241, 0x2002000, v236
	v_add_u32_e32 v242, 0x4002000, v236
	v_add_u32_e32 v243, 0x6002000, v236
	s_waitcnt vmcnt(0)
	s_branch .LBB0_445
.LBB0_444:
	s_or_b64 exec, exec, s[14:15]
	v_mul_u32_u24_e32 v147, 0x44, v173
	v_lshl_add_u32 v147, v147, 2, v113
	ds_read_b32 v175, v147
	v_mad_u32_u24 v173, v173, s20, v102
	v_lshl_add_u32 v173, v173, 2, v135
	ds_read_b32 v177, v173
	s_ashr_i32 s14, s29, 2
	s_waitcnt lgkmcnt(1)
	v_lshlrev_b32_e32 v174, 16, v175
	v_and_b32_e32 v175, 0xffff0000, v175
	v_pk_add_f32 v[198:199], v[174:175], 1.0 op_sel_hi:[1,0] neg_lo:[1,0] neg_hi:[1,0]
	s_waitcnt lgkmcnt(0)
	v_lshlrev_b32_e32 v176, 16, v177
	v_pk_mul_f32 v[84:85], v[84:85], v[198:199]
	v_and_b32_e32 v177, 0xffff0000, v177
	v_max_f32_e32 v197, 0xda24260, v84
	v_rcp_f32_e32 v198, v197
	v_max_f32_e32 v197, 0xda24260, v85
	v_rcp_f32_e32 v199, v197
	s_ashr_i32 s15, s14, 31
	s_lshl_b64 vcc, s[14:15], 6
	s_and_b32 s14, s29, 3
	v_pk_mul_f32 v[174:175], v[198:199], v[174:175]
	s_lshl_b32 s15, s14, 23
	v_cvt_pk_bf16_f32 v174, v174, v175
	ds_write_b32 v147, v174
	v_pk_mul_f32 v[174:175], v[84:85], v[176:177]
	s_add_u32 s16, s86, s15
	v_cvt_pk_bf16_f32 v147, v174, v175
	ds_write_b32 v173, v147
	global_load_dwordx4 v[50:53], v[34:35], off nt
	v_mul_u32_u24_e32 v147, 0x44, v172
	v_lshl_add_u32 v147, v147, 2, v113
	ds_read_b32 v173, v147
	v_mad_u32_u24 v174, v172, s20, v102
	v_lshl_add_u32 v197, v174, 2, v135
	ds_read_b32 v175, v197
	s_addc_u32 s17, s87, 0
	s_waitcnt lgkmcnt(1)
	v_lshlrev_b32_e32 v172, 16, v173
	v_and_b32_e32 v173, 0xffff0000, v173
	v_pk_add_f32 v[176:177], v[172:173], 1.0 op_sel_hi:[1,0] neg_lo:[1,0] neg_hi:[1,0]
	s_waitcnt lgkmcnt(0)
	v_lshlrev_b32_e32 v174, 16, v175
	v_pk_mul_f32 v[84:85], v[84:85], v[176:177]
	v_and_b32_e32 v175, 0xffff0000, v175
	v_max_f32_e32 v176, 0xda24260, v84
	v_max_f32_e32 v177, 0xda24260, v85
	v_rcp_f32_e32 v176, v176
	v_rcp_f32_e32 v177, v177
	s_brev_b32 s15, 8
	s_lshl_b32 s80, s14, 9
	v_pk_mul_f32 v[172:173], v[176:177], v[172:173]
	s_mov_b32 s29, s28
	v_cvt_pk_bf16_f32 v172, v172, v173
	ds_write_b32 v147, v172
	v_pk_mul_f32 v[172:173], v[84:85], v[174:175]
	s_nop 0
	v_cvt_pk_bf16_f32 v147, v172, v173
	ds_write_b32 v197, v147
	global_load_dwordx4 v[46:49], v[82:83], off offset:-192 nt
	v_mul_u32_u24_e32 v147, 0x44, v171
	v_lshl_add_u32 v147, v147, 2, v113
	ds_read_b32 v173, v147
	v_mad_u32_u24 v171, v171, s20, v102
	v_lshl_add_u32 v171, v171, 2, v135
	ds_read_b32 v175, v171
	s_waitcnt lgkmcnt(1)
	v_lshlrev_b32_e32 v172, 16, v173
	v_and_b32_e32 v173, 0xffff0000, v173
	v_pk_add_f32 v[176:177], v[172:173], 1.0 op_sel_hi:[1,0] neg_lo:[1,0] neg_hi:[1,0]
	s_waitcnt lgkmcnt(0)
	v_lshlrev_b32_e32 v174, 16, v175
	v_pk_mul_f32 v[84:85], v[84:85], v[176:177]
	v_and_b32_e32 v175, 0xffff0000, v175
	v_max_f32_e32 v176, 0xda24260, v84
	v_max_f32_e32 v177, 0xda24260, v85
	v_rcp_f32_e32 v176, v176
	v_rcp_f32_e32 v177, v177
	s_nop 0
	v_pk_mul_f32 v[172:173], v[176:177], v[172:173]
	s_nop 0
	v_cvt_pk_bf16_f32 v172, v172, v173
	ds_write_b32 v147, v172
	v_pk_mul_f32 v[172:173], v[84:85], v[174:175]
	s_nop 0
	v_cvt_pk_bf16_f32 v147, v172, v173
	ds_write_b32 v171, v147
	global_load_dwordx4 v[42:45], v[82:83], off offset:-128 nt
	v_mul_u32_u24_e32 v147, 0x44, v170
	v_lshl_add_u32 v147, v147, 2, v113
	ds_read_b32 v171, v147
	v_mad_u32_u24 v172, v170, s20, v102
	v_lshl_add_u32 v176, v172, 2, v135
	ds_read_b32 v173, v176
	s_waitcnt lgkmcnt(1)
	v_lshlrev_b32_e32 v170, 16, v171
	v_and_b32_e32 v171, 0xffff0000, v171
	v_pk_add_f32 v[174:175], v[170:171], 1.0 op_sel_hi:[1,0] neg_lo:[1,0] neg_hi:[1,0]
	s_waitcnt lgkmcnt(0)
	v_lshlrev_b32_e32 v172, 16, v173
	v_pk_mul_f32 v[84:85], v[84:85], v[174:175]
	v_and_b32_e32 v173, 0xffff0000, v173
	v_max_f32_e32 v174, 0xda24260, v84
	v_max_f32_e32 v175, 0xda24260, v85
	v_rcp_f32_e32 v174, v174
	v_rcp_f32_e32 v175, v175
	s_nop 0
	v_pk_mul_f32 v[170:171], v[174:175], v[170:171]
	s_nop 0
	v_cvt_pk_bf16_f32 v170, v170, v171
	ds_write_b32 v147, v170
	v_pk_mul_f32 v[170:171], v[84:85], v[172:173]
	s_nop 0
	v_cvt_pk_bf16_f32 v147, v170, v171
	ds_write_b32 v176, v147
	global_load_dwordx4 v[38:41], v[82:83], off offset:-64 nt
	v_mul_u32_u24_e32 v147, 0x44, v169
	v_lshl_add_u32 v147, v147, 2, v113
	ds_read_b32 v171, v147
	v_mad_u32_u24 v169, v169, s20, v102
	v_lshl_add_u32 v169, v169, 2, v135
	ds_read_b32 v173, v169
	v_add_u32_e32 v176, v137, v73
	s_waitcnt lgkmcnt(1)
	v_lshlrev_b32_e32 v170, 16, v171
	v_and_b32_e32 v171, 0xffff0000, v171
	v_pk_add_f32 v[174:175], v[170:171], 1.0 op_sel_hi:[1,0] neg_lo:[1,0] neg_hi:[1,0]
	s_waitcnt lgkmcnt(0)
	v_lshlrev_b32_e32 v172, 16, v173
	v_pk_mul_f32 v[84:85], v[84:85], v[174:175]
	v_and_b32_e32 v173, 0xffff0000, v173
	v_max_f32_e32 v174, 0xda24260, v84
	v_max_f32_e32 v175, 0xda24260, v85
	v_rcp_f32_e32 v174, v174
	v_rcp_f32_e32 v175, v175
	s_nop 0
	v_pk_mul_f32 v[170:171], v[174:175], v[170:171]
	s_nop 0
	v_cvt_pk_bf16_f32 v170, v170, v171
	ds_write_b32 v147, v170
	v_pk_mul_f32 v[170:171], v[84:85], v[172:173]
	s_nop 0
	v_cvt_pk_bf16_f32 v147, v170, v171
	ds_write_b32 v169, v147
	global_load_dwordx4 v[34:37], v[82:83], off nt
	v_lshl_add_u64 v[82:83], v[82:83], 0, s[10:11]
	v_mul_u32_u24_e32 v147, 0x44, v168
	v_lshl_add_u32 v147, v147, 2, v113
	ds_read_b32 v169, v147
	v_mad_u32_u24 v170, v168, s20, v102
	v_lshl_add_u32 v174, v170, 2, v135
	ds_read_b32 v171, v174
	s_waitcnt lgkmcnt(1)
	v_lshlrev_b32_e32 v168, 16, v169
	v_and_b32_e32 v169, 0xffff0000, v169
	v_pk_add_f32 v[172:173], v[168:169], 1.0 op_sel_hi:[1,0] neg_lo:[1,0] neg_hi:[1,0]
	s_waitcnt lgkmcnt(0)
	v_lshlrev_b32_e32 v170, 16, v171
	v_pk_mul_f32 v[84:85], v[84:85], v[172:173]
	v_and_b32_e32 v171, 0xffff0000, v171
	v_max_f32_e32 v172, 0xda24260, v84
	v_max_f32_e32 v173, 0xda24260, v85
	v_rcp_f32_e32 v172, v172
	v_rcp_f32_e32 v173, v173
	s_nop 0
	v_pk_mul_f32 v[168:169], v[172:173], v[168:169]
	s_nop 0
	v_cvt_pk_bf16_f32 v168, v168, v169
	ds_write_b32 v147, v168
	v_pk_mul_f32 v[168:169], v[84:85], v[170:171]
	s_nop 0
	v_cvt_pk_bf16_f32 v147, v168, v169
	ds_write_b32 v174, v147
	global_load_dwordx4 v[2:5], v236, s[100:101] nt
	v_mul_u32_u24_e32 v147, 0x44, v95
	v_lshl_add_u32 v147, v147, 2, v113
	ds_read_b32 v169, v147
	v_mad_u32_u24 v95, v95, s20, v102
	v_lshl_add_u32 v95, v95, 2, v135
	ds_read_b32 v171, v95
	s_waitcnt lgkmcnt(1)
	v_lshlrev_b32_e32 v168, 16, v169
	v_and_b32_e32 v169, 0xffff0000, v169
	v_pk_add_f32 v[172:173], v[168:169], 1.0 op_sel_hi:[1,0] neg_lo:[1,0] neg_hi:[1,0]
	s_waitcnt lgkmcnt(0)
	v_lshlrev_b32_e32 v170, 16, v171
	v_pk_mul_f32 v[84:85], v[84:85], v[172:173]
	v_and_b32_e32 v171, 0xffff0000, v171
	v_max_f32_e32 v172, 0xda24260, v84
	v_max_f32_e32 v173, 0xda24260, v85
	v_rcp_f32_e32 v172, v172
	v_rcp_f32_e32 v173, v173
	s_nop 0
	v_pk_mul_f32 v[168:169], v[172:173], v[168:169]
	s_nop 0
	v_cvt_pk_bf16_f32 v168, v168, v169
	ds_write_b32 v147, v168
	v_pk_mul_f32 v[168:169], v[84:85], v[170:171]
	s_nop 0
	v_cvt_pk_bf16_f32 v147, v168, v169
	ds_write_b32 v95, v147
	v_mul_u32_u24_e32 v95, 0x44, v94
	v_lshl_add_u32 v172, v95, 2, v113
	ds_read_b32 v95, v172
	v_mad_u32_u24 v147, v94, s20, v102
	v_lshl_add_u32 v147, v147, 2, v135
	ds_read_b32 v169, v147
	s_waitcnt lgkmcnt(1)
	v_lshlrev_b32_e32 v94, 16, v95
	v_and_b32_e32 v95, 0xffff0000, v95
	v_pk_add_f32 v[170:171], v[94:95], 1.0 op_sel_hi:[1,0] neg_lo:[1,0] neg_hi:[1,0]
	s_waitcnt lgkmcnt(0)
	v_lshlrev_b32_e32 v168, 16, v169
	v_pk_mul_f32 v[84:85], v[84:85], v[170:171]
	v_and_b32_e32 v169, 0xffff0000, v169
	v_max_f32_e32 v170, 0xda24260, v84
	v_max_f32_e32 v171, 0xda24260, v85
	v_rcp_f32_e32 v170, v170
	v_rcp_f32_e32 v171, v171
	s_nop 0
	v_pk_mul_f32 v[94:95], v[170:171], v[94:95]
	s_nop 0
	v_cvt_pk_bf16_f32 v94, v94, v95
	ds_write_b32 v172, v94
	v_pk_mul_f32 v[94:95], v[84:85], v[168:169]
	s_nop 0
	v_cvt_pk_bf16_f32 v94, v94, v95
	ds_write_b32 v147, v94
	global_load_dwordx4 v[6:9], v237, s[100:101] nt
	v_mul_u32_u24_e32 v94, 0x44, v93
	v_lshl_add_u32 v147, v94, 2, v113
	ds_read_b32 v95, v147
	v_mad_u32_u24 v93, v93, s20, v102
	v_lshl_add_u32 v93, v93, 2, v135
	ds_read_b32 v169, v93
	s_waitcnt lgkmcnt(1)
	v_lshlrev_b32_e32 v94, 16, v95
	v_and_b32_e32 v95, 0xffff0000, v95
	v_pk_add_f32 v[170:171], v[94:95], 1.0 op_sel_hi:[1,0] neg_lo:[1,0] neg_hi:[1,0]
	s_waitcnt lgkmcnt(0)
	v_lshlrev_b32_e32 v168, 16, v169
	v_pk_mul_f32 v[84:85], v[84:85], v[170:171]
	v_and_b32_e32 v169, 0xffff0000, v169
	v_max_f32_e32 v170, 0xda24260, v84
	v_max_f32_e32 v171, 0xda24260, v85
	v_rcp_f32_e32 v170, v170
	v_rcp_f32_e32 v171, v171
	s_nop 0
	v_pk_mul_f32 v[94:95], v[170:171], v[94:95]
	s_nop 0
	v_cvt_pk_bf16_f32 v94, v94, v95
	ds_write_b32 v147, v94
	v_pk_mul_f32 v[94:95], v[84:85], v[168:169]
	s_nop 0
	v_cvt_pk_bf16_f32 v94, v94, v95
	ds_write_b32 v93, v94
	v_mul_u32_u24_e32 v93, 0x44, v92
	v_lshl_add_u32 v147, v93, 2, v113
	ds_read_b32 v93, v147
	v_mad_u32_u24 v94, v92, s20, v102
	v_lshl_add_u32 v170, v94, 2, v135
	ds_read_b32 v95, v170
	s_waitcnt lgkmcnt(1)
	v_lshlrev_b32_e32 v92, 16, v93
	v_and_b32_e32 v93, 0xffff0000, v93
	v_pk_add_f32 v[168:169], v[92:93], 1.0 op_sel_hi:[1,0] neg_lo:[1,0] neg_hi:[1,0]
	s_waitcnt lgkmcnt(0)
	v_lshlrev_b32_e32 v94, 16, v95
	v_pk_mul_f32 v[84:85], v[84:85], v[168:169]
	v_and_b32_e32 v95, 0xffff0000, v95
	v_max_f32_e32 v168, 0xda24260, v84
	v_max_f32_e32 v169, 0xda24260, v85
	v_rcp_f32_e32 v168, v168
	v_rcp_f32_e32 v169, v169
	s_nop 0
	v_pk_mul_f32 v[92:93], v[168:169], v[92:93]
	s_nop 0
	v_cvt_pk_bf16_f32 v92, v92, v93
	ds_write_b32 v147, v92
	v_pk_mul_f32 v[92:93], v[84:85], v[94:95]
	s_nop 0
	v_cvt_pk_bf16_f32 v92, v92, v93
	ds_write_b32 v170, v92
	global_load_dwordx4 v[18:21], v238, s[100:101] nt
	v_mul_u32_u24_e32 v92, 0x44, v91
	v_lshl_add_u32 v147, v92, 2, v113
	ds_read_b32 v93, v147
	v_mad_u32_u24 v91, v91, s20, v102
	v_lshl_add_u32 v91, v91, 2, v135
	ds_read_b32 v95, v91
	s_waitcnt lgkmcnt(1)
	v_lshlrev_b32_e32 v92, 16, v93
	v_and_b32_e32 v93, 0xffff0000, v93
	v_pk_add_f32 v[168:169], v[92:93], 1.0 op_sel_hi:[1,0] neg_lo:[1,0] neg_hi:[1,0]
	s_waitcnt lgkmcnt(0)
	v_lshlrev_b32_e32 v94, 16, v95
	v_pk_mul_f32 v[84:85], v[84:85], v[168:169]
	v_and_b32_e32 v95, 0xffff0000, v95
	v_max_f32_e32 v168, 0xda24260, v84
	v_max_f32_e32 v169, 0xda24260, v85
	v_rcp_f32_e32 v168, v168
	v_rcp_f32_e32 v169, v169
	s_nop 0
	v_pk_mul_f32 v[92:93], v[168:169], v[92:93]
	s_nop 0
	v_cvt_pk_bf16_f32 v92, v92, v93
	ds_write_b32 v147, v92
	v_pk_mul_f32 v[92:93], v[84:85], v[94:95]
	s_nop 0
	v_cvt_pk_bf16_f32 v92, v92, v93
	ds_write_b32 v91, v92
	v_mul_u32_u24_e32 v91, 0x44, v90
	v_lshl_add_u32 v147, v91, 2, v113
	ds_read_b32 v91, v147
	v_mad_u32_u24 v92, v90, s20, v102
	v_lshl_add_u32 v168, v92, 2, v135
	ds_read_b32 v93, v168
	s_waitcnt lgkmcnt(1)
	v_lshlrev_b32_e32 v90, 16, v91
	v_and_b32_e32 v91, 0xffff0000, v91
	v_pk_add_f32 v[94:95], v[90:91], 1.0 op_sel_hi:[1,0] neg_lo:[1,0] neg_hi:[1,0]
	s_waitcnt lgkmcnt(0)
	v_lshlrev_b32_e32 v92, 16, v93
	v_pk_mul_f32 v[84:85], v[84:85], v[94:95]
	v_and_b32_e32 v93, 0xffff0000, v93
	v_max_f32_e32 v94, 0xda24260, v84
	v_max_f32_e32 v95, 0xda24260, v85
	v_rcp_f32_e32 v94, v94
	v_rcp_f32_e32 v95, v95
	s_nop 0
	v_pk_mul_f32 v[90:91], v[94:95], v[90:91]
	s_nop 0
	v_cvt_pk_bf16_f32 v90, v90, v91
	ds_write_b32 v147, v90
	v_pk_mul_f32 v[90:91], v[84:85], v[92:93]
	s_nop 0
	v_cvt_pk_bf16_f32 v90, v90, v91
	ds_write_b32 v168, v90
	global_load_dwordx4 v[22:25], v239, s[100:101] nt
	v_mul_u32_u24_e32 v90, 0x44, v89
	v_lshl_add_u32 v147, v90, 2, v113
	ds_read_b32 v91, v147
	v_mad_u32_u24 v89, v89, s20, v102
	v_lshl_add_u32 v89, v89, 2, v135
	ds_read_b32 v93, v89
	s_waitcnt lgkmcnt(1)
	v_lshlrev_b32_e32 v90, 16, v91
	v_and_b32_e32 v91, 0xffff0000, v91
	v_pk_add_f32 v[94:95], v[90:91], 1.0 op_sel_hi:[1,0] neg_lo:[1,0] neg_hi:[1,0]
	s_waitcnt lgkmcnt(0)
	v_lshlrev_b32_e32 v92, 16, v93
	v_pk_mul_f32 v[84:85], v[84:85], v[94:95]
	v_and_b32_e32 v93, 0xffff0000, v93
	v_max_f32_e32 v94, 0xda24260, v84
	v_max_f32_e32 v95, 0xda24260, v85
	v_rcp_f32_e32 v94, v94
	v_rcp_f32_e32 v95, v95
	s_nop 0
	v_pk_mul_f32 v[90:91], v[94:95], v[90:91]
	s_nop 0
	v_cvt_pk_bf16_f32 v90, v90, v91
	ds_write_b32 v147, v90
	v_pk_mul_f32 v[90:91], v[84:85], v[92:93]
	v_add_u32_e32 v147, v137, v71
	v_cvt_pk_bf16_f32 v90, v90, v91
	ds_write_b32 v89, v90
	v_mul_u32_u24_e32 v89, 0x44, v88
	v_lshl_add_u32 v94, v89, 2, v113
	ds_read_b32 v89, v94
	v_mad_u32_u24 v90, v88, s20, v102
	v_lshl_add_u32 v95, v90, 2, v135
	ds_read_b32 v91, v95
	s_waitcnt lgkmcnt(1)
	v_lshlrev_b32_e32 v88, 16, v89
	v_and_b32_e32 v89, 0xffff0000, v89
	v_pk_add_f32 v[92:93], v[88:89], 1.0 op_sel_hi:[1,0] neg_lo:[1,0] neg_hi:[1,0]
	s_waitcnt lgkmcnt(0)
	v_lshlrev_b32_e32 v90, 16, v91
	v_pk_mul_f32 v[84:85], v[84:85], v[92:93]
	v_and_b32_e32 v91, 0xffff0000, v91
	v_max_f32_e32 v92, 0xda24260, v84
	v_max_f32_e32 v93, 0xda24260, v85
	v_rcp_f32_e32 v92, v92
	v_rcp_f32_e32 v93, v93
	s_nop 0
	v_pk_mul_f32 v[88:89], v[92:93], v[88:89]
	s_nop 0
	v_cvt_pk_bf16_f32 v88, v88, v89
	ds_write_b32 v94, v88
	v_pk_mul_f32 v[88:89], v[84:85], v[90:91]
	s_nop 0
	v_cvt_pk_bf16_f32 v88, v88, v89
	ds_write_b32 v95, v88
	global_load_dwordx4 v[10:13], v240, s[100:101] nt
	v_mul_u32_u24_e32 v88, 0x44, v87
	v_lshl_add_u32 v94, v88, 2, v113
	ds_read_b32 v89, v94
	v_mad_u32_u24 v87, v87, s20, v102
	v_lshl_add_u32 v87, v87, 2, v135
	ds_read_b32 v91, v87
	s_waitcnt lgkmcnt(1)
	v_lshlrev_b32_e32 v88, 16, v89
	v_and_b32_e32 v89, 0xffff0000, v89
	v_pk_add_f32 v[92:93], v[88:89], 1.0 op_sel_hi:[1,0] neg_lo:[1,0] neg_hi:[1,0]
	s_waitcnt lgkmcnt(0)
	v_lshlrev_b32_e32 v90, 16, v91
	v_pk_mul_f32 v[84:85], v[84:85], v[92:93]
	v_and_b32_e32 v91, 0xffff0000, v91
	v_max_f32_e32 v92, 0xda24260, v84
	v_max_f32_e32 v93, 0xda24260, v85
	v_rcp_f32_e32 v92, v92
	v_rcp_f32_e32 v93, v93
	s_nop 0
	v_pk_mul_f32 v[88:89], v[92:93], v[88:89]
	s_nop 0
	v_cvt_pk_bf16_f32 v88, v88, v89
	ds_write_b32 v94, v88
	v_pk_mul_f32 v[88:89], v[84:85], v[90:91]
	s_nop 0
	v_cvt_pk_bf16_f32 v88, v88, v89
	ds_write_b32 v87, v88
	v_mul_u32_u24_e32 v87, 0x44, v86
	v_lshl_add_u32 v92, v87, 2, v113
	ds_read_b32 v87, v92
	v_mad_u32_u24 v88, v86, s20, v102
	v_lshl_add_u32 v93, v88, 2, v135
	ds_read_b32 v89, v93
	s_waitcnt lgkmcnt(1)
	v_lshlrev_b32_e32 v86, 16, v87
	v_and_b32_e32 v87, 0xffff0000, v87
	v_pk_add_f32 v[90:91], v[86:87], 1.0 op_sel_hi:[1,0] neg_lo:[1,0] neg_hi:[1,0]
	s_waitcnt lgkmcnt(0)
	v_lshlrev_b32_e32 v88, 16, v89
	v_pk_mul_f32 v[84:85], v[84:85], v[90:91]
	v_and_b32_e32 v89, 0xffff0000, v89
	v_max_f32_e32 v90, 0xda24260, v84
	v_max_f32_e32 v91, 0xda24260, v85
	v_rcp_f32_e32 v90, v90
	v_rcp_f32_e32 v91, v91
	v_pk_mul_f32 v[84:85], v[84:85], v[88:89]
	v_pk_mul_f32 v[86:87], v[90:91], v[86:87]
	s_nop 0
	v_cvt_pk_bf16_f32 v86, v86, v87
	v_cvt_pk_bf16_f32 v84, v84, v85
	ds_write_b32 v92, v86
	ds_write_b32 v93, v84
	global_load_dwordx4 v[14:17], v241, s[100:101] nt
	s_waitcnt lgkmcnt(0)
	s_barrier
	ds_read_b128 v[246:249], v136
	ds_read_b128 v[172:175], v147
	ds_read_b128 v[198:201], v147 offset:4352
	ds_read_b128 v[202:205], v147 offset:8704
	s_waitcnt lgkmcnt(2)
	v_mfma_f32_16x16x32_bf16 v[88:91], v[246:249], v[172:175], 0
	ds_read_b128 v[172:175], v176
	s_waitcnt lgkmcnt(2)
	v_mfma_f32_16x16x32_bf16 v[92:95], v[246:249], v[198:201], 0
	ds_read_b128 v[250:253], v136 offset:64
	ds_read_b128 v[198:201], v147 offset:64
	s_waitcnt lgkmcnt(3)
	v_mfma_f32_16x16x32_bf16 v[168:171], v[246:249], v[202:205], 0
	ds_read_b128 v[202:205], v147 offset:4416
	s_waitcnt lgkmcnt(3)
	v_mfma_f32_16x16x32_bf16 v[84:87], v[246:249], v[172:175], 0
	ds_read_b128 v[172:175], v147 offset:8768
	s_waitcnt lgkmcnt(2)
	v_mfma_f32_16x16x32_bf16 v[88:91], v[250:253], v[198:201], v[88:91]
	ds_read_b128 v[198:201], v176 offset:64
	global_load_dwordx4 v[26:29], v242, s[100:101] nt
	s_waitcnt lgkmcnt(2)
	v_mfma_f32_16x16x32_bf16 v[92:95], v[250:253], v[202:205], v[92:95]
	ds_read_b128 v[246:249], v136 offset:128
	ds_read_b128 v[202:205], v147 offset:128
	s_waitcnt lgkmcnt(3)
	v_mfma_f32_16x16x32_bf16 v[168:171], v[250:253], v[172:175], v[168:171]
	ds_read_b128 v[172:175], v147 offset:4480
	s_waitcnt lgkmcnt(3)
	v_mfma_f32_16x16x32_bf16 v[84:87], v[250:253], v[198:201], v[84:87]
	ds_read_b128 v[198:201], v147 offset:8832
	s_waitcnt lgkmcnt(2)
	v_mfma_f32_16x16x32_bf16 v[88:91], v[246:249], v[202:205], v[88:91]
	ds_read_b128 v[202:205], v176 offset:128
	s_waitcnt lgkmcnt(2)
	v_mfma_f32_16x16x32_bf16 v[92:95], v[246:249], v[172:175], v[92:95]
	ds_read_b128 v[250:253], v136 offset:192
	ds_read_b128 v[172:175], v147 offset:192
	s_waitcnt lgkmcnt(3)
	v_mfma_f32_16x16x32_bf16 v[168:171], v[246:249], v[198:201], v[168:171]
	ds_read_b128 v[198:201], v147 offset:4544
	s_waitcnt lgkmcnt(3)
	v_mfma_f32_16x16x32_bf16 v[84:87], v[246:249], v[202:205], v[84:87]
	ds_read_b128 v[202:205], v147 offset:8896
	s_waitcnt lgkmcnt(2)
	v_mfma_f32_16x16x32_bf16 v[88:91], v[250:253], v[172:175], v[88:91]
	ds_read_b128 v[172:175], v176 offset:192
	s_waitcnt lgkmcnt(2)
	v_mfma_f32_16x16x32_bf16 v[92:95], v[250:253], v[198:201], v[92:95]
	s_waitcnt lgkmcnt(1)
	v_mfma_f32_16x16x32_bf16 v[168:171], v[250:253], v[202:205], v[168:171]
	s_waitcnt lgkmcnt(0)
	v_mfma_f32_16x16x32_bf16 v[84:87], v[250:253], v[172:175], v[84:87]
	s_nop 7
	v_cvt_pk_bf16_f32 v88, v88, s0
	v_cvt_pk_bf16_f32 v89, v89, s0
	v_cvt_pk_bf16_f32 v90, v90, s0
	v_cvt_pk_bf16_f32 v91, v91, s0
	v_cndmask_b32_e64 v88, 0, v88, s[42:43]
	v_cndmask_b32_e64 v89, 0, v89, s[44:45]
	v_cndmask_b32_e64 v90, 0, v90, s[46:47]
	v_cndmask_b32_e64 v91, 0, v91, s[48:49]
	v_perm_b32 v88, v89, v88, s21
	v_perm_b32 v89, v91, v90, s21
	v_add_u32_e32 v90, v138, v75
	global_load_dwordx4 v[30:33], v243, s[100:101] nt
	ds_write_b64 v90, v[88:89]
	v_cvt_pk_bf16_f32 v88, v92, s0
	v_cvt_pk_bf16_f32 v89, v93, s0
	v_cvt_pk_bf16_f32 v91, v94, s0
	v_cvt_pk_bf16_f32 v92, v95, s0
	v_cndmask_b32_e64 v88, 0, v88, s[50:51]
	v_cndmask_b32_e64 v89, 0, v89, s[52:53]
	v_cndmask_b32_e64 v91, 0, v91, s[54:55]
	v_cndmask_b32_e64 v92, 0, v92, s[56:57]
	v_perm_b32 v88, v89, v88, s21
	v_perm_b32 v89, v92, v91, s21
	ds_write_b64 v90, v[88:89] offset:2304
	v_cvt_pk_bf16_f32 v88, v168, s0
	v_cvt_pk_bf16_f32 v89, v169, s0
	v_cvt_pk_bf16_f32 v91, v170, s0
	v_cvt_pk_bf16_f32 v92, v171, s0
	v_cvt_pk_bf16_f32 v84, v84, s0
	v_cvt_pk_bf16_f32 v85, v85, s0
	v_cvt_pk_bf16_f32 v86, v86, s0
	v_cvt_pk_bf16_f32 v87, v87, s0
	v_cndmask_b32_e64 v88, 0, v88, s[58:59]
	v_cndmask_b32_e64 v89, 0, v89, s[60:61]
	v_cndmask_b32_e64 v91, 0, v91, s[62:63]
	v_cndmask_b32_e64 v92, 0, v92, s[64:65]
	v_cndmask_b32_e64 v84, 0, v84, s[66:67]
	v_cndmask_b32_e64 v85, 0, v85, s[68:69]
	v_cndmask_b32_e64 v86, 0, v86, s[70:71]
	v_cndmask_b32_e64 v87, 0, v87, s[72:73]
	v_perm_b32 v88, v89, v88, s21
	v_perm_b32 v89, v92, v91, s21
	v_perm_b32 v84, v85, v84, s21
	v_perm_b32 v85, v87, v86, s21
	v_add_u32_e32 v86, v138, v96
	ds_write_b64 v90, v[88:89] offset:4608
	ds_write_b64 v86, v[84:85]
	s_waitcnt lgkmcnt(0)
	s_barrier
	ds_read_b64_tr_b16 v[84:85], v164
	ds_read_b64_tr_b16 v[86:87], v164 offset:1088
	ds_read_b128 v[88:91], v139
	ds_read_b128 v[92:95], v140
	s_waitcnt lgkmcnt(1)
	v_mfma_f32_16x16x32_bf16 v[88:91], v[88:91], v[84:87], 0
	v_add_u32_e32 v147, v106, v71
	v_add_u32_e32 v176, v106, v73
	s_waitcnt lgkmcnt(0)
	v_mfma_f32_16x16x32_bf16 v[88:91], v[92:95], v[84:87], v[88:91]
	ds_read_b128 v[92:95], v141
	ds_read_b128 v[168:171], v142
	s_waitcnt lgkmcnt(1)
	v_mfma_f32_16x16x32_bf16 v[92:95], v[92:95], v[84:87], 0
	s_waitcnt lgkmcnt(0)
	v_mfma_f32_16x16x32_bf16 v[92:95], v[168:171], v[84:87], v[92:95]
	ds_read_b128 v[168:171], v143
	ds_read_b128 v[172:175], v144
	s_waitcnt lgkmcnt(1)
	v_mfma_f32_16x16x32_bf16 v[168:171], v[168:171], v[84:87], 0
	s_waitcnt lgkmcnt(0)
	v_mfma_f32_16x16x32_bf16 v[168:171], v[172:175], v[84:87], v[168:171]
	ds_read_b128 v[172:175], v145
	ds_read_b128 v[198:201], v152
	s_waitcnt lgkmcnt(1)
	v_mfma_f32_16x16x32_bf16 v[172:175], v[172:175], v[84:87], 0
	s_waitcnt lgkmcnt(0)
	v_mfma_f32_16x16x32_bf16 v[84:87], v[198:201], v[84:87], v[172:175]
	s_nop 5
	ds_read_b64_tr_b16 v[172:173], v165
	ds_read_b64_tr_b16 v[174:175], v165 offset:1088
	ds_read_b128 v[198:201], v153
	ds_read_b128 v[202:205], v154
	s_waitcnt lgkmcnt(1)
	v_mfma_f32_16x16x32_bf16 v[88:91], v[198:201], v[172:175], v[88:91]
	s_waitcnt lgkmcnt(0)
	v_mfma_f32_16x16x32_bf16 v[88:91], v[202:205], v[172:175], v[88:91]
	ds_read_b128 v[198:201], v155
	ds_read_b128 v[202:205], v156
	s_waitcnt lgkmcnt(1)
	v_mfma_f32_16x16x32_bf16 v[92:95], v[198:201], v[172:175], v[92:95]
	s_waitcnt lgkmcnt(0)
	v_mfma_f32_16x16x32_bf16 v[92:95], v[202:205], v[172:175], v[92:95]
	ds_read_b128 v[198:201], v157
	ds_read_b128 v[202:205], v158
	s_waitcnt lgkmcnt(1)
	v_mfma_f32_16x16x32_bf16 v[168:171], v[198:201], v[172:175], v[168:171]
	s_waitcnt lgkmcnt(0)
	v_mfma_f32_16x16x32_bf16 v[168:171], v[202:205], v[172:175], v[168:171]
	ds_read_b128 v[198:201], v159
	ds_read_b128 v[202:205], v160
	s_waitcnt lgkmcnt(1)
	v_mfma_f32_16x16x32_bf16 v[84:87], v[198:201], v[172:175], v[84:87]
	s_waitcnt lgkmcnt(0)
	v_mfma_f32_16x16x32_bf16 v[84:87], v[202:205], v[172:175], v[84:87]
	ds_read_b128 v[172:175], v147
	ds_read_b128 v[198:201], v147 offset:4352
	ds_read_b128 v[202:205], v147 offset:8704
	ds_read_b128 v[246:249], v176
	s_lshl_b32 s80, s14, 8
	ds_read_b128 v[250:253], v147 offset:64
	s_waitcnt vmcnt(15) lgkmcnt(4)
	v_mfma_f32_16x16x32_bf16 v[88:91], v[172:175], v[62:65], v[88:91]
	ds_read_b128 v[172:175], v147 offset:4416
	s_waitcnt lgkmcnt(4)
	v_mfma_f32_16x16x32_bf16 v[92:95], v[198:201], v[62:65], v[92:95]
	ds_read_b128 v[198:201], v147 offset:8768
	s_waitcnt lgkmcnt(4)
	v_mfma_f32_16x16x32_bf16 v[168:171], v[202:205], v[62:65], v[168:171]
	ds_read_b128 v[202:205], v176 offset:64
	s_waitcnt lgkmcnt(4)
	v_mfma_f32_16x16x32_bf16 v[84:87], v[246:249], v[62:65], v[84:87]
	ds_read_b128 v[246:249], v147 offset:128
	s_waitcnt vmcnt(14) lgkmcnt(4)
	v_mfma_f32_16x16x32_bf16 v[88:91], v[250:253], v[58:61], v[88:91]
	ds_read_b128 v[250:253], v147 offset:4480
	s_waitcnt lgkmcnt(4)
	v_mfma_f32_16x16x32_bf16 v[92:95], v[172:175], v[58:61], v[92:95]
	ds_read_b128 v[172:175], v147 offset:8832
	s_waitcnt lgkmcnt(4)
	v_mfma_f32_16x16x32_bf16 v[168:171], v[198:201], v[58:61], v[168:171]
	ds_read_b128 v[198:201], v176 offset:128
	s_waitcnt lgkmcnt(4)
	v_mfma_f32_16x16x32_bf16 v[84:87], v[202:205], v[58:61], v[84:87]
	ds_read_b128 v[202:205], v147 offset:192
	s_waitcnt vmcnt(13) lgkmcnt(4)
	v_mfma_f32_16x16x32_bf16 v[88:91], v[246:249], v[54:57], v[88:91]
	ds_read_b128 v[246:249], v147 offset:4544
	s_waitcnt lgkmcnt(4)
	v_mfma_f32_16x16x32_bf16 v[92:95], v[250:253], v[54:57], v[92:95]
	ds_read_b128 v[250:253], v147 offset:8896
	s_waitcnt lgkmcnt(4)
	v_mfma_f32_16x16x32_bf16 v[168:171], v[172:175], v[54:57], v[168:171]
	ds_read_b128 v[172:175], v176 offset:192
	s_waitcnt lgkmcnt(4)
	v_mfma_f32_16x16x32_bf16 v[84:87], v[198:201], v[54:57], v[84:87]
	ds_read_b128 v[198:201], v147 offset:17408
	s_waitcnt vmcnt(12) lgkmcnt(4)
	v_mfma_f32_16x16x32_bf16 v[88:91], v[202:205], v[50:53], v[88:91]
	ds_read_b128 v[202:205], v147 offset:21760
	s_waitcnt lgkmcnt(4)
	v_mfma_f32_16x16x32_bf16 v[92:95], v[246:249], v[50:53], v[92:95]
	ds_read_b128 v[246:249], v147 offset:26112
	s_waitcnt lgkmcnt(4)
	v_mfma_f32_16x16x32_bf16 v[168:171], v[250:253], v[50:53], v[168:171]
	ds_read_b128 v[250:253], v176 offset:17408
	s_waitcnt lgkmcnt(4)
	v_mfma_f32_16x16x32_bf16 v[84:87], v[172:175], v[50:53], v[84:87]
	ds_read_b128 v[172:175], v147 offset:17472
	s_waitcnt vmcnt(11) lgkmcnt(4)
	v_mfma_f32_16x16x32_bf16 v[88:91], v[198:201], v[46:49], v[88:91]
	ds_read_b128 v[198:201], v147 offset:21824
	s_waitcnt lgkmcnt(4)
	v_mfma_f32_16x16x32_bf16 v[92:95], v[202:205], v[46:49], v[92:95]
	ds_read_b128 v[202:205], v147 offset:26176
	s_waitcnt lgkmcnt(4)
	v_mfma_f32_16x16x32_bf16 v[168:171], v[246:249], v[46:49], v[168:171]
	ds_read_b128 v[246:249], v176 offset:17472
	s_waitcnt lgkmcnt(4)
	v_mfma_f32_16x16x32_bf16 v[84:87], v[250:253], v[46:49], v[84:87]
	ds_read_b128 v[250:253], v147 offset:17536
	s_waitcnt vmcnt(10) lgkmcnt(4)
	v_mfma_f32_16x16x32_bf16 v[88:91], v[172:175], v[42:45], v[88:91]
	ds_read_b128 v[172:175], v147 offset:21888
	s_waitcnt lgkmcnt(4)
	v_mfma_f32_16x16x32_bf16 v[92:95], v[198:201], v[42:45], v[92:95]
	ds_read_b128 v[198:201], v147 offset:26240
	s_waitcnt lgkmcnt(4)
	v_mfma_f32_16x16x32_bf16 v[168:171], v[202:205], v[42:45], v[168:171]
	ds_read_b128 v[202:205], v176 offset:17536
	s_waitcnt lgkmcnt(4)
	v_mfma_f32_16x16x32_bf16 v[84:87], v[246:249], v[42:45], v[84:87]
	ds_read_b128 v[246:249], v147 offset:17600
	s_waitcnt vmcnt(9) lgkmcnt(4)
	v_mfma_f32_16x16x32_bf16 v[88:91], v[250:253], v[38:41], v[88:91]
	ds_read_b128 v[250:253], v147 offset:21952
	s_waitcnt lgkmcnt(4)
	v_mfma_f32_16x16x32_bf16 v[92:95], v[172:175], v[38:41], v[92:95]
	ds_read_b128 v[172:175], v147 offset:26304
	s_waitcnt lgkmcnt(4)
	v_mfma_f32_16x16x32_bf16 v[168:171], v[198:201], v[38:41], v[168:171]
	ds_read_b128 v[198:201], v176 offset:17600
	s_waitcnt lgkmcnt(4)
	v_mfma_f32_16x16x32_bf16 v[84:87], v[202:205], v[38:41], v[84:87]
	v_lshl_add_u64 v[58:59], vcc, 0, v[76:77]
	s_waitcnt vmcnt(8) lgkmcnt(3)
	v_mfma_f32_16x16x32_bf16 v[42:45], v[246:249], v[34:37], v[88:91]
	s_waitcnt lgkmcnt(2)
	v_mfma_f32_16x16x32_bf16 v[46:49], v[250:253], v[34:37], v[92:95]
	s_waitcnt lgkmcnt(1)
	v_mfma_f32_16x16x32_bf16 v[50:53], v[172:175], v[34:37], v[168:171]
	s_waitcnt lgkmcnt(0)
	v_mfma_f32_16x16x32_bf16 v[38:41], v[198:201], v[34:37], v[84:87]
	v_lshlrev_b64 v[34:35], 8, v[58:59]
	v_lshl_add_u64 v[34:35], s[16:17], 0, v[34:35]
	v_lshl_add_u64 v[34:35], v[34:35], 0, v[0:1]
	s_mov_b64 s[16:17], 0x10000000
	v_lshl_add_u64 v[36:37], v[34:35], 0, s[16:17]
	v_add_co_u32_e32 v34, vcc, s15, v34
	v_lshlrev_b64 v[58:59], 11, v[58:59]
	s_nop 0
	v_addc_co_u32_e32 v35, vcc, 0, v35, vcc
	global_load_dwordx4 v[54:57], v[34:35], off nt
	s_nop 0
	global_load_dwordx4 v[34:37], v[36:37], off offset:16 nt
	s_barrier
	ds_write2_b32 v166, v42, v43 offset1:132
	v_add_u32_e32 v42, 0x400, v166
	ds_write2_b32 v42, v44, v45 offset0:8 offset1:140
	v_add_u32_e32 v42, 0x2000, v166
	ds_write2_b32 v42, v46, v47 offset0:64 offset1:196
	v_add_u32_e32 v42, 0x2400, v166
	ds_write2_b32 v42, v48, v49 offset0:72 offset1:204
	v_add_u32_e32 v42, 0x4200, v166
	ds_write2_b32 v42, v50, v51 offset1:132
	v_add_u32_e32 v42, 0x4600, v166
	ds_write2_b32 v42, v52, v53 offset0:8 offset1:140
	v_add_u32_e32 v42, 0x6200, v166
	ds_write2_b32 v42, v38, v39 offset0:64 offset1:196
	v_add_u32_e32 v38, 0x6600, v166
	ds_write2_b32 v38, v40, v41 offset0:72 offset1:204
	s_waitcnt lgkmcnt(0)
	s_barrier
	ds_read_b128 v[50:53], v162
	ds_read_b128 v[46:49], v162 offset:16
	ds_read_b128 v[42:45], v162 offset:32
	ds_read_b128 v[38:41], v162 offset:48
	v_lshl_add_u64 v[58:59], s[74:75], 0, v[58:59]
	s_waitcnt lgkmcnt(3)
	v_pk_mul_f32 v[60:61], v[52:53], v[52:53]
	v_pk_mul_f32 v[62:63], v[50:51], v[50:51]
	v_lshl_add_u64 v[58:59], v[58:59], 0, s[80:81]
	v_pk_mov_b32 v[64:65], v[62:63], v[60:61] op_sel:[1,0]
	v_mov_b32_e32 v63, v61
	v_pk_add_f32 v[60:61], v[64:65], v[62:63]
	s_waitcnt lgkmcnt(2)
	v_pk_mul_f32 v[62:63], v[48:49], v[48:49]
	v_pk_mul_f32 v[64:65], v[46:47], v[46:47]
	v_pk_add_f32 v[60:61], v[60:61], v[60:61] op_sel:[0,1] op_sel_hi:[1,0]
	v_pk_mov_b32 v[84:85], v[64:65], v[62:63] op_sel:[1,0]
	v_mov_b32_e32 v65, v63
	v_pk_add_f32 v[62:63], v[84:85], v[64:65]
	s_waitcnt lgkmcnt(0)
	v_mul_f32_e32 v64, v38, v38
	v_mul_f32_e32 v65, v39, v39
	v_pk_add_f32 v[62:63], v[62:63], v[62:63] op_sel:[0,1] op_sel_hi:[1,0]
	v_mov_b32_e32 v61, v64
	v_mov_b32_e32 v63, v65
	v_pk_add_f32 v[60:61], v[60:61], v[62:63]
	v_mul_f32_e32 v62, v43, v43
	v_mul_f32_e32 v64, v45, v45
	v_mul_f32_e32 v84, v40, v40
	v_mul_f32_e32 v85, v41, v41
	v_pk_fma_f32 v[62:63], v[42:43], v[42:43], v[62:63] op_sel_hi:[1,1,0]
	v_pk_fma_f32 v[64:65], v[44:45], v[44:45], v[64:65] op_sel_hi:[1,1,0]
	v_mov_b32_e32 v63, v84
	v_mov_b32_e32 v65, v85
	v_pk_add_f32 v[62:63], v[62:63], v[64:65]
	v_lshl_add_u64 v[86:87], v[58:59], 0, v[0:1]
	v_pk_add_f32 v[60:61], v[60:61], v[62:63]
	s_waitcnt vmcnt(1)
	v_lshlrev_b32_e32 v92, 16, v54
	v_add_f32_e32 v60, v60, v61
	ds_bpermute_b32 v61, v97, v60
	v_and_b32_e32 v93, 0xffff0000, v54
	v_lshlrev_b32_e32 v94, 16, v55
	v_and_b32_e32 v95, 0xffff0000, v55
	v_lshlrev_b32_e32 v88, 16, v56
	s_waitcnt lgkmcnt(0)
	v_add_f32_e32 v60, v60, v61
	ds_bpermute_b32 v61, v98, v60
	v_and_b32_e32 v89, 0xffff0000, v56
	v_lshlrev_b32_e32 v90, 16, v57
	v_and_b32_e32 v91, 0xffff0000, v57
	s_waitcnt lgkmcnt(0)
	v_add_f32_e32 v60, v60, v61
	ds_bpermute_b32 v61, v163, v60
	s_waitcnt lgkmcnt(0)
	v_add_f32_e32 v60, v60, v61
	v_fmamk_f32 v60, v60, 0x3c000000, v178
	v_cmp_gt_f32_e32 vcc, s22, v60
	v_mul_f32_e32 v61, 0x4b800000, v60
	s_nop 0
	v_cndmask_b32_e32 v60, v60, v61, vcc
	v_rsq_f32_e32 v60, v60
	s_nop 0
	v_mul_f32_e32 v61, 0x45800000, v60
	v_cndmask_b32_e32 v84, v60, v61, vcc
	v_pk_mul_f32 v[52:53], v[52:53], v[84:85] op_sel_hi:[1,0]
	v_pk_mul_f32 v[50:51], v[50:51], v[84:85] op_sel_hi:[1,0]
	v_pk_mul_f32 v[48:49], v[48:49], v[84:85] op_sel_hi:[1,0]
	v_pk_mul_f32 v[46:47], v[46:47], v[84:85] op_sel_hi:[1,0]
	v_pk_mul_f32 v[44:45], v[44:45], v[84:85] op_sel_hi:[1,0]
	v_pk_mul_f32 v[42:43], v[42:43], v[84:85] op_sel_hi:[1,0]
	v_pk_mul_f32 v[40:41], v[40:41], v[84:85] op_sel_hi:[1,0]
	v_pk_mul_f32 v[38:39], v[38:39], v[84:85] op_sel_hi:[1,0]
	s_and_b64 vcc, exec, s[12:13]
	v_pk_mul_f32 v[38:39], v[232:233], v[38:39]
	v_pk_mul_f32 v[42:43], v[228:229], v[42:43]
	v_pk_mul_f32 v[46:47], v[224:225], v[46:47]
	v_pk_mul_f32 v[50:51], v[220:221], v[50:51]
	v_pk_mul_f32 v[52:53], v[222:223], v[52:53]
	v_pk_mul_f32 v[48:49], v[226:227], v[48:49]
	v_pk_mul_f32 v[52:53], v[52:53], v[94:95]
	v_pk_mul_f32 v[50:51], v[50:51], v[92:93]
	v_pk_mul_f32 v[62:63], v[48:49], v[90:91]
	v_pk_mul_f32 v[48:49], v[46:47], v[88:89]
	v_cvt_pk_bf16_f32 v46, v50, v51
	v_cvt_pk_bf16_f32 v47, v52, v53
	v_cvt_pk_bf16_f32 v48, v48, v49
	v_cvt_pk_bf16_f32 v49, v62, v63
	global_store_dwordx4 v[86:87], v[46:49], off offset:1024
	v_pk_mul_f32 v[44:45], v[230:231], v[44:45]
	v_pk_mul_f32 v[40:41], v[234:235], v[40:41]
	s_waitcnt vmcnt(1)
	v_lshlrev_b32_e32 v46, 16, v34
	v_and_b32_e32 v47, 0xffff0000, v34
	v_lshlrev_b32_e32 v34, 16, v35
	v_and_b32_e32 v35, 0xffff0000, v35
	v_lshlrev_b32_e32 v48, 16, v36
	v_and_b32_e32 v49, 0xffff0000, v36
	v_lshlrev_b32_e32 v36, 16, v37
	v_and_b32_e32 v37, 0xffff0000, v37
	v_pk_mul_f32 v[44:45], v[44:45], v[34:35]
	v_pk_mul_f32 v[34:35], v[42:43], v[46:47]
	v_pk_mul_f32 v[40:41], v[40:41], v[36:37]
	v_pk_mul_f32 v[36:37], v[38:39], v[48:49]
	v_cvt_pk_bf16_f32 v34, v34, v35
	v_cvt_pk_bf16_f32 v35, v44, v45
	v_cvt_pk_bf16_f32 v36, v36, v37
	v_cvt_pk_bf16_f32 v37, v40, v41
	global_store_dwordx4 v[86:87], v[34:37], off offset:1040
	s_barrier
	s_cbranch_vccnz .LBB0_455
.LBB0_445:
	s_add_i32 s28, s29, s2
	s_cmpk_gt_i32 s28, 0x7ff
	s_cselect_b64 s[12:13], -1, 0
	s_waitcnt vmcnt(11)
	ds_write_b128 v109, v[2:5]
	ds_write_b128 v109, v[2:5] offset:17408
	s_waitcnt vmcnt(10)
	ds_write_b128 v109, v[6:9] offset:34816
	s_waitcnt vmcnt(9)
	ds_write_b128 v109, v[18:21] offset:52224
	s_waitcnt vmcnt(8)
	ds_write_b128 v110, v[22:25]
	s_waitcnt vmcnt(7)
	ds_write_b128 v111, v[10:13]
	ds_write_b128 v111, v[10:13] offset:17408
	s_waitcnt vmcnt(6)
	ds_write_b128 v111, v[14:17] offset:34816
	s_waitcnt vmcnt(5)
	ds_write_b128 v111, v[26:29] offset:52224
	s_waitcnt vmcnt(4)
	ds_write_b128 v112, v[30:33]
	s_waitcnt lgkmcnt(0)
	s_barrier
	s_cmpk_lt_i32 s28, 0x800
	s_cselect_b32 s14, s28, s29
	s_lshr_b32 s15, s14, 2
	s_lshl_b32 s15, s15, 14
	s_and_b32 s14, s14, 3
	s_lshl_b32 s14, s14, 23
	s_add_u32 s14, s14, s15
	s_add_u32 s14, s14, 0x8000000
	s_add_u32 s100, s86, s14
	s_addc_u32 s101, s87, 0
	s_and_b32 s14, s29, 3
	s_lshl_b32 s14, s14, 9
	s_mov_b32 s15, 0
	v_lshl_add_u64 v[244:245], v[80:81], 0, s[14:15]
	global_load_dwordx4 v[220:223], v[244:245], off nt
	global_load_dwordx4 v[224:227], v[244:245], off offset:16 nt
	global_load_dwordx4 v[228:231], v[244:245], off offset:32 nt
	global_load_dwordx4 v[232:235], v[244:245], off offset:48 nt
.LBB0_447:
	s_movk_i32 s14, 0x8000
	v_add_co_u32_e32 v34, vcc, s14, v82
	v_readfirstlane_b32 s14, v70
	s_nop 0
	v_addc_co_u32_e32 v35, vcc, -1, v83, vcc
	global_load_dwordx4 v[62:65], v[34:35], off offset:-192 nt
	s_bfe_u32 s16, s14, 0x20006
	s_lshl_b32 s14, s16, 4
	s_or_b32 s15, s14, 15
	v_mov_b32_e32 v197, s15
	v_mov_b32_e32 v200, s14
	v_cndmask_b32_e64 v173, v197, v200, s[40:41]
	v_or_b32_e32 v172, s14, v115
	v_or_b32_e32 v171, s14, v118
	v_or_b32_e32 v170, s14, v119
	v_mad_u32_u24 v84, v173, s18, v113
	v_mad_u32_u24 v85, v172, s18, v113
	v_mad_u32_u24 v86, v171, s18, v113
	v_mad_u32_u24 v87, v170, s18, v113
	v_or_b32_e32 v169, s14, v120
	v_or_b32_e32 v168, s14, v121
	v_or_b32_e32 v95, s14, v122
	v_or_b32_e32 v94, s14, v123
	v_mad_u32_u24 v88, v169, s18, v113
	v_mad_u32_u24 v89, v168, s18, v113
	v_mad_u32_u24 v90, v95, s18, v113
	v_mad_u32_u24 v91, v94, s18, v113
	ds_read_b32 v92, v84
	ds_read_b32 v93, v85
	ds_read_b32 v147, v86
	ds_read_b32 v174, v87
	ds_read_b32 v175, v88
	ds_read_b32 v176, v89
	ds_read_b32 v177, v90
	ds_read_b32 v199, v91
	global_load_dwordx4 v[58:61], v[34:35], off offset:-128 nt
	s_waitcnt lgkmcnt(7)
	v_lshlrev_b32_e32 v84, 16, v92
	v_and_b32_e32 v85, 0xffff0000, v92
	s_waitcnt lgkmcnt(6)
	v_lshlrev_b32_e32 v86, 16, v93
	v_and_b32_e32 v87, 0xffff0000, v93
	s_waitcnt lgkmcnt(5)
	v_lshlrev_b32_e32 v88, 16, v147
	v_and_b32_e32 v89, 0xffff0000, v147
	v_pk_add_f32 v[84:85], v[84:85], 1.0 op_sel_hi:[1,0] neg_lo:[1,0] neg_hi:[1,0]
	v_pk_add_f32 v[86:87], v[86:87], 1.0 op_sel_hi:[1,0] neg_lo:[1,0] neg_hi:[1,0]
	s_waitcnt lgkmcnt(4)
	v_lshlrev_b32_e32 v90, 16, v174
	v_and_b32_e32 v91, 0xffff0000, v174
	v_pk_mul_f32 v[84:85], v[84:85], v[86:87]
	v_pk_add_f32 v[86:87], v[88:89], 1.0 op_sel_hi:[1,0] neg_lo:[1,0] neg_hi:[1,0]
	s_waitcnt lgkmcnt(3)
	v_lshlrev_b32_e32 v92, 16, v175
	v_and_b32_e32 v93, 0xffff0000, v175
	v_pk_mul_f32 v[84:85], v[84:85], v[86:87]
	v_pk_add_f32 v[86:87], v[90:91], 1.0 op_sel_hi:[1,0] neg_lo:[1,0] neg_hi:[1,0]
	v_or_b32_e32 v91, s14, v127
	v_pk_mul_f32 v[84:85], v[84:85], v[86:87]
	v_pk_add_f32 v[86:87], v[92:93], 1.0 op_sel_hi:[1,0] neg_lo:[1,0] neg_hi:[1,0]
	v_or_b32_e32 v93, s14, v124
	v_pk_mul_f32 v[84:85], v[84:85], v[86:87]
	s_waitcnt lgkmcnt(2)
	v_lshlrev_b32_e32 v86, 16, v176
	v_and_b32_e32 v87, 0xffff0000, v176
	v_pk_add_f32 v[174:175], v[86:87], 1.0 op_sel_hi:[1,0] neg_lo:[1,0] neg_hi:[1,0]
	v_cndmask_b32_e64 v86, v200, v197, s[40:41]
	s_waitcnt lgkmcnt(1)
	v_lshlrev_b32_e32 v176, 16, v177
	v_and_b32_e32 v177, 0xffff0000, v177
	v_mad_u32_u24 v201, v93, s18, v113
	v_or_b32_e32 v92, s14, v126
	v_or_b32_e32 v90, s14, v128
	v_or_b32_e32 v89, s14, v129
	v_or_b32_e32 v88, s14, v130
	v_or_b32_e32 v87, s14, v131
	v_mad_u32_u24 v197, v86, s18, v113
	s_waitcnt lgkmcnt(0)
	v_lshlrev_b32_e32 v198, 16, v199
	v_and_b32_e32 v199, 0xffff0000, v199
	v_mad_u32_u24 v202, v92, s18, v113
	v_mad_u32_u24 v203, v91, s18, v113
	v_mad_u32_u24 v204, v90, s18, v113
	v_mad_u32_u24 v205, v89, s18, v113
	v_mad_u32_u24 v206, v88, s18, v113
	v_mad_u32_u24 v207, v87, s18, v113
	ds_read_b32 v201, v201
	ds_read_b32 v208, v202
	ds_read_b32 v209, v203
	ds_read_b32 v210, v204
	ds_read_b32 v211, v205
	ds_read_b32 v212, v206
	ds_read_b32 v213, v207
	ds_read_b32 v197, v197
	global_load_dwordx4 v[54:57], v[34:35], off offset:-64 nt
	v_pk_mul_f32 v[84:85], v[84:85], v[174:175]
	v_pk_add_f32 v[174:175], v[176:177], 1.0 op_sel_hi:[1,0] neg_lo:[1,0] neg_hi:[1,0]
	s_waitcnt lgkmcnt(7)
	v_lshlrev_b32_e32 v200, 16, v201
	v_and_b32_e32 v201, 0xffff0000, v201
	v_pk_mul_f32 v[84:85], v[84:85], v[174:175]
	v_pk_add_f32 v[174:175], v[198:199], 1.0 op_sel_hi:[1,0] neg_lo:[1,0] neg_hi:[1,0]
	s_waitcnt lgkmcnt(6)
	v_lshlrev_b32_e32 v202, 16, v208
	v_and_b32_e32 v203, 0xffff0000, v208
	v_pk_mul_f32 v[84:85], v[84:85], v[174:175]
	v_pk_add_f32 v[174:175], v[200:201], 1.0 op_sel_hi:[1,0] neg_lo:[1,0] neg_hi:[1,0]
	s_waitcnt lgkmcnt(5)
	v_lshlrev_b32_e32 v204, 16, v209
	v_and_b32_e32 v205, 0xffff0000, v209
	v_pk_mul_f32 v[84:85], v[84:85], v[174:175]
	v_pk_add_f32 v[174:175], v[202:203], 1.0 op_sel_hi:[1,0] neg_lo:[1,0] neg_hi:[1,0]
	s_waitcnt lgkmcnt(4)
	v_lshlrev_b32_e32 v206, 16, v210
	v_and_b32_e32 v207, 0xffff0000, v210
	v_pk_mul_f32 v[84:85], v[84:85], v[174:175]
	v_pk_add_f32 v[174:175], v[204:205], 1.0 op_sel_hi:[1,0] neg_lo:[1,0] neg_hi:[1,0]
	s_waitcnt lgkmcnt(3)
	v_lshlrev_b32_e32 v208, 16, v211
	v_and_b32_e32 v209, 0xffff0000, v211
	v_pk_mul_f32 v[84:85], v[84:85], v[174:175]
	v_pk_add_f32 v[174:175], v[206:207], 1.0 op_sel_hi:[1,0] neg_lo:[1,0] neg_hi:[1,0]
	s_waitcnt lgkmcnt(2)
	v_lshlrev_b32_e32 v210, 16, v212
	v_and_b32_e32 v211, 0xffff0000, v212
	v_pk_mul_f32 v[84:85], v[84:85], v[174:175]
	v_pk_add_f32 v[174:175], v[208:209], 1.0 op_sel_hi:[1,0] neg_lo:[1,0] neg_hi:[1,0]
	s_waitcnt lgkmcnt(1)
	v_lshlrev_b32_e32 v212, 16, v213
	v_and_b32_e32 v213, 0xffff0000, v213
	v_pk_mul_f32 v[84:85], v[84:85], v[174:175]
	v_pk_add_f32 v[174:175], v[210:211], 1.0 op_sel_hi:[1,0] neg_lo:[1,0] neg_hi:[1,0]
	s_waitcnt lgkmcnt(0)
	v_lshlrev_b32_e32 v216, 16, v197
	v_and_b32_e32 v217, 0xffff0000, v197
	v_pk_mul_f32 v[84:85], v[84:85], v[174:175]
	v_pk_add_f32 v[174:175], v[212:213], 1.0 op_sel_hi:[1,0] neg_lo:[1,0] neg_hi:[1,0]
	v_or_b32_e32 v197, s16, v133
	v_pk_mul_f32 v[84:85], v[84:85], v[174:175]
	v_pk_add_f32 v[174:175], v[216:217], 1.0 op_sel_hi:[1,0] neg_lo:[1,0] neg_hi:[1,0]
	s_cmp_lg_u32 s16, 0
	v_mov_b32_e32 v147, v146
	v_lshl_add_u32 v197, v197, 9, v134
	v_pk_mul_f32 v[84:85], v[84:85], v[174:175]
	s_cselect_b64 s[14:15], -1, 0
	ds_write_b64 v197, v[84:85]
	s_and_b64 s[30:31], s[40:41], s[14:15]
	v_mov_b64_e32 v[84:85], v[146:147]
	s_waitcnt lgkmcnt(0)
	s_barrier
	s_and_saveexec_b64 s[14:15], s[30:31]
	ds_read_b64 v[84:85], v134
	s_or_b64 exec, exec, s[14:15]
	s_cmp_eq_u32 s16, 0
	s_cselect_b64 s[14:15], -1, 0
	s_cmp_gt_u32 s16, 1
	v_cndmask_b32_e64 v147, 0, 1, s[14:15]
	s_cselect_b64 s[14:15], -1, 0
	v_cndmask_b32_e64 v174, 0, 1, s[14:15]
	v_cndmask_b32_e64 v147, v147, v174, s[40:41]
	v_and_b32_e32 v147, 1, v147
	v_cmp_eq_u32_e32 vcc, 1, v147
	s_and_saveexec_b64 s[14:15], vcc
	s_cbranch_execz .LBB0_451
	ds_read_b64 v[174:175], v167 offset:512
	s_waitcnt lgkmcnt(0)
	v_pk_mul_f32 v[84:85], v[84:85], v[174:175]

.LBB0_455:
	v_or_b32_e32 v31, s25, v101
	v_sub_u32_e32 v32, v99, v31
	v_sub_u32_e32 v33, 0, v32
	v_max_i32_e32 v32, v32, v33
	v_cvt_f32_u32_e32 v59, v32
	v_or_b32_e32 v32, 1, v31
	v_sub_u32_e32 v33, v99, v32
	v_sub_u32_e32 v34, 0, v33
	v_max_i32_e32 v33, v33, v34
	v_cvt_f32_u32_e32 v60, v33
	v_or_b32_e32 v33, 2, v31
	v_sub_u32_e32 v34, v99, v33
	v_sub_u32_e32 v35, 0, v34
	v_max_i32_e32 v34, v34, v35
	v_cvt_f32_u32_e32 v61, v34
	v_or_b32_e32 v34, 3, v31
	s_lshl_b32 s10, s8, 22
	v_sub_u32_e32 v35, v99, v34
	s_and_b32 s10, s10, 0x1c00000
	v_sub_u32_e32 v36, 0, v35
	s_add_u32 s10, s86, s10
	v_max_i32_e32 v35, v35, v36
	s_addc_u32 s11, s87, 0
	v_cvt_f32_u32_e32 v62, v35
	v_sub_u32_e32 v35, v107, v31
	s_add_u32 s12, s10, 0x4000000
	v_sub_u32_e32 v36, 0, v35
	s_addc_u32 s13, s11, 0
	s_ashr_i32 s14, s8, 3
	v_max_i32_e32 v35, v35, v36
	s_ashr_i32 s15, s14, 31
	v_cvt_f32_u32_e32 v63, v35
	v_sub_u32_e32 v35, v107, v32
	s_lshl_b64 s[14:15], s[14:15], 13
	v_sub_u32_e32 v36, 0, v35
	v_lshl_add_u64 v[2:3], s[14:15], 0, v[68:69]
	v_max_i32_e32 v35, v35, v36
	v_lshlrev_b64 v[2:3], 1, v[2:3]
	s_add_u32 s16, s10, 0x2000000
	v_cvt_f32_u32_e32 v64, v35
	v_sub_u32_e32 v35, v107, v33
	v_lshl_add_u64 v[4:5], s[12:13], 0, v[2:3]
	s_addc_u32 s17, s11, 0
	v_sub_u32_e32 v36, 0, v35
	v_lshl_add_u64 v[6:7], s[16:17], 0, v[2:3]
	global_load_dwordx4 v[14:17], v[4:5], off nt
	global_load_dwordx4 v[10:13], v[6:7], off nt
	v_lshl_add_u64 v[4:5], s[14:15], 0, v[66:67]
	v_max_i32_e32 v35, v35, v36
	v_lshlrev_b64 v[4:5], 1, v[4:5]
	v_lshlrev_b32_e32 v0, 1, v104
	v_add_u32_e32 v27, 1, v76
	v_cvt_f32_u32_e32 v65, v35
	v_sub_u32_e32 v35, v107, v34
	v_lshl_add_u64 v[6:7], s[12:13], 0, v[4:5]
	v_and_b32_e32 v0, 0x70, v0
	s_add_i32 s12, 0, 0x12000
	v_cvt_f32_i32_e32 v43, v27
	v_sub_u32_e32 v27, 0x80, v76
	s_movk_i32 s13, 0x90
	v_sub_u32_e32 v36, 0, v35
	v_add_u32_e32 v26, 0, v0
	v_add_u32_e32 v0, s12, v0
	v_cvt_f32_i32_e32 v52, v27
	v_mul_lo_u32 v27, v76, s13
	v_max_i32_e32 v35, v35, v36
	v_add_u32_e32 v53, v26, v27
	v_add_u32_e32 v54, v0, v27
	v_ashrrev_i32_e32 v27, 3, v74
	v_cvt_f32_u32_e32 v74, v35
	v_sub_u32_e32 v35, v105, v31
	v_sub_u32_e32 v36, 0, v35
	v_max_i32_e32 v35, v35, v36
	v_cvt_f32_u32_e32 v76, v35
	v_sub_u32_e32 v35, v105, v32
	v_lshl_add_u64 v[2:3], s[10:11], 0, v[2:3]
	v_sub_u32_e32 v36, 0, v35
	global_load_dwordx4 v[18:21], v[2:3], off nt
	global_load_dwordx4 v[22:25], v[6:7], off nt
	v_lshl_add_u64 v[2:3], s[16:17], 0, v[4:5]
	v_lshl_add_u64 v[4:5], s[10:11], 0, v[4:5]
	v_add_u32_e32 v28, 1, v27
	v_max_i32_e32 v35, v35, v36
	global_load_dwordx4 v[6:9], v[2:3], off nt
	s_nop 0
	global_load_dwordx4 v[2:5], v[4:5], off nt
	v_cvt_f32_i32_e32 v55, v28
	v_sub_u32_e32 v28, 0x80, v27
	v_mul_lo_u32 v27, v27, s13
	v_cvt_f32_u32_e32 v77, v35
	v_sub_u32_e32 v35, v105, v33
	v_add_u32_e32 v58, v0, v27
	v_lshlrev_b32_e32 v0, 1, v100
	v_sub_u32_e32 v36, 0, v35
	v_add_u32_e32 v42, 0, v0
	v_max_i32_e32 v35, v35, v36
	v_mad_u64_u32 v[44:45], s[10:11], v78, s13, v[42:43]
	v_cvt_f32_u32_e32 v78, v35
	v_sub_u32_e32 v35, v105, v34
	v_sub_u32_e32 v36, 0, v35
	v_max_i32_e32 v35, v35, v36
	v_cvt_f32_u32_e32 v79, v35
	v_sub_u32_e32 v35, v103, v31
	v_sub_u32_e32 v36, 0, v35
	v_max_i32_e32 v35, v35, v36
	v_cvt_f32_u32_e32 v80, v35
	v_sub_u32_e32 v35, v103, v32
	v_sub_u32_e32 v36, 0, v35
	v_max_i32_e32 v35, v35, v36
	v_cvt_f32_u32_e32 v81, v35
	v_sub_u32_e32 v35, v103, v33
	v_sub_u32_e32 v36, 0, v35
	v_max_i32_e32 v35, v35, v36
	v_cvt_f32_u32_e32 v82, v35
	v_sub_u32_e32 v35, v103, v34
	v_sub_u32_e32 v36, 0, v35
	v_add_u32_e32 v57, v26, v27
	v_or_b32_e32 v26, 64, v99
	v_max_i32_e32 v35, v35, v36
	v_cvt_f32_u32_e32 v83, v35
	v_sub_u32_e32 v35, v26, v31
	v_sub_u32_e32 v36, 0, v35
	v_max_i32_e32 v35, v35, v36
	v_cvt_f32_u32_e32 v84, v35
	v_sub_u32_e32 v35, v26, v32
	v_sub_u32_e32 v36, 0, v35
	v_max_i32_e32 v35, v35, v36
	v_cvt_f32_u32_e32 v85, v35
	v_sub_u32_e32 v35, v26, v33
	v_sub_u32_e32 v36, 0, v35
	v_max_i32_e32 v35, v35, v36
	v_sub_u32_e32 v26, v26, v34
	v_cvt_f32_u32_e32 v86, v35
	v_sub_u32_e32 v35, 0, v26
	v_or_b32_e32 v27, 0x50, v99
	v_max_i32_e32 v26, v26, v35
	v_cvt_f32_u32_e32 v87, v26
	v_sub_u32_e32 v26, v27, v31
	v_sub_u32_e32 v35, 0, v26
	v_max_i32_e32 v26, v26, v35
	v_cvt_f32_u32_e32 v88, v26
	v_sub_u32_e32 v26, v27, v32
	v_sub_u32_e32 v35, 0, v26
	v_max_i32_e32 v26, v26, v35
	v_cvt_f32_u32_e32 v89, v26
	v_sub_u32_e32 v26, v27, v33
	v_sub_u32_e32 v35, 0, v26
	v_max_i32_e32 v26, v26, v35
	v_cvt_f32_u32_e32 v90, v26
	v_sub_u32_e32 v26, v27, v34
	v_sub_u32_e32 v27, 0, v26
	v_cvt_f32_i32_e32 v56, v28
	v_or_b32_e32 v28, 0x60, v99
	v_max_i32_e32 v26, v26, v27
	v_cvt_f32_u32_e32 v91, v26
	v_sub_u32_e32 v26, v28, v31
	v_sub_u32_e32 v27, 0, v26
	v_max_i32_e32 v26, v26, v27
	v_cvt_f32_u32_e32 v92, v26
	v_sub_u32_e32 v26, v28, v32
	v_sub_u32_e32 v27, 0, v26
	v_max_i32_e32 v26, v26, v27
	v_cvt_f32_u32_e32 v93, v26
	v_sub_u32_e32 v26, v28, v33
	v_sub_u32_e32 v27, 0, v26
	v_max_i32_e32 v26, v26, v27
	v_cvt_f32_u32_e32 v94, v26
	v_sub_u32_e32 v26, v28, v34
	v_sub_u32_e32 v27, 0, v26
	v_or_b32_e32 v29, 0x70, v102
	v_max_i32_e32 v26, v26, v27
	v_cvt_f32_u32_e32 v95, v26
	v_sub_u32_e32 v26, v29, v31
	v_sub_u32_e32 v27, 0, v26
	v_max_i32_e32 v26, v26, v27
	v_cvt_f32_u32_e32 v102, v26
	v_sub_u32_e32 v26, v29, v32
	v_sub_u32_e32 v27, 0, v26
	v_max_i32_e32 v26, v26, v27
	v_cvt_f32_u32_e32 v103, v26
	v_sub_u32_e32 v26, v29, v33
	v_sub_u32_e32 v27, 0, v26
	v_max_i32_e32 v26, v26, v27
	v_cvt_f32_u32_e32 v104, v26
	v_sub_u32_e32 v26, v29, v34
	v_sub_u32_e32 v27, 0, v26
	v_max_i32_e32 v26, v26, v27
	s_andn2_b32 s25, s25, 63
	v_cvt_f32_u32_e32 v105, v26
	v_or_b32_e32 v26, s25, v99
	v_readlane_b32 s11, v255, 22
	v_mul_lo_u32 v32, v26, s18
	v_or_b32_e32 v37, 64, v100
	v_add_u32_e32 v34, s11, v0
	v_add_u32_e32 v0, s11, v32
	v_mul_u32_u24_e32 v30, 0x90, v29
	v_mul_u32_u24_e32 v27, 0x110, v29
	v_add_u32_e32 v28, 0x1100, v0
	v_add_u32_e32 v29, 0x2200, v0
	v_add_u32_e32 v36, 0x3300, v0
	v_or_b32_e32 v38, v37, v108
	v_lshlrev_b32_e32 v37, 1, v37
	v_mul_u32_u24_e32 v33, 0x90, v114
	v_add_u32_e32 v112, v0, v37
	v_add_u32_e32 v113, v28, v37
	v_add_u32_e32 v114, v29, v37
	v_add_u32_e32 v115, v36, v37
	v_or_b32_e32 v37, 0x60, v100
	s_add_i32 s10, s11, s27
	s_add_i32 s12, s12, s26
	v_or_b32_e32 v39, v37, v108
	v_lshlrev_b32_e32 v37, 1, v37
	v_add_u32_e32 v45, s10, v100
	v_lshl_add_u32 v31, v116, 1, s12
	v_add_u32_e32 v107, v0, v125
	v_add_u32_e32 v111, v36, v125
	v_add_u32_e32 v100, v0, v37
	v_add_u32_e32 v118, v36, v37
	v_mul_lo_u32 v36, v26, s13
	v_and_b32_e32 v26, 48, v117
	v_or_b32_e32 v0, s25, v101
	v_readlane_b32 s12, v255, 27
	v_mul_lo_u32 v40, v0, s18
	v_lshlrev_b32_e32 v0, 2, v26
	v_readlane_b32 s13, v255, 28
	s_lshl_b32 s10, s24, 6
	v_ashrrev_i32_e32 v46, 2, v70
	v_lshl_add_u64 v[48:49], s[12:13], 0, v[0:1]
	v_readlane_b32 s12, v254, 0
	v_readlane_b32 s13, v254, 1
	s_add_i32 s10, s10, 0
	s_load_dword s73, s[12:13], 0x98
	v_add_u32_e32 v109, v28, v125
	v_add_u32_e32 v108, v28, v37
	v_add_u32_e32 v116, v29, v37
	v_lshl_add_u32 v37, v99, 2, s10
	v_mul_lo_u32 v28, v46, s18
	s_lshl_b64 s[10:11], s[8:9], 14
	v_add_u32_e32 v110, v29, v125
	v_add3_u32 v70, 0, v28, v0
	v_mov_b32_e32 v29, s11
	v_or_b32_e32 v0, s10, v72
	v_lshlrev_b32_e32 v28, 7, v99
	s_lshl_b32 s9, s24, 11
	v_readlane_b32 s10, v255, 12
	v_mul_u32_u24_e32 v35, 0x90, v132
	v_mul_u32_u24_e32 v38, 0x90, v38
	v_mul_u32_u24_e32 v39, 0x90, v39
	v_or3_b32 v28, s9, v28, v0
	v_readlane_b32 s11, v255, 13
	v_readlane_b32 s70, v255, 32
	v_readlane_b32 s66, v255, 34
	v_readlane_b32 s60, v255, 36
	v_readlane_b32 s62, v255, 38
	v_readlane_b32 s64, v255, 40
	v_readlane_b32 s34, v255, 42
	v_readlane_b32 s52, v255, 44
	v_readlane_b32 s54, v255, 46
	v_readlane_b32 s58, v255, 48
	v_ashrrev_i32_e32 v47, 31, v46
	v_lshl_add_u64 v[50:51], s[10:11], 0, v[28:29]
	s_lshl_b64 s[10:11], s[2:3], 14
	v_add_u32_e32 v72, v42, v30
	v_add_u32_e32 v99, v45, v27
	v_add_u32_e32 v101, v31, v33
	v_add_u32_e32 v117, v34, v32
	v_add_u32_e32 v119, v31, v35
	v_add_u32_e32 v120, v31, v38
	v_add_u32_e32 v121, v31, v39
	v_add_u32_e32 v106, v106, v36
	v_lshlrev_b32_e32 v0, 1, v26
	v_add_u32_e32 v122, v37, v40
	v_readlane_b32 s69, v255, 31
	v_readlane_b32 s71, v255, 33
	v_readlane_b32 s67, v255, 35
	v_readlane_b32 s61, v255, 37
	v_readlane_b32 s63, v255, 39
	v_readlane_b32 s65, v255, 41
	v_readlane_b32 s35, v255, 43
	v_readlane_b32 s53, v255, 45
	v_readlane_b32 s55, v255, 47
	v_readlane_b32 s59, v255, 49
	v_readlane_b32 s14, v255, 29
	v_readlane_b32 s15, v255, 30
	s_waitcnt vmcnt(0)
	v_lshlrev_b32_e32 v236, 4, v214
	v_add_u32_e32 v237, 0x2000000, v236
	v_add_u32_e32 v238, 0x4000000, v236
	v_add_u32_e32 v239, 0x2000, v236
	v_add_u32_e32 v240, 0x2002000, v236
	v_add_u32_e32 v241, 0x4002000, v236
	s_branch .LBB0_457
.LBB0_456:
	ds_read_b128 v[26:29], v44 offset:55296
	v_add_u32_e32 v144, v42, v75
	ds_read_b128 v[30:33], v144
	ds_read_b128 v[124:127], v44 offset:55360
	ds_read_b128 v[34:37], v144 offset:64
	ds_read_b128 v[38:41], v144 offset:2304
	ds_read_b128 v[128:131], v144 offset:2368
	v_add_u32_e32 v145, v42, v96
	v_mul_f32_e32 v160, v123, v65
	v_exp_f32_e32 v160, v160
	s_ashr_i32 s14, s8, 3
	s_ashr_i32 s15, s14, 31
	s_waitcnt lgkmcnt(1)
	v_mfma_f32_16x16x32_bf16 v[132:135], v[26:29], v[38:41], 0
	ds_read_b128 v[38:41], v144 offset:4608
	ds_read_b128 v[136:139], v144 offset:4672
	s_lshl_b64 s[14:15], s[14:15], 7
	s_lshl_b32 s8, s9, 22
	s_waitcnt lgkmcnt(1)
	v_mfma_f32_16x16x32_bf16 v[140:143], v[26:29], v[38:41], 0
	ds_read_b128 v[38:41], v145
	ds_read_b128 v[152:155], v145 offset:64
	s_add_u32 s16, s86, s8
	s_addc_u32 s17, s87, 0
	s_waitcnt lgkmcnt(1)
	v_mfma_f32_16x16x32_bf16 v[156:159], v[26:29], v[38:41], 0
	ds_read_b128 v[38:41], v144 offset:9216
	ds_read_b128 v[162:165], v144 offset:9280
	s_mov_b32 s8, 0x6000000
	s_lshl_b32 s80, s9, 8
	s_waitcnt lgkmcnt(1)
	v_mfma_f32_16x16x32_bf16 v[166:169], v[26:29], v[38:41], 0
	ds_read_b128 v[38:41], v144 offset:11520
	ds_read_b128 v[170:173], v144 offset:11584
	s_waitcnt lgkmcnt(1)
	v_mfma_f32_16x16x32_bf16 v[174:177], v[26:29], v[38:41], 0
	ds_read_b128 v[38:41], v144 offset:13824
	ds_read_b128 v[198:201], v72
	ds_read_b128 v[202:205], v144 offset:13888
	v_add_co_u32_e32 v144, vcc, 0xffffe000, v50
	v_mfma_f32_16x16x32_bf16 v[30:33], v[26:29], v[30:33], 0
	s_nop 0
	v_addc_co_u32_e32 v145, vcc, -1, v51, vcc
	ds_read_b128 v[210:213], v72 offset:64
	v_mfma_f32_16x16x32_bf16 v[128:131], v[124:127], v[128:131], v[132:135]
	v_mfma_f32_16x16x32_bf16 v[132:135], v[124:127], v[136:139], v[140:143]
	v_mul_f32_e32 v136, v123, v60
	s_nop 5
	v_mul_f32_e32 v130, v160, v130
	v_mul_f32_e32 v140, v123, v61
	s_waitcnt lgkmcnt(3)
	v_mfma_f32_16x16x32_bf16 v[206:209], v[26:29], v[38:41], 0
	v_exp_f32_e32 v147, v140
	v_mul_f32_e32 v140, v123, v62
	s_waitcnt lgkmcnt(2)
	v_mfma_f32_16x16x32_bf16 v[198:201], v[26:29], v[198:201], 0
	v_mul_f32_e32 v26, v123, v59
	v_mfma_f32_16x16x32_bf16 v[216:219], v[124:127], v[34:37], v[30:33]
	global_load_dwordx4 v[38:41], v[144:145], off offset:-64 nt
	global_load_dwordx4 v[34:37], v[144:145], off nt
	v_exp_f32_e32 v144, v26
	v_exp_f32_e32 v145, v136
	v_mfma_f32_16x16x32_bf16 v[136:139], v[124:127], v[152:155], v[156:159]
	v_exp_f32_e32 v152, v140
	s_nop 1
	v_mul_f32_e32 v144, v144, v216
	v_mul_f32_e32 v145, v145, v217
	v_mul_f32_e32 v147, v147, v218
	v_mul_f32_e32 v156, v152, v219
	v_cvt_pk_bf16_f32 v144, v144, v145
	v_cvt_pk_bf16_f32 v145, v147, v156
	v_add_u32_e32 v147, v45, v71
	global_load_dwordx4 v[30:33], v[50:51], off offset:-64 nt
	global_load_dwordx4 v[26:29], v[50:51], off nt
	v_mfma_f32_16x16x32_bf16 v[140:143], v[124:127], v[162:165], v[166:169]
	ds_write_b64 v147, v[144:145]
	v_mul_f32_e32 v144, v123, v63
	v_mul_f32_e32 v145, v123, v64
	v_mul_f32_e32 v162, v123, v74
	v_exp_f32_e32 v144, v144
	v_exp_f32_e32 v145, v145
	v_exp_f32_e32 v162, v162
	v_mfma_f32_16x16x32_bf16 v[152:155], v[124:127], v[170:173], v[174:177]
	v_mul_f32_e32 v128, v144, v128
	v_mul_f32_e32 v129, v145, v129
	v_mul_f32_e32 v131, v162, v131
	v_cvt_pk_bf16_f32 v128, v128, v129
	v_cvt_pk_bf16_f32 v129, v130, v131
	ds_write_b64 v147, v[128:129] offset:4352
	v_mul_f32_e32 v128, v123, v76
	v_mul_f32_e32 v129, v123, v77
	v_mul_f32_e32 v130, v123, v78
	v_mul_f32_e32 v131, v123, v79
	v_exp_f32_e32 v128, v128
	v_exp_f32_e32 v129, v129
	v_exp_f32_e32 v130, v130
	v_exp_f32_e32 v131, v131
	v_mul_f32_e32 v128, v128, v132
	v_mul_f32_e32 v129, v129, v133
	v_mul_f32_e32 v130, v130, v134
	v_mul_f32_e32 v131, v131, v135
	v_cvt_pk_bf16_f32 v128, v128, v129
	v_cvt_pk_bf16_f32 v129, v130, v131
	ds_write_b64 v147, v[128:129] offset:8704
	v_mul_f32_e32 v128, v123, v80
	v_mul_f32_e32 v129, v123, v81
	v_mul_f32_e32 v130, v123, v82
	v_mul_f32_e32 v131, v123, v83
	v_exp_f32_e32 v128, v128
	v_exp_f32_e32 v129, v129
	v_exp_f32_e32 v130, v130
	v_exp_f32_e32 v131, v131
	v_mul_f32_e32 v128, v128, v136
	v_mul_f32_e32 v129, v129, v137
	v_mul_f32_e32 v130, v130, v138
	v_mul_f32_e32 v131, v131, v139
	v_cvt_pk_bf16_f32 v128, v128, v129
	v_cvt_pk_bf16_f32 v129, v130, v131
	v_add_u32_e32 v130, v45, v73
	ds_write_b64 v130, v[128:129]
	v_mul_f32_e32 v128, v123, v84
	v_mul_f32_e32 v129, v123, v85
	v_mul_f32_e32 v130, v123, v86
	v_mul_f32_e32 v131, v123, v87
	v_exp_f32_e32 v128, v128
	v_exp_f32_e32 v129, v129
	v_exp_f32_e32 v130, v130
	v_exp_f32_e32 v131, v131
	v_mul_f32_e32 v128, v128, v140
	v_mul_f32_e32 v129, v129, v141
	v_mul_f32_e32 v130, v130, v142
	v_mul_f32_e32 v131, v131, v143
	v_cvt_pk_bf16_f32 v128, v128, v129
	v_cvt_pk_bf16_f32 v129, v130, v131
	ds_write_b64 v147, v[128:129] offset:17408
	v_mul_f32_e32 v128, v123, v88
	v_mul_f32_e32 v129, v123, v89
	v_mul_f32_e32 v130, v123, v90
	v_mul_f32_e32 v131, v123, v91
	v_exp_f32_e32 v128, v128
	v_exp_f32_e32 v129, v129
	v_exp_f32_e32 v130, v130
	v_exp_f32_e32 v131, v131
	v_mul_f32_e32 v128, v128, v152
	v_mul_f32_e32 v129, v129, v153
	v_mul_f32_e32 v130, v130, v154
	v_mul_f32_e32 v131, v131, v155
	v_cvt_pk_bf16_f32 v128, v128, v129
	v_cvt_pk_bf16_f32 v129, v130, v131
	ds_write_b64 v147, v[128:129] offset:21760
	v_mul_f32_e32 v128, v123, v92
	v_mul_f32_e32 v129, v123, v93
	v_mul_f32_e32 v130, v123, v94
	v_mul_f32_e32 v131, v123, v95
	s_waitcnt lgkmcnt(7)
	v_mfma_f32_16x16x32_bf16 v[156:159], v[124:127], v[202:205], v[206:209]
	v_exp_f32_e32 v128, v128
	v_exp_f32_e32 v129, v129
	v_exp_f32_e32 v130, v130
	v_exp_f32_e32 v131, v131
	s_waitcnt lgkmcnt(6)
	v_mfma_f32_16x16x32_bf16 v[124:127], v[124:127], v[210:213], v[198:201]
	s_nop 1
	v_mul_f32_e32 v128, v128, v156
	v_mul_f32_e32 v129, v129, v157
	v_mul_f32_e32 v130, v130, v158
	v_mul_f32_e32 v131, v131, v159
	v_cvt_pk_bf16_f32 v128, v128, v129
	v_cvt_pk_bf16_f32 v129, v130, v131
	ds_write_b64 v147, v[128:129] offset:26112
	v_mul_f32_e32 v128, v123, v102
	v_mul_f32_e32 v129, v123, v103
	v_mul_f32_e32 v130, v123, v104
	v_mul_f32_e32 v123, v123, v105
	v_exp_f32_e32 v128, v128
	v_exp_f32_e32 v129, v129
	v_exp_f32_e32 v130, v130
	v_exp_f32_e32 v123, v123
	v_mul_f32_e32 v124, v128, v124
	v_mul_f32_e32 v125, v129, v125
	v_mul_f32_e32 v126, v130, v126
	v_mul_f32_e32 v123, v123, v127
	v_cvt_pk_bf16_f32 v124, v124, v125
	v_cvt_pk_bf16_f32 v125, v126, v123
	ds_write_b64 v99, v[124:125]
	s_waitcnt lgkmcnt(0)
	s_barrier
	ds_read_b128 v[124:127], v117
	ds_read_b64_tr_b16 v[128:129], v101
	ds_read_b64_tr_b16 v[130:131], v101 offset:576
	ds_read_b128 v[132:135], v117 offset:4352
	ds_read_b128 v[136:139], v117 offset:8704
	ds_read_b128 v[152:155], v107
	ds_read_b128 v[140:143], v117 offset:13056
	s_waitcnt lgkmcnt(4)
	v_mfma_f32_16x16x32_bf16 v[124:127], v[124:127], v[128:131], 0
	v_lshl_add_u64 v[144:145], s[14:15], 0, v[46:47]
	s_mov_b64 s[14:15], 0x6000000
	v_lshl_add_u64 v[50:51], v[50:51], 0, s[10:11]
	s_waitcnt lgkmcnt(3)
	v_mfma_f32_16x16x32_bf16 v[132:135], v[132:135], v[128:131], 0
	s_waitcnt lgkmcnt(2)
	v_mfma_f32_16x16x32_bf16 v[136:139], v[136:139], v[128:131], 0
	s_waitcnt lgkmcnt(0)
	v_mfma_f32_16x16x32_bf16 v[128:131], v[140:143], v[128:131], 0
	ds_read_b128 v[140:143], v109
	ds_read_b64_tr_b16 v[156:157], v119
	ds_read_b64_tr_b16 v[158:159], v119 offset:576
	ds_read_b64_tr_b16 v[162:163], v120
	ds_read_b64_tr_b16 v[164:165], v120 offset:576
	s_waitcnt lgkmcnt(2)
	v_mfma_f32_16x16x32_bf16 v[124:127], v[152:155], v[156:159], v[124:127]
	ds_read_b128 v[152:155], v110
	s_waitcnt lgkmcnt(0)
	v_mfma_f32_16x16x32_bf16 v[136:139], v[152:155], v[156:159], v[136:139]
	ds_read_b128 v[152:155], v112
	v_mfma_f32_16x16x32_bf16 v[132:135], v[140:143], v[156:159], v[132:135]
	ds_read_b128 v[140:143], v111
	s_waitcnt lgkmcnt(1)
	v_mfma_f32_16x16x32_bf16 v[124:127], v[152:155], v[162:165], v[124:127]
	ds_read_b128 v[152:155], v114
	s_waitcnt lgkmcnt(0)
	v_mfma_f32_16x16x32_bf16 v[136:139], v[152:155], v[162:165], v[136:139]
	ds_read_b128 v[152:155], v100
	v_mfma_f32_16x16x32_bf16 v[128:131], v[140:143], v[156:159], v[128:131]
	ds_read_b128 v[140:143], v113
	s_waitcnt lgkmcnt(0)
	v_mfma_f32_16x16x32_bf16 v[132:135], v[140:143], v[162:165], v[132:135]
	ds_read_b128 v[140:143], v115
	s_waitcnt lgkmcnt(0)
	v_mfma_f32_16x16x32_bf16 v[128:131], v[140:143], v[162:165], v[128:131]
	ds_read_b64_tr_b16 v[140:141], v121
	ds_read_b64_tr_b16 v[142:143], v121 offset:576
	ds_read_b128 v[156:159], v108
	s_waitcnt lgkmcnt(1)
	v_mfma_f32_16x16x32_bf16 v[124:127], v[152:155], v[140:143], v[124:127]
	ds_read_b128 v[152:155], v116
	s_waitcnt lgkmcnt(1)
	v_mfma_f32_16x16x32_bf16 v[132:135], v[156:159], v[140:143], v[132:135]
	ds_read_b128 v[156:159], v118
	s_waitcnt lgkmcnt(1)
	v_mfma_f32_16x16x32_bf16 v[136:139], v[152:155], v[140:143], v[136:139]
	s_waitcnt lgkmcnt(0)
	v_mfma_f32_16x16x32_bf16 v[128:131], v[156:159], v[140:143], v[128:131]
	ds_read_b128 v[140:143], v106 offset:18432
	ds_read_b128 v[152:155], v106 offset:18496
	s_waitcnt vmcnt(3) lgkmcnt(1)
	v_mfma_f32_16x16x32_bf16 v[124:127], v[140:143], v[38:41], v[124:127]
	ds_read_b128 v[140:143], v106 offset:20736
	ds_read_b128 v[156:159], v106 offset:20800
	s_waitcnt lgkmcnt(1)
	v_mfma_f32_16x16x32_bf16 v[132:135], v[140:143], v[38:41], v[132:135]
	ds_read_b128 v[140:143], v106 offset:23040
	ds_read_b128 v[162:165], v106 offset:23104
	s_waitcnt lgkmcnt(1)
	v_mfma_f32_16x16x32_bf16 v[136:139], v[140:143], v[38:41], v[136:139]
	ds_read_b128 v[140:143], v106 offset:25344
	ds_read_b128 v[166:169], v106 offset:25408
	s_waitcnt lgkmcnt(1)
	v_mfma_f32_16x16x32_bf16 v[38:41], v[140:143], v[38:41], v[128:131]
	s_waitcnt vmcnt(2)
	v_mfma_f32_16x16x32_bf16 v[124:127], v[152:155], v[34:37], v[124:127]
	v_mfma_f32_16x16x32_bf16 v[128:131], v[156:159], v[34:37], v[132:135]
	v_mfma_f32_16x16x32_bf16 v[132:135], v[162:165], v[34:37], v[136:139]
	s_waitcnt lgkmcnt(0)
	v_mfma_f32_16x16x32_bf16 v[34:37], v[166:169], v[34:37], v[38:41]
	s_nop 2
	ds_read_b128 v[38:41], v106 offset:36864
	ds_read_b128 v[136:139], v106 offset:36928
	s_waitcnt vmcnt(1) lgkmcnt(1)
	v_mfma_f32_16x16x32_bf16 v[38:41], v[38:41], v[30:33], v[124:127]
	s_nop 2
	ds_read_b128 v[124:127], v106 offset:39168
	ds_read_b128 v[140:143], v106 offset:39232
	s_waitcnt lgkmcnt(1)
	v_mfma_f32_16x16x32_bf16 v[124:127], v[124:127], v[30:33], v[128:131]
	s_nop 2
	ds_read_b128 v[128:131], v106 offset:41472
	ds_read_b128 v[152:155], v106 offset:41536
	s_waitcnt lgkmcnt(1)
	v_mfma_f32_16x16x32_bf16 v[128:131], v[128:131], v[30:33], v[132:135]
	s_nop 2
	ds_read_b128 v[132:135], v106 offset:43776
	ds_read_b128 v[156:159], v106 offset:43840
	s_waitcnt lgkmcnt(1)
	v_mfma_f32_16x16x32_bf16 v[30:33], v[132:135], v[30:33], v[34:37]
	s_waitcnt vmcnt(0)
	v_mfma_f32_16x16x32_bf16 v[34:37], v[136:139], v[26:29], v[38:41]
	v_mfma_f32_16x16x32_bf16 v[38:41], v[140:143], v[26:29], v[124:127]
	v_mfma_f32_16x16x32_bf16 v[124:127], v[152:155], v[26:29], v[128:131]
	v_lshl_add_u64 v[152:153], v[48:49], 0, s[80:81]
	s_lshl_b32 s80, s9, 7
	s_waitcnt lgkmcnt(0)
	v_mfma_f32_16x16x32_bf16 v[26:29], v[156:159], v[26:29], v[30:33]
	s_nop 2
	global_load_dwordx4 v[2:5], v236, s[100:101] nt
	global_load_dwordx4 v[6:9], v237, s[100:101] nt
	global_load_dwordx4 v[22:25], v238, s[100:101] nt
	v_lshlrev_b64 v[30:31], 7, v[144:145]
	v_lshl_add_u64 v[30:31], s[16:17], 0, v[30:31]
	v_lshl_add_u64 v[30:31], v[30:31], 0, v[0:1]
	v_lshl_add_u64 v[128:129], v[30:31], 0, s[14:15]
	v_add_co_u32_e32 v30, vcc, s8, v30
	v_lshlrev_b64 v[144:145], 11, v[144:145]
	s_nop 0
	v_addc_co_u32_e32 v31, vcc, 0, v31, vcc
	global_load_dwordx4 v[30:33], v[30:31], off nt
	s_nop 0
	global_load_dwordx4 v[128:131], v[128:129], off offset:16 nt
	s_barrier
	global_load_dwordx4 v[18:21], v239, s[100:101] nt
	global_load_dwordx4 v[10:13], v240, s[100:101] nt
	global_load_dwordx4 v[14:17], v241, s[100:101] nt
	ds_write2_b32 v122, v34, v35 offset1:68
	ds_write2_b32 v122, v36, v37 offset0:136 offset1:204
	v_add_u32_e32 v34, 0x1000, v122
	ds_write2_b32 v34, v38, v39 offset0:64 offset1:132
	v_add_u32_e32 v34, 0x1200, v122
	ds_write2_b32 v34, v40, v41 offset0:72 offset1:140
	v_add_u32_e32 v34, 0x2000, v122
	ds_write2_b32 v34, v124, v125 offset0:128 offset1:196
	v_add_u32_e32 v34, 0x2400, v122
	ds_write2_b32 v34, v126, v127 offset0:8 offset1:76
	v_add_u32_e32 v34, 0x3200, v122
	ds_write2_b32 v34, v26, v27 offset0:64 offset1:132
	v_add_u32_e32 v26, 0x3400, v122
	ds_write2_b32 v26, v28, v29 offset0:72 offset1:140
	s_waitcnt lgkmcnt(0)
	s_barrier
	ds_read_b128 v[38:41], v70
	ds_read_b128 v[124:127], v70 offset:16
	ds_read_b128 v[132:135], v70 offset:32
	ds_read_b128 v[136:139], v70 offset:48
	v_lshl_add_u64 v[144:145], s[74:75], 0, v[144:145]
	s_waitcnt lgkmcnt(3)
	v_pk_mul_f32 v[140:141], v[40:41], v[40:41]
	v_pk_mul_f32 v[142:143], v[38:39], v[38:39]
	v_lshl_add_u64 v[144:145], v[144:145], 0, s[80:81]
	v_pk_mov_b32 v[154:155], v[142:143], v[140:141] op_sel:[1,0]
	v_mov_b32_e32 v143, v141
	v_pk_add_f32 v[156:157], v[154:155], v[142:143]
	s_waitcnt lgkmcnt(2)
	v_pk_mul_f32 v[140:141], v[126:127], v[126:127]
	v_pk_mul_f32 v[142:143], v[124:125], v[124:125]
	s_waitcnt lgkmcnt(0)
	v_mul_f32_e32 v123, v136, v136
	v_pk_mov_b32 v[154:155], v[142:143], v[140:141] op_sel:[1,0]
	v_mov_b32_e32 v143, v141
	v_pk_add_f32 v[158:159], v[154:155], v[142:143]
	v_mul_f32_e32 v147, v137, v137
	v_pk_add_f32 v[156:157], v[156:157], v[156:157] op_sel:[0,1] op_sel_hi:[1,0]
	v_pk_add_f32 v[158:159], v[158:159], v[158:159] op_sel:[0,1] op_sel_hi:[1,0]
	v_mov_b32_e32 v157, v123
	v_mov_b32_e32 v159, v147
	v_pk_add_f32 v[156:157], v[156:157], v[158:159]
	v_mul_f32_e32 v158, v133, v133
	v_mul_f32_e32 v160, v138, v138
	v_pk_fma_f32 v[158:159], v[132:133], v[132:133], v[158:159] op_sel_hi:[1,1,0]
	v_mul_f32_e32 v164, v139, v139
	v_mov_b32_e32 v159, v160
	v_mul_f32_e32 v160, v135, v135
	v_pk_fma_f32 v[162:163], v[134:135], v[134:135], v[160:161] op_sel_hi:[1,1,0]
	v_lshl_add_u64 v[144:145], v[144:145], 0, v[0:1]
	v_mov_b32_e32 v163, v164
	v_pk_add_f32 v[158:159], v[158:159], v[162:163]
	s_mov_b32 s8, s3
	v_pk_add_f32 v[156:157], v[156:157], v[158:159]
	s_waitcnt vmcnt(4)
	v_lshlrev_b32_e32 v158, 16, v30
	v_add_f32_e32 v123, v156, v157
	ds_bpermute_b32 v147, v97, v123
	v_and_b32_e32 v159, 0xffff0000, v30
	v_lshlrev_b32_e32 v30, 16, v31
	v_and_b32_e32 v31, 0xffff0000, v31
	v_lshlrev_b32_e32 v162, 16, v32
	s_waitcnt lgkmcnt(0)
	v_add_f32_e32 v123, v123, v147
	ds_bpermute_b32 v147, v98, v123
	v_and_b32_e32 v163, 0xffff0000, v32
	v_lshlrev_b32_e32 v32, 16, v33
	v_and_b32_e32 v33, 0xffff0000, v33
	s_waitcnt lgkmcnt(0)
	v_add_f32_e32 v123, v123, v147
	v_fmamk_f32 v123, v123, 0x3c800000, v178
	v_mul_f32_e32 v147, 0x4b800000, v123
	v_cmp_gt_f32_e32 vcc, s22, v123
	s_nop 1
	v_cndmask_b32_e32 v123, v123, v147, vcc
	v_rsq_f32_e32 v123, v123
	s_nop 0
	v_mul_f32_e32 v147, 0x45800000, v123
	v_cndmask_b32_e32 v156, v123, v147, vcc
	v_pk_mul_f32 v[40:41], v[40:41], v[156:157] op_sel_hi:[1,0]
	v_pk_mul_f32 v[38:39], v[38:39], v[156:157] op_sel_hi:[1,0]
	v_pk_mul_f32 v[28:29], v[222:223], v[40:41]
	v_pk_mul_f32 v[26:27], v[220:221], v[38:39]
	v_pk_mul_f32 v[28:29], v[28:29], v[30:31]
	v_pk_mul_f32 v[30:31], v[126:127], v[156:157] op_sel_hi:[1,0]
	v_pk_mul_f32 v[38:39], v[124:125], v[156:157] op_sel_hi:[1,0]
	v_pk_mul_f32 v[30:31], v[226:227], v[30:31]
	v_pk_mul_f32 v[34:35], v[224:225], v[38:39]
	v_pk_mul_f32 v[26:27], v[26:27], v[158:159]
	v_pk_mul_f32 v[30:31], v[30:31], v[32:33]
	v_pk_mul_f32 v[32:33], v[34:35], v[162:163]
	v_cvt_pk_bf16_f32 v26, v26, v27
	v_cvt_pk_bf16_f32 v27, v28, v29
	v_cvt_pk_bf16_f32 v28, v32, v33
	v_cvt_pk_bf16_f32 v29, v30, v31
	v_pk_mul_f32 v[34:35], v[134:135], v[156:157] op_sel_hi:[1,0]
	v_pk_mul_f32 v[36:37], v[132:133], v[156:157] op_sel_hi:[1,0]
	global_store_dwordx4 v[144:145], v[26:29], off
	s_waitcnt vmcnt(4)
	v_pk_mul_f32 v[36:37], v[228:229], v[36:37]
	v_pk_mul_f32 v[34:35], v[230:231], v[34:35]
	v_lshlrev_b32_e32 v26, 16, v128
	v_and_b32_e32 v27, 0xffff0000, v128
	v_lshlrev_b32_e32 v28, 16, v129
	v_and_b32_e32 v29, 0xffff0000, v129
	v_pk_mul_f32 v[28:29], v[34:35], v[28:29]
	v_pk_mul_f32 v[26:27], v[36:37], v[26:27]
	v_pk_mul_f32 v[34:35], v[138:139], v[156:157] op_sel_hi:[1,0]
	v_pk_mul_f32 v[36:37], v[136:137], v[156:157] op_sel_hi:[1,0]
	v_lshlrev_b32_e32 v30, 16, v130
	v_and_b32_e32 v31, 0xffff0000, v130
	v_lshlrev_b32_e32 v32, 16, v131
	v_and_b32_e32 v33, 0xffff0000, v131
	v_pk_mul_f32 v[36:37], v[232:233], v[36:37]
	v_pk_mul_f32 v[34:35], v[234:235], v[34:35]
	v_pk_mul_f32 v[30:31], v[36:37], v[30:31]
	v_pk_mul_f32 v[32:33], v[34:35], v[32:33]
	v_cvt_pk_bf16_f32 v26, v26, v27
	v_cvt_pk_bf16_f32 v27, v28, v29
	v_cvt_pk_bf16_f32 v28, v30, v31
	v_cvt_pk_bf16_f32 v29, v32, v33
	s_and_b64 vcc, exec, s[12:13]
	global_store_dwordx4 v[144:145], v[26:29], off offset:16
	s_barrier
	s_cbranch_vccnz .LBB0_459
.LBB0_457:
	s_add_i32 s3, s8, s2
	s_cmpk_gt_i32 s3, 0x7ff
	s_cselect_b64 s[12:13], -1, 0
	s_cmpk_lt_i32 s3, 0x800
	s_cselect_b32 s14, s3, -1
	s_and_b32 s9, s8, 7
	s_cmp_eq_u32 s9, 1
	s_cselect_b64 vcc, -1, 0
	s_cmp_lg_u32 s9, 2
	v_cndmask_b32_e32 v26, v181, v182, vcc
	s_cselect_b64 vcc, -1, 0
	s_cmp_lg_u32 s9, 3
	v_cndmask_b32_e32 v26, v183, v26, vcc
	s_cselect_b64 vcc, -1, 0
	s_cmp_lg_u32 s9, 4
	v_cndmask_b32_e32 v26, v184, v26, vcc
	s_cselect_b64 vcc, -1, 0
	s_cmp_lg_u32 s9, 5
	v_cndmask_b32_e32 v26, v185, v26, vcc
	s_cselect_b64 vcc, -1, 0
	s_cmp_lg_u32 s9, 6
	v_cndmask_b32_e32 v26, v186, v26, vcc
	s_cselect_b64 vcc, -1, 0
	s_cmp_lg_u32 s9, 7
	v_cndmask_b32_e32 v26, v187, v26, vcc
	s_cselect_b64 vcc, -1, 0
	v_cndmask_b32_e32 v123, v188, v26, vcc
	v_mul_f32_e32 v26, v123, v43
	v_exp_f32_e32 v26, v26
	v_mul_f32_e32 v27, v123, v52
	v_exp_f32_e32 v38, v27
	s_waitcnt vmcnt(2)
	v_lshlrev_b32_e32 v30, 16, v2
	v_and_b32_e32 v31, 0xffff0000, v2
	v_lshlrev_b32_e32 v32, 16, v3
	v_and_b32_e32 v33, 0xffff0000, v3
	v_lshlrev_b32_e32 v34, 16, v4
	v_and_b32_e32 v35, 0xffff0000, v4
	v_lshlrev_b32_e32 v36, 16, v5
	v_and_b32_e32 v37, 0xffff0000, v5
	v_pk_mul_f32 v[28:29], v[26:27], v[32:33] op_sel_hi:[0,1]
	v_pk_mul_f32 v[40:41], v[26:27], v[30:31] op_sel_hi:[0,1]
	v_pk_mul_f32 v[124:125], v[26:27], v[36:37] op_sel_hi:[0,1]
	v_pk_mul_f32 v[126:127], v[26:27], v[34:35] op_sel_hi:[0,1]
	v_cvt_pk_bf16_f32 v26, v40, v41
	v_cvt_pk_bf16_f32 v27, v28, v29
	v_cvt_pk_bf16_f32 v28, v126, v127
	v_cvt_pk_bf16_f32 v29, v124, v125
	ds_write_b128 v53, v[26:29] offset:18432
	v_pk_mul_f32 v[28:29], v[38:39], v[32:33] op_sel_hi:[0,1]
	v_pk_mul_f32 v[26:27], v[38:39], v[30:31] op_sel_hi:[0,1]
	v_pk_mul_f32 v[30:31], v[38:39], v[36:37] op_sel_hi:[0,1]
	v_pk_mul_f32 v[32:33], v[38:39], v[34:35] op_sel_hi:[0,1]
	v_cvt_pk_bf16_f32 v26, v26, v27
	v_cvt_pk_bf16_f32 v27, v28, v29
	v_cvt_pk_bf16_f32 v28, v32, v33
	v_cvt_pk_bf16_f32 v29, v30, v31
	ds_write_b128 v53, v[2:5]
	ds_write_b128 v53, v[26:29] offset:36864
	ds_write_b128 v53, v[6:9] offset:55296
	ds_write_b128 v54, v[22:25]
	v_mul_f32_e32 v26, v123, v55
	v_exp_f32_e32 v26, v26
	v_mul_f32_e32 v27, v123, v56
	v_exp_f32_e32 v38, v27
	v_lshlrev_b32_e32 v30, 16, v18
	v_and_b32_e32 v31, 0xffff0000, v18
	v_lshlrev_b32_e32 v32, 16, v19
	v_and_b32_e32 v33, 0xffff0000, v19
	v_lshlrev_b32_e32 v34, 16, v20
	v_and_b32_e32 v35, 0xffff0000, v20
	v_lshlrev_b32_e32 v36, 16, v21
	v_and_b32_e32 v37, 0xffff0000, v21
	v_pk_mul_f32 v[28:29], v[26:27], v[32:33] op_sel_hi:[0,1]
	v_pk_mul_f32 v[40:41], v[26:27], v[30:31] op_sel_hi:[0,1]
	v_pk_mul_f32 v[124:125], v[26:27], v[36:37] op_sel_hi:[0,1]
	v_pk_mul_f32 v[126:127], v[26:27], v[34:35] op_sel_hi:[0,1]
	v_cvt_pk_bf16_f32 v26, v40, v41
	v_cvt_pk_bf16_f32 v27, v28, v29
	v_cvt_pk_bf16_f32 v28, v126, v127
	v_cvt_pk_bf16_f32 v29, v124, v125
	ds_write_b128 v57, v[26:29] offset:18432
	v_pk_mul_f32 v[28:29], v[38:39], v[32:33] op_sel_hi:[0,1]
	v_pk_mul_f32 v[26:27], v[38:39], v[30:31] op_sel_hi:[0,1]
	v_pk_mul_f32 v[30:31], v[38:39], v[36:37] op_sel_hi:[0,1]
	v_pk_mul_f32 v[32:33], v[38:39], v[34:35] op_sel_hi:[0,1]
	v_cvt_pk_bf16_f32 v26, v26, v27
	v_cvt_pk_bf16_f32 v27, v28, v29
	v_cvt_pk_bf16_f32 v28, v32, v33
	v_cvt_pk_bf16_f32 v29, v30, v31
	s_cmp_lt_i32 s14, 0
	ds_write_b128 v57, v[18:21]
	ds_write_b128 v57, v[26:29] offset:36864
	ds_write_b128 v57, v[10:13] offset:55296
	ds_write_b128 v58, v[14:17]
	s_waitcnt lgkmcnt(0)
	s_barrier
	s_cmpk_lt_i32 s3, 0x800
	s_cselect_b32 s14, s3, s8
	s_lshr_b32 s15, s14, 3
	s_lshl_b32 s15, s15, 14
	s_and_b32 s14, s14, 7
	s_lshl_b32 s14, s14, 22
	s_add_u32 s14, s14, s15
	s_add_u32 s100, s86, s14
	s_addc_u32 s101, s87, 0
	s_and_b32 s14, s8, 7
	s_lshl_b32 s14, s14, 8
	s_mov_b32 s15, 0
	v_lshl_add_u64 v[244:245], v[48:49], 0, s[14:15]
	global_load_dwordx4 v[220:223], v[244:245], off nt
	global_load_dwordx4 v[224:227], v[244:245], off offset:16 nt
	global_load_dwordx4 v[228:231], v[244:245], off offset:32 nt
	global_load_dwordx4 v[232:235], v[244:245], off offset:48 nt
	s_branch .LBB0_456
